# GLU epilogue: second column-half operand tiles loaded together with the first half (one memory round trip); attention K-tile staging issues its 16 loads together instead of load-wait-write x16
# speedup vs baseline: 1.0639x; 1.0011x over previous
.LBB0_362:
	s_andn2_b64 vcc, exec, s[0:1]
	s_cbranch_vccnz .LBB0_372
	s_cmpk_gt_i32 s6, 0xcf
	s_cbranch_scc1 .LBB0_372
	v_mov_b32_e32 v58, v194
	v_readlane_b32 s4, v235, 10
	v_lshlrev_b32_e32 v0, 4, v58
	v_and_b32_e32 v0, 0x1f0, v0
	v_ashrrev_i32_e32 v59, 31, v58
	v_readlane_b32 s5, v235, 11
	v_add_u32_e32 v6, 0, v0
	s_nop 0
	v_lshl_add_u64 v[0:1], v[58:59], 4, s[4:5]
	s_barrier
	global_load_dwordx4 v[128:131], v[0:1], off
	v_lshrrev_b32_e32 v2, 5, v58
	v_mul_lo_u32 v2, v2, s96
	v_add_u32_e32 v151, v6, v2
	v_add_co_u32_e32 v2, vcc, s92, v0
	v_add_u32_e32 v7, 0x200, v58
	s_nop 0
	v_addc_co_u32_e32 v3, vcc, 0, v1, vcc
	s_lshl_b32 s0, s6, 5
	s_and_b32 s1, s0, 0xffffff80
	v_and_b32_e32 v4, 15, v58
	v_or_b32_e32 v5, s1, v4
	s_movk_i32 s1, 0x6000
	v_readfirstlane_b32 s0, v58
	s_ashr_i32 s0, s0, 2
	s_and_b32 s0, s0, -16
	v_bfe_u32 v161, v58, 4, 2
	s_cmpk_lt_i32 s0, 0x80
	s_cselect_b64 s[4:5], -1, 0
	s_cmpk_gt_i32 s0, 0x7f
	v_add_u32_e32 v163, s0, v5
	v_lshlrev_b32_e32 v172, 4, v161
	global_load_dwordx4 v[132:135], v[2:3], off
	v_lshrrev_b32_e32 v2, 5, v7
	v_mul_lo_u32 v2, v2, s96
	v_add_u32_e32 v152, v6, v2
	v_add_co_u32_e32 v2, vcc, s75, v0
	v_add_u32_e32 v7, 0x400, v58
	s_nop 0
	v_addc_co_u32_e32 v3, vcc, 0, v1, vcc
	global_load_dwordx4 v[136:139], v[2:3], off
	v_lshrrev_b32_e32 v2, 5, v7
	v_mul_lo_u32 v2, v2, s96
	v_add_u32_e32 v153, v6, v2
	v_add_co_u32_e32 v2, vcc, s1, v0
	v_add_u32_e32 v7, 0x600, v58
	s_nop 0
	v_addc_co_u32_e32 v3, vcc, 0, v1, vcc
	s_mov_b32 s1, 0x8000
	global_load_dwordx4 v[140:143], v[2:3], off
	v_lshrrev_b32_e32 v2, 5, v7
	v_mul_lo_u32 v2, v2, s96
	v_add_u32_e32 v154, v6, v2
	v_add_co_u32_e32 v2, vcc, s1, v0
	v_add_u32_e32 v7, 0x800, v58
	s_nop 0
	v_addc_co_u32_e32 v3, vcc, 0, v1, vcc
	s_mov_b32 s1, 0xa000
	global_load_dwordx4 v[144:147], v[2:3], off
	v_lshrrev_b32_e32 v2, 5, v7
	v_mul_lo_u32 v2, v2, s96
	v_add_u32_e32 v155, v6, v2
	v_add_co_u32_e32 v2, vcc, s1, v0
	v_add_u32_e32 v7, 0xa00, v58
	s_nop 0
	v_addc_co_u32_e32 v3, vcc, 0, v1, vcc
	s_mov_b32 s1, 0xc000
	global_load_dwordx4 v[176:179], v[2:3], off
	v_lshrrev_b32_e32 v2, 5, v7
	v_mul_lo_u32 v2, v2, s96
	v_add_u32_e32 v156, v6, v2
	v_add_co_u32_e32 v2, vcc, s1, v0
	v_add_u32_e32 v7, 0xc00, v58
	s_nop 0
	v_addc_co_u32_e32 v3, vcc, 0, v1, vcc
	s_mov_b32 s1, 0xe000
	global_load_dwordx4 v[180:183], v[2:3], off
	v_lshrrev_b32_e32 v2, 5, v7
	v_mul_lo_u32 v2, v2, s96
	v_add_u32_e32 v157, v6, v2
	v_add_co_u32_e32 v2, vcc, s1, v0
	v_add_u32_e32 v7, 0xe00, v58
	s_nop 0
	v_addc_co_u32_e32 v3, vcc, 0, v1, vcc
	s_mov_b32 s1, 0x10000
	global_load_dwordx4 v[184:187], v[2:3], off
	v_lshrrev_b32_e32 v2, 5, v7
	v_mul_lo_u32 v2, v2, s96
	v_add_u32_e32 v158, v6, v2
	v_add_co_u32_e32 v2, vcc, s1, v0
	v_add_u32_e32 v7, 0x1000, v58
	s_nop 0
	v_addc_co_u32_e32 v3, vcc, 0, v1, vcc
	s_mov_b32 s1, 0x12000
	global_load_dwordx4 v[188:191], v[2:3], off
	v_lshrrev_b32_e32 v2, 5, v7
	v_mul_lo_u32 v2, v2, s96
	v_add_u32_e32 v159, v6, v2
	v_add_co_u32_e32 v2, vcc, s1, v0
	v_add_u32_e32 v7, 0x1200, v58
	s_nop 0
	v_addc_co_u32_e32 v3, vcc, 0, v1, vcc
	s_mov_b32 s1, 0x14000
	global_load_dwordx4 v[204:207], v[2:3], off
	v_lshrrev_b32_e32 v2, 5, v7
	v_mul_lo_u32 v2, v2, s96
	v_add_u32_e32 v160, v6, v2
	v_add_co_u32_e32 v2, vcc, s1, v0
	v_add_u32_e32 v7, 0x1400, v58
	s_nop 0
	v_addc_co_u32_e32 v3, vcc, 0, v1, vcc
	s_mov_b32 s1, 0x16000
	global_load_dwordx4 v[208:211], v[2:3], off
	v_lshrrev_b32_e32 v2, 5, v7
	v_mul_lo_u32 v2, v2, s96
	v_add_u32_e32 v162, v6, v2
	v_add_co_u32_e32 v2, vcc, s1, v0
	v_add_u32_e32 v7, 0x1600, v58
	s_nop 0
	v_addc_co_u32_e32 v3, vcc, 0, v1, vcc
	s_mov_b32 s1, 0x1a000
	global_load_dwordx4 v[212:215], v[2:3], off
	v_lshrrev_b32_e32 v2, 5, v7
	v_mul_lo_u32 v2, v2, s96
	v_add_u32_e32 v164, v6, v2
	v_add_co_u32_e32 v2, vcc, s97, v0
	v_add_u32_e32 v7, 0x1800, v58
	s_nop 0
	v_addc_co_u32_e32 v3, vcc, 0, v1, vcc
	global_load_dwordx4 v[216:219], v[2:3], off
	v_lshrrev_b32_e32 v2, 5, v7
	v_mul_lo_u32 v2, v2, s96
	v_add_u32_e32 v165, v6, v2
	v_add_co_u32_e32 v2, vcc, s1, v0
	v_add_u32_e32 v7, 0x1a00, v58
	s_nop 0
	v_addc_co_u32_e32 v3, vcc, 0, v1, vcc
	s_mov_b32 s1, 0x1c000
	global_load_dwordx4 v[220:223], v[2:3], off
	v_lshrrev_b32_e32 v2, 5, v7
	v_mul_lo_u32 v2, v2, s96
	v_add_u32_e32 v166, v6, v2
	v_add_co_u32_e32 v2, vcc, s1, v0
	v_add_u32_e32 v7, 0x1c00, v58
	s_nop 0
	v_addc_co_u32_e32 v3, vcc, 0, v1, vcc
	v_add_co_u32_e32 v0, vcc, 0x1e000, v0
	global_load_dwordx4 v[224:227], v[2:3], off
	v_lshrrev_b32_e32 v2, 5, v7
	v_mul_lo_u32 v2, v2, s96
	v_addc_co_u32_e32 v1, vcc, 0, v1, vcc
	v_add_u32_e32 v167, v6, v2
	global_load_dwordx4 v[228:231], v[0:1], off
	v_add_u32_e32 v7, 0x1e00, v58
	v_lshrrev_b32_e32 v7, 5, v7
	v_mul_lo_u32 v7, v7, s96
	v_add_u32_e32 v175, v6, v7
	s_waitcnt vmcnt(15)
	ds_write_b128 v151, v[128:131]
	s_waitcnt vmcnt(14)
	ds_write_b128 v152, v[132:135]
	s_waitcnt vmcnt(13)
	ds_write_b128 v153, v[136:139]
	s_waitcnt vmcnt(12)
	ds_write_b128 v154, v[140:143]
	s_waitcnt vmcnt(11)
	ds_write_b128 v155, v[144:147]
	s_waitcnt vmcnt(10)
	ds_write_b128 v156, v[176:179]
	s_waitcnt vmcnt(9)
	ds_write_b128 v157, v[180:183]
	s_waitcnt vmcnt(8)
	ds_write_b128 v158, v[184:187]
	s_waitcnt vmcnt(7)
	ds_write_b128 v159, v[188:191]
	s_waitcnt vmcnt(6)
	ds_write_b128 v160, v[204:207]
	s_waitcnt vmcnt(5)
	ds_write_b128 v162, v[208:211]
	s_waitcnt vmcnt(4)
	ds_write_b128 v164, v[212:215]
	s_waitcnt vmcnt(3)
	ds_write_b128 v165, v[216:219]
	s_waitcnt vmcnt(2)
	ds_write_b128 v166, v[220:223]
	s_waitcnt vmcnt(1)
	ds_write_b128 v167, v[224:227]
	s_waitcnt vmcnt(0)
	ds_write_b128 v175, v[228:231]
	s_cbranch_scc1 .LBB0_366
	v_mov_b64_e32 v[0:1], s[86:87]
	v_mad_i64_i32 v[0:1], s[0:1], v163, s66, v[0:1]
	v_readlane_b32 s0, v235, 9
	s_lshl_b32 s94, s0, 1
	v_lshl_add_u64 v[0:1], v[0:1], 0, s[94:95]
	v_lshl_add_u64 v[0:1], v[0:1], 0, v[172:173]
	s_mov_b64 s[0:1], 0x1000
	v_lshl_add_u64 v[2:3], v[0:1], 0, s[0:1]
	v_add_co_u32_e32 v0, vcc, 0x1000, v0
	s_nop 1
	v_addc_co_u32_e32 v1, vcc, 0, v1, vcc
	global_load_dwordx4 v[50:53], v[2:3], off offset:64
	global_load_dwordx4 v[46:49], v[2:3], off offset:128
	global_load_dwordx4 v[42:45], v[2:3], off offset:192
	global_load_dwordx4 v[36:39], v[2:3], off offset:256
	global_load_dwordx4 v[32:35], v[2:3], off offset:320
	global_load_dwordx4 v[28:31], v[2:3], off offset:384
	global_load_dwordx4 v[54:57], v[0:1], off
	global_load_dwordx4 v[24:27], v[2:3], off offset:448

.LBB0_574:
	s_and_b64 s[0:1], s[78:79], exec
	s_cselect_b32 s0, 0xd0, 0
	s_add_i32 s0, s0, s2
	s_lshl_b32 s0, s0, 5
	s_add_i32 s0, s0, 0x7ffffa00
	v_mov_b32_e32 v4, v194
	s_and_b32 s1, s0, 0x7fffff80
	s_nop 0
	v_readfirstlane_b32 s0, v4
	v_and_b32_e32 v6, 15, v4
	s_ashr_i32 s0, s0, 2
	v_or_b32_e32 v7, s1, v6
	v_readlane_b32 s1, v235, 6
	s_and_b32 s0, s0, -16
	s_lshl_b32 s1, s1, 1
	s_add_u32 s4, s45, s1
	s_addc_u32 s5, s44, 0
	v_lshlrev_b32_e32 v0, 4, v4
	v_ashrrev_i32_e32 v5, 31, v4
	v_and_b32_e32 v0, 0x1f0, v0
	v_lshl_add_u64 v[96:97], v[4:5], 4, s[4:5]
	s_barrier
	v_add_u32_e32 v8, 0, v0
	global_load_dwordx4 v[128:131], v[96:97], off
	v_lshrrev_b32_e32 v5, 5, v4
	v_mul_lo_u32 v5, v5, s96
	v_add_u32_e32 v153, v8, v5
	v_add_u32_e32 v5, 0x200, v4
	v_lshrrev_b32_e32 v5, 5, v5
	v_mul_lo_u32 v5, v5, s96
	v_add_u32_e32 v154, v8, v5
	v_add_u32_e32 v5, 0x400, v4
	v_lshrrev_b32_e32 v5, 5, v5
	v_mul_lo_u32 v5, v5, s96
	v_add_u32_e32 v155, v8, v5
	s_movk_i32 s1, 0x6000
	v_add_u32_e32 v5, 0x600, v4
	v_lshrrev_b32_e32 v5, 5, v5
	v_mul_lo_u32 v5, v5, s96
	v_add_u32_e32 v156, v8, v5
	v_add_u32_e32 v5, 0x800, v4
	v_lshrrev_b32_e32 v5, 5, v5
	v_mul_lo_u32 v5, v5, s96
	v_add_u32_e32 v157, v8, v5
	v_add_u32_e32 v5, 0xa00, v4
	v_lshrrev_b32_e32 v5, 5, v5
	v_mul_lo_u32 v5, v5, s96
	v_add_u32_e32 v158, v8, v5
	v_add_u32_e32 v5, 0xc00, v4
	v_lshrrev_b32_e32 v5, 5, v5
	v_mul_lo_u32 v5, v5, s96
	v_add_u32_e32 v159, v8, v5
	v_add_u32_e32 v5, 0xe00, v4
	v_lshrrev_b32_e32 v5, 5, v5
	v_mul_lo_u32 v5, v5, s96
	v_add_u32_e32 v160, v8, v5
	v_add_u32_e32 v5, 0x1000, v4
	v_lshrrev_b32_e32 v5, 5, v5
	v_mul_lo_u32 v5, v5, s96
	v_add_u32_e32 v161, v8, v5
	v_add_u32_e32 v5, 0x1200, v4
	v_lshrrev_b32_e32 v5, 5, v5
	v_mul_lo_u32 v5, v5, s96
	v_add_u32_e32 v162, v8, v5
	v_add_u32_e32 v5, 0x1400, v4
	v_lshrrev_b32_e32 v5, 5, v5
	v_mul_lo_u32 v5, v5, s96
	v_add_u32_e32 v164, v8, v5
	v_add_u32_e32 v5, 0x1600, v4
	v_lshrrev_b32_e32 v5, 5, v5
	v_mul_lo_u32 v5, v5, s96
	v_add_u32_e32 v166, v8, v5
	v_add_u32_e32 v5, 0x1800, v4
	v_lshrrev_b32_e32 v5, 5, v5
	v_mul_lo_u32 v5, v5, s96
	v_add_u32_e32 v167, v8, v5
	v_add_u32_e32 v5, 0x1a00, v4
	v_lshrrev_b32_e32 v5, 5, v5
	v_mul_lo_u32 v5, v5, s96
	v_add_u32_e32 v174, v8, v5
	v_add_u32_e32 v5, 0x1c00, v4
	v_lshrrev_b32_e32 v5, 5, v5
	v_mul_lo_u32 v5, v5, s96
	v_add_u32_e32 v175, v8, v5
	v_add_u32_e32 v5, 0x1e00, v4
	v_lshrrev_b32_e32 v5, 5, v5
	v_mul_lo_u32 v5, v5, s96
	v_bfe_u32 v163, v4, 4, 2
	s_cmpk_lt_i32 s0, 0x80
	v_add_u32_e32 v177, v8, v5
	s_cselect_b64 s[4:5], -1, 0
	s_cmpk_gt_i32 s0, 0x7f
	v_add_u32_e32 v165, s0, v7
	v_lshlrev_b32_e32 v172, 4, v163
	v_add_co_u32_e32 v0, vcc, s92, v96
	s_nop 1
	v_addc_co_u32_e32 v1, vcc, 0, v97, vcc
	global_load_dwordx4 v[132:135], v[0:1], off
	v_add_co_u32_e32 v0, vcc, s75, v96
	s_nop 1
	v_addc_co_u32_e32 v1, vcc, 0, v97, vcc
	global_load_dwordx4 v[136:139], v[0:1], off
	v_add_co_u32_e32 v0, vcc, s1, v96
	s_mov_b32 s1, 0x8000
	s_nop 0
	v_addc_co_u32_e32 v1, vcc, 0, v97, vcc
	global_load_dwordx4 v[140:143], v[0:1], off
	v_add_co_u32_e32 v0, vcc, s1, v96
	s_mov_b32 s1, 0xa000
	s_nop 0
	v_addc_co_u32_e32 v1, vcc, 0, v97, vcc
	global_load_dwordx4 v[144:147], v[0:1], off
	v_add_co_u32_e32 v0, vcc, s1, v96
	s_mov_b32 s1, 0xc000
	s_nop 0
	v_addc_co_u32_e32 v1, vcc, 0, v97, vcc
	global_load_dwordx4 v[148:151], v[0:1], off
	v_add_co_u32_e32 v0, vcc, s1, v96
	s_mov_b32 s1, 0xe000
	s_nop 0
	v_addc_co_u32_e32 v1, vcc, 0, v97, vcc
	global_load_dwordx4 v[180:183], v[0:1], off
	v_add_co_u32_e32 v0, vcc, s1, v96
	s_mov_b32 s1, 0x10000
	s_nop 0
	v_addc_co_u32_e32 v1, vcc, 0, v97, vcc
	global_load_dwordx4 v[184:187], v[0:1], off
	v_add_co_u32_e32 v0, vcc, s1, v96
	s_mov_b32 s1, 0x12000
	s_nop 0
	v_addc_co_u32_e32 v1, vcc, 0, v97, vcc
	global_load_dwordx4 v[188:191], v[0:1], off
	v_add_co_u32_e32 v0, vcc, s1, v96
	s_mov_b32 s1, 0x14000
	s_nop 0
	v_addc_co_u32_e32 v1, vcc, 0, v97, vcc
	global_load_dwordx4 v[204:207], v[0:1], off
	v_add_co_u32_e32 v0, vcc, s1, v96
	s_mov_b32 s1, 0x16000
	s_nop 0
	v_addc_co_u32_e32 v1, vcc, 0, v97, vcc
	global_load_dwordx4 v[208:211], v[0:1], off
	v_add_co_u32_e32 v0, vcc, s1, v96
	s_mov_b32 s1, 0x1a000
	s_nop 0
	v_addc_co_u32_e32 v1, vcc, 0, v97, vcc
	global_load_dwordx4 v[212:215], v[0:1], off
	v_add_co_u32_e32 v0, vcc, s97, v96
	s_nop 1
	v_addc_co_u32_e32 v1, vcc, 0, v97, vcc
	global_load_dwordx4 v[216:219], v[0:1], off
	v_add_co_u32_e32 v0, vcc, s1, v96
	s_mov_b32 s1, 0x1c000
	s_nop 0
	v_addc_co_u32_e32 v1, vcc, 0, v97, vcc
	global_load_dwordx4 v[220:223], v[0:1], off
	v_add_co_u32_e32 v0, vcc, s1, v96
	s_nop 1
	v_addc_co_u32_e32 v1, vcc, 0, v97, vcc
	global_load_dwordx4 v[224:227], v[0:1], off
	v_add_co_u32_e32 v0, vcc, 0x1e000, v96
	s_nop 1
	v_addc_co_u32_e32 v1, vcc, 0, v97, vcc
	global_load_dwordx4 v[228:231], v[0:1], off
	s_waitcnt vmcnt(15)
	ds_write_b128 v153, v[128:131]
	s_waitcnt vmcnt(14)
	ds_write_b128 v154, v[132:135]
	s_waitcnt vmcnt(13)
	ds_write_b128 v155, v[136:139]
	s_waitcnt vmcnt(12)
	ds_write_b128 v156, v[140:143]
	s_waitcnt vmcnt(11)
	ds_write_b128 v157, v[144:147]
	s_waitcnt vmcnt(10)
	ds_write_b128 v158, v[148:151]
	s_waitcnt vmcnt(9)
	ds_write_b128 v159, v[180:183]
	s_waitcnt vmcnt(8)
	ds_write_b128 v160, v[184:187]
	s_waitcnt vmcnt(7)
	ds_write_b128 v161, v[188:191]
	s_waitcnt vmcnt(6)
	ds_write_b128 v162, v[204:207]
	s_waitcnt vmcnt(5)
	ds_write_b128 v164, v[208:211]
	s_waitcnt vmcnt(4)
	ds_write_b128 v166, v[212:215]
	s_waitcnt vmcnt(3)
	ds_write_b128 v167, v[216:219]
	s_waitcnt vmcnt(2)
	ds_write_b128 v174, v[220:223]
	s_waitcnt vmcnt(1)
	ds_write_b128 v175, v[224:227]
	s_waitcnt vmcnt(0)
	ds_write_b128 v177, v[228:231]
	s_cbranch_scc1 .LBB0_576
	v_mov_b64_e32 v[0:1], s[86:87]
	v_mad_i64_i32 v[0:1], s[0:1], v165, s66, v[0:1]
	v_readlane_b32 s0, v235, 9
	s_lshl_b32 s94, s0, 1
	v_lshl_add_u64 v[0:1], v[0:1], 0, s[94:95]
	v_lshl_add_u64 v[0:1], v[0:1], 0, v[172:173]
	s_mov_b64 s[0:1], 0x1000
	v_lshl_add_u64 v[2:3], v[0:1], 0, s[0:1]
	v_add_co_u32_e32 v0, vcc, 0x1000, v0
	s_nop 1
	v_addc_co_u32_e32 v1, vcc, 0, v1, vcc
	global_load_dwordx4 v[50:53], v[2:3], off offset:64
	global_load_dwordx4 v[46:49], v[2:3], off offset:128
	global_load_dwordx4 v[42:45], v[2:3], off offset:192
	global_load_dwordx4 v[36:39], v[2:3], off offset:256
	global_load_dwordx4 v[32:35], v[2:3], off offset:320
	global_load_dwordx4 v[28:31], v[2:3], off offset:384
	global_load_dwordx4 v[54:57], v[0:1], off
	global_load_dwordx4 v[24:27], v[2:3], off offset:448

.LBB0_588:
	s_ashr_i32 s0, s16, 2
	s_ashr_i32 s1, s0, 31
	s_lshl_b64 s[4:5], s[0:1], 20
	s_lshl_b32 s0, s0, 5
	v_mov_b32_e32 v4, v194
	s_add_i32 s1, s0, 0x4000
	s_nop 0
	v_readfirstlane_b32 s0, v4
	s_ashr_i32 s0, s0, 2
	v_and_b32_e32 v6, 15, v4
	s_and_b32 s0, s0, -16
	v_or_b32_e32 v7, s1, v6
	s_add_u32 s1, s8, s4
	s_addc_u32 s5, s9, s5
	s_add_u32 s4, s1, 0x100000
	s_addc_u32 s5, s5, 0
	v_lshlrev_b32_e32 v0, 4, v4
	v_ashrrev_i32_e32 v5, 31, v4
	v_and_b32_e32 v0, 0x1f0, v0
	v_lshl_add_u64 v[96:97], v[4:5], 4, s[4:5]
	s_barrier
	v_add_u32_e32 v8, 0, v0
	global_load_dwordx4 v[92:95], v[96:97], off
	v_lshrrev_b32_e32 v5, 5, v4
	v_mul_lo_u32 v5, v5, s96
	v_add_u32_e32 v153, v8, v5
	v_add_u32_e32 v5, 0x200, v4
	v_lshrrev_b32_e32 v5, 5, v5
	v_mul_lo_u32 v5, v5, s96
	v_add_u32_e32 v154, v8, v5
	v_add_u32_e32 v5, 0x400, v4
	v_lshrrev_b32_e32 v5, 5, v5
	v_mul_lo_u32 v5, v5, s96
	v_add_u32_e32 v155, v8, v5
	s_movk_i32 s1, 0x6000
	v_add_u32_e32 v5, 0x600, v4
	v_lshrrev_b32_e32 v5, 5, v5
	v_mul_lo_u32 v5, v5, s96
	v_add_u32_e32 v156, v8, v5
	v_add_u32_e32 v5, 0x800, v4
	v_lshrrev_b32_e32 v5, 5, v5
	v_mul_lo_u32 v5, v5, s96
	v_add_u32_e32 v157, v8, v5
	v_add_u32_e32 v5, 0xa00, v4
	v_lshrrev_b32_e32 v5, 5, v5
	v_mul_lo_u32 v5, v5, s96
	v_add_u32_e32 v158, v8, v5
	v_add_u32_e32 v5, 0xc00, v4
	v_lshrrev_b32_e32 v5, 5, v5
	v_mul_lo_u32 v5, v5, s96
	v_add_u32_e32 v159, v8, v5
	v_add_u32_e32 v5, 0xe00, v4
	v_lshrrev_b32_e32 v5, 5, v5
	v_mul_lo_u32 v5, v5, s96
	v_add_u32_e32 v160, v8, v5
	v_add_u32_e32 v5, 0x1000, v4
	v_lshrrev_b32_e32 v5, 5, v5
	v_mul_lo_u32 v5, v5, s96
	v_add_u32_e32 v161, v8, v5
	v_add_u32_e32 v5, 0x1200, v4
	v_lshrrev_b32_e32 v5, 5, v5
	v_mul_lo_u32 v5, v5, s96
	v_add_u32_e32 v162, v8, v5
	v_add_u32_e32 v5, 0x1400, v4
	v_lshrrev_b32_e32 v5, 5, v5
	v_mul_lo_u32 v5, v5, s96
	v_add_u32_e32 v164, v8, v5
	v_add_u32_e32 v5, 0x1600, v4
	v_lshrrev_b32_e32 v5, 5, v5
	v_mul_lo_u32 v5, v5, s96
	v_add_u32_e32 v166, v8, v5
	v_add_u32_e32 v5, 0x1800, v4
	v_lshrrev_b32_e32 v5, 5, v5
	v_mul_lo_u32 v5, v5, s96
	v_add_u32_e32 v167, v8, v5
	v_add_u32_e32 v5, 0x1a00, v4
	v_lshrrev_b32_e32 v5, 5, v5
	v_mul_lo_u32 v5, v5, s96
	v_add_u32_e32 v174, v8, v5
	v_add_u32_e32 v5, 0x1c00, v4
	v_lshrrev_b32_e32 v5, 5, v5
	v_mul_lo_u32 v5, v5, s96
	v_add_u32_e32 v175, v8, v5
	v_add_u32_e32 v5, 0x1e00, v4
	v_lshrrev_b32_e32 v5, 5, v5
	v_mul_lo_u32 v5, v5, s96
	v_bfe_u32 v163, v4, 4, 2
	s_cmp_lt_i32 s0, 32
	v_add_u32_e32 v177, v8, v5
	s_cselect_b64 s[4:5], -1, 0
	s_cmp_gt_i32 s0, 31
	v_add_u32_e32 v165, s0, v7
	v_lshlrev_b32_e32 v172, 4, v163
	v_add_co_u32_e32 v0, vcc, s92, v96
	s_nop 1
	v_addc_co_u32_e32 v1, vcc, 0, v97, vcc
	global_load_dwordx4 v[100:103], v[0:1], off
	v_add_co_u32_e32 v0, vcc, s75, v96
	s_nop 1
	v_addc_co_u32_e32 v1, vcc, 0, v97, vcc
	global_load_dwordx4 v[104:107], v[0:1], off
	v_add_co_u32_e32 v0, vcc, s1, v96
	s_mov_b32 s1, 0x8000
	s_nop 0
	v_addc_co_u32_e32 v1, vcc, 0, v97, vcc
	global_load_dwordx4 v[108:111], v[0:1], off
	v_add_co_u32_e32 v0, vcc, s1, v96
	s_mov_b32 s1, 0xa000
	s_nop 0
	v_addc_co_u32_e32 v1, vcc, 0, v97, vcc
	global_load_dwordx4 v[112:115], v[0:1], off
	v_add_co_u32_e32 v0, vcc, s1, v96
	s_mov_b32 s1, 0xc000
	s_nop 0
	v_addc_co_u32_e32 v1, vcc, 0, v97, vcc
	global_load_dwordx4 v[116:119], v[0:1], off
	v_add_co_u32_e32 v0, vcc, s1, v96
	s_mov_b32 s1, 0xe000
	s_nop 0
	v_addc_co_u32_e32 v1, vcc, 0, v97, vcc
	global_load_dwordx4 v[120:123], v[0:1], off
	v_add_co_u32_e32 v0, vcc, s1, v96
	s_mov_b32 s1, 0x10000
	s_nop 0
	v_addc_co_u32_e32 v1, vcc, 0, v97, vcc
	global_load_dwordx4 v[124:127], v[0:1], off
	v_add_co_u32_e32 v0, vcc, s1, v96
	s_mov_b32 s1, 0x12000
	s_nop 0
	v_addc_co_u32_e32 v1, vcc, 0, v97, vcc
	global_load_dwordx4 v[128:131], v[0:1], off
	v_add_co_u32_e32 v0, vcc, s1, v96
	s_mov_b32 s1, 0x14000
	s_nop 0
	v_addc_co_u32_e32 v1, vcc, 0, v97, vcc
	global_load_dwordx4 v[132:135], v[0:1], off
	v_add_co_u32_e32 v0, vcc, s1, v96
	s_mov_b32 s1, 0x16000
	s_nop 0
	v_addc_co_u32_e32 v1, vcc, 0, v97, vcc
	global_load_dwordx4 v[136:139], v[0:1], off
	v_add_co_u32_e32 v0, vcc, s1, v96
	s_mov_b32 s1, 0x1a000
	s_nop 0
	v_addc_co_u32_e32 v1, vcc, 0, v97, vcc
	global_load_dwordx4 v[140:143], v[0:1], off
	v_add_co_u32_e32 v0, vcc, s97, v96
	s_nop 1
	v_addc_co_u32_e32 v1, vcc, 0, v97, vcc
	global_load_dwordx4 v[144:147], v[0:1], off
	v_add_co_u32_e32 v0, vcc, s1, v96
	s_mov_b32 s1, 0x1c000
	s_nop 0
	v_addc_co_u32_e32 v1, vcc, 0, v97, vcc
	global_load_dwordx4 v[148:151], v[0:1], off
	v_add_co_u32_e32 v0, vcc, s1, v96
	s_nop 1
	v_addc_co_u32_e32 v1, vcc, 0, v97, vcc
	global_load_dwordx4 v[180:183], v[0:1], off
	v_add_co_u32_e32 v0, vcc, 0x1e000, v96
	s_nop 1
	v_addc_co_u32_e32 v1, vcc, 0, v97, vcc
	global_load_dwordx4 v[184:187], v[0:1], off
	s_waitcnt vmcnt(15)
	ds_write_b128 v153, v[92:95]
	s_waitcnt vmcnt(14)
	ds_write_b128 v154, v[100:103]
	s_waitcnt vmcnt(13)
	ds_write_b128 v155, v[104:107]
	s_waitcnt vmcnt(12)
	ds_write_b128 v156, v[108:111]
	s_waitcnt vmcnt(11)
	ds_write_b128 v157, v[112:115]
	s_waitcnt vmcnt(10)
	ds_write_b128 v158, v[116:119]
	s_waitcnt vmcnt(9)
	ds_write_b128 v159, v[120:123]
	s_waitcnt vmcnt(8)
	ds_write_b128 v160, v[124:127]
	s_waitcnt vmcnt(7)
	ds_write_b128 v161, v[128:131]
	s_waitcnt vmcnt(6)
	ds_write_b128 v162, v[132:135]
	s_waitcnt vmcnt(5)
	ds_write_b128 v164, v[136:139]
	s_waitcnt vmcnt(4)
	ds_write_b128 v166, v[140:143]
	s_waitcnt vmcnt(3)
	ds_write_b128 v167, v[144:147]
	s_waitcnt vmcnt(2)
	ds_write_b128 v174, v[148:151]
	s_waitcnt vmcnt(1)
	ds_write_b128 v175, v[180:183]
	s_waitcnt vmcnt(0)
	ds_write_b128 v177, v[184:187]
	s_cbranch_scc1 .LBB0_590
	v_mov_b64_e32 v[0:1], s[86:87]
	v_mad_i64_i32 v[0:1], s[0:1], v165, s66, v[0:1]
	v_readlane_b32 s0, v235, 9
	s_lshl_b32 s94, s0, 1
	v_lshl_add_u64 v[0:1], v[0:1], 0, s[94:95]
	v_lshl_add_u64 v[0:1], v[0:1], 0, v[172:173]
	s_mov_b64 s[0:1], 0x1000
	v_lshl_add_u64 v[2:3], v[0:1], 0, s[0:1]
	v_add_co_u32_e32 v0, vcc, 0x1000, v0
	s_nop 1
	v_addc_co_u32_e32 v1, vcc, 0, v1, vcc
	global_load_dwordx4 v[50:53], v[2:3], off offset:64
	global_load_dwordx4 v[46:49], v[2:3], off offset:128
	global_load_dwordx4 v[42:45], v[2:3], off offset:192
	global_load_dwordx4 v[36:39], v[2:3], off offset:256
	global_load_dwordx4 v[32:35], v[2:3], off offset:320
	global_load_dwordx4 v[28:31], v[2:3], off offset:384
	global_load_dwordx4 v[54:57], v[0:1], off
	global_load_dwordx4 v[24:27], v[2:3], off offset:448

.LBB0_790:
	v_readlane_b32 s0, v234, 61
	v_readlane_b32 s1, v234, 62
	s_andn2_b64 vcc, exec, s[0:1]
	s_cbranch_vccnz .LBB0_808
	v_mov_b32_e32 v58, v194
	v_readlane_b32 s4, v234, 1
	v_lshlrev_b32_e32 v0, 4, v58
	v_and_b32_e32 v0, 0x1f0, v0
	v_ashrrev_i32_e32 v59, 31, v58
	v_readlane_b32 s5, v234, 2
	v_add_u32_e32 v6, 0, v0
	s_nop 0
	v_lshl_add_u64 v[0:1], v[58:59], 4, s[4:5]
	s_barrier
	global_load_dwordx4 v[128:131], v[0:1], off
	v_lshrrev_b32_e32 v2, 5, v58
	v_mul_lo_u32 v2, v2, s96
	v_add_u32_e32 v151, v6, v2
	v_add_co_u32_e32 v2, vcc, s92, v0
	v_add_u32_e32 v7, 0x200, v58
	s_nop 0
	v_addc_co_u32_e32 v3, vcc, 0, v1, vcc
	v_and_b32_e32 v4, 15, v58
	v_readlane_b32 s1, v235, 61
	v_readfirstlane_b32 s0, v58
	s_ashr_i32 s0, s0, 2
	v_or_b32_e32 v5, s1, v4
	s_movk_i32 s1, 0x6000
	s_and_b32 s0, s0, -16
	v_bfe_u32 v161, v58, 4, 2
	s_cmpk_lt_i32 s0, 0x80
	s_cselect_b64 s[4:5], -1, 0
	s_cmpk_gt_i32 s0, 0x7f
	v_add_u32_e32 v163, s0, v5
	v_lshlrev_b32_e32 v172, 4, v161
	global_load_dwordx4 v[132:135], v[2:3], off
	v_lshrrev_b32_e32 v2, 5, v7
	v_mul_lo_u32 v2, v2, s96
	v_add_u32_e32 v152, v6, v2
	v_add_co_u32_e32 v2, vcc, s75, v0
	v_add_u32_e32 v7, 0x400, v58
	s_nop 0
	v_addc_co_u32_e32 v3, vcc, 0, v1, vcc
	global_load_dwordx4 v[136:139], v[2:3], off
	v_lshrrev_b32_e32 v2, 5, v7
	v_mul_lo_u32 v2, v2, s96
	v_add_u32_e32 v153, v6, v2
	v_add_co_u32_e32 v2, vcc, s1, v0
	v_add_u32_e32 v7, 0x600, v58
	s_nop 0
	v_addc_co_u32_e32 v3, vcc, 0, v1, vcc
	s_mov_b32 s1, 0x8000
	global_load_dwordx4 v[140:143], v[2:3], off
	v_lshrrev_b32_e32 v2, 5, v7
	v_mul_lo_u32 v2, v2, s96
	v_add_u32_e32 v154, v6, v2
	v_add_co_u32_e32 v2, vcc, s1, v0
	v_add_u32_e32 v7, 0x800, v58
	s_nop 0
	v_addc_co_u32_e32 v3, vcc, 0, v1, vcc
	s_mov_b32 s1, 0xa000
	global_load_dwordx4 v[144:147], v[2:3], off
	v_lshrrev_b32_e32 v2, 5, v7
	v_mul_lo_u32 v2, v2, s96
	v_add_u32_e32 v155, v6, v2
	v_add_co_u32_e32 v2, vcc, s1, v0
	v_add_u32_e32 v7, 0xa00, v58
	s_nop 0
	v_addc_co_u32_e32 v3, vcc, 0, v1, vcc
	s_mov_b32 s1, 0xc000
	global_load_dwordx4 v[176:179], v[2:3], off
	v_lshrrev_b32_e32 v2, 5, v7
	v_mul_lo_u32 v2, v2, s96
	v_add_u32_e32 v156, v6, v2
	v_add_co_u32_e32 v2, vcc, s1, v0
	v_add_u32_e32 v7, 0xc00, v58
	s_nop 0
	v_addc_co_u32_e32 v3, vcc, 0, v1, vcc
	s_mov_b32 s1, 0xe000
	global_load_dwordx4 v[180:183], v[2:3], off
	v_lshrrev_b32_e32 v2, 5, v7
	v_mul_lo_u32 v2, v2, s96
	v_add_u32_e32 v157, v6, v2
	v_add_co_u32_e32 v2, vcc, s1, v0
	v_add_u32_e32 v7, 0xe00, v58
	s_nop 0
	v_addc_co_u32_e32 v3, vcc, 0, v1, vcc
	s_mov_b32 s1, 0x10000
	global_load_dwordx4 v[184:187], v[2:3], off
	v_lshrrev_b32_e32 v2, 5, v7
	v_mul_lo_u32 v2, v2, s96
	v_add_u32_e32 v158, v6, v2
	v_add_co_u32_e32 v2, vcc, s1, v0
	v_add_u32_e32 v7, 0x1000, v58
	s_nop 0
	v_addc_co_u32_e32 v3, vcc, 0, v1, vcc
	s_mov_b32 s1, 0x12000
	global_load_dwordx4 v[188:191], v[2:3], off
	v_lshrrev_b32_e32 v2, 5, v7
	v_mul_lo_u32 v2, v2, s96
	v_add_u32_e32 v159, v6, v2
	v_add_co_u32_e32 v2, vcc, s1, v0
	v_add_u32_e32 v7, 0x1200, v58
	s_nop 0
	v_addc_co_u32_e32 v3, vcc, 0, v1, vcc
	s_mov_b32 s1, 0x14000
	global_load_dwordx4 v[204:207], v[2:3], off
	v_lshrrev_b32_e32 v2, 5, v7
	v_mul_lo_u32 v2, v2, s96
	v_add_u32_e32 v160, v6, v2
	v_add_co_u32_e32 v2, vcc, s1, v0
	v_add_u32_e32 v7, 0x1400, v58
	s_nop 0
	v_addc_co_u32_e32 v3, vcc, 0, v1, vcc
	s_mov_b32 s1, 0x16000
	global_load_dwordx4 v[208:211], v[2:3], off
	v_lshrrev_b32_e32 v2, 5, v7
	v_mul_lo_u32 v2, v2, s96
	v_add_u32_e32 v162, v6, v2
	v_add_co_u32_e32 v2, vcc, s1, v0
	v_add_u32_e32 v7, 0x1600, v58
	s_nop 0
	v_addc_co_u32_e32 v3, vcc, 0, v1, vcc
	s_mov_b32 s1, 0x1a000
	global_load_dwordx4 v[212:215], v[2:3], off
	v_lshrrev_b32_e32 v2, 5, v7
	v_mul_lo_u32 v2, v2, s96
	v_add_u32_e32 v164, v6, v2
	v_add_co_u32_e32 v2, vcc, s97, v0
	v_add_u32_e32 v7, 0x1800, v58
	s_nop 0
	v_addc_co_u32_e32 v3, vcc, 0, v1, vcc
	global_load_dwordx4 v[216:219], v[2:3], off
	v_lshrrev_b32_e32 v2, 5, v7
	v_mul_lo_u32 v2, v2, s96
	v_add_u32_e32 v165, v6, v2
	v_add_co_u32_e32 v2, vcc, s1, v0
	v_add_u32_e32 v7, 0x1a00, v58
	s_nop 0
	v_addc_co_u32_e32 v3, vcc, 0, v1, vcc
	s_mov_b32 s1, 0x1c000
	global_load_dwordx4 v[220:223], v[2:3], off
	v_lshrrev_b32_e32 v2, 5, v7
	v_mul_lo_u32 v2, v2, s96
	v_add_u32_e32 v166, v6, v2
	v_add_co_u32_e32 v2, vcc, s1, v0
	v_add_u32_e32 v7, 0x1c00, v58
	s_nop 0
	v_addc_co_u32_e32 v3, vcc, 0, v1, vcc
	v_add_co_u32_e32 v0, vcc, 0x1e000, v0
	global_load_dwordx4 v[224:227], v[2:3], off
	v_lshrrev_b32_e32 v2, 5, v7
	v_mul_lo_u32 v2, v2, s96
	v_addc_co_u32_e32 v1, vcc, 0, v1, vcc
	v_add_u32_e32 v167, v6, v2
	global_load_dwordx4 v[228:231], v[0:1], off
	v_add_u32_e32 v7, 0x1e00, v58
	v_lshrrev_b32_e32 v7, 5, v7
	v_mul_lo_u32 v7, v7, s96
	v_add_u32_e32 v175, v6, v7
	s_waitcnt vmcnt(15)
	ds_write_b128 v151, v[128:131]
	s_waitcnt vmcnt(14)
	ds_write_b128 v152, v[132:135]
	s_waitcnt vmcnt(13)
	ds_write_b128 v153, v[136:139]
	s_waitcnt vmcnt(12)
	ds_write_b128 v154, v[140:143]
	s_waitcnt vmcnt(11)
	ds_write_b128 v155, v[144:147]
	s_waitcnt vmcnt(10)
	ds_write_b128 v156, v[176:179]
	s_waitcnt vmcnt(9)
	ds_write_b128 v157, v[180:183]
	s_waitcnt vmcnt(8)
	ds_write_b128 v158, v[184:187]
	s_waitcnt vmcnt(7)
	ds_write_b128 v159, v[188:191]
	s_waitcnt vmcnt(6)
	ds_write_b128 v160, v[204:207]
	s_waitcnt vmcnt(5)
	ds_write_b128 v162, v[208:211]
	s_waitcnt vmcnt(4)
	ds_write_b128 v164, v[212:215]
	s_waitcnt vmcnt(3)
	ds_write_b128 v165, v[216:219]
	s_waitcnt vmcnt(2)
	ds_write_b128 v166, v[220:223]
	s_waitcnt vmcnt(1)
	ds_write_b128 v167, v[224:227]
	s_waitcnt vmcnt(0)
	ds_write_b128 v175, v[228:231]
	s_cbranch_scc1 .LBB0_793
	v_mov_b64_e32 v[0:1], s[86:87]
	v_mad_i64_i32 v[0:1], s[0:1], v163, s66, v[0:1]
	v_readlane_b32 s0, v235, 9
	s_lshl_b32 s94, s0, 1
	v_lshl_add_u64 v[0:1], v[0:1], 0, s[94:95]
	v_lshl_add_u64 v[0:1], v[0:1], 0, v[172:173]
	s_mov_b64 s[0:1], 0x1000
	v_lshl_add_u64 v[2:3], v[0:1], 0, s[0:1]
	v_add_co_u32_e32 v0, vcc, 0x1000, v0
	s_nop 1
	v_addc_co_u32_e32 v1, vcc, 0, v1, vcc
	global_load_dwordx4 v[50:53], v[2:3], off offset:64
	global_load_dwordx4 v[46:49], v[2:3], off offset:128
	global_load_dwordx4 v[42:45], v[2:3], off offset:192
	global_load_dwordx4 v[36:39], v[2:3], off offset:256
	global_load_dwordx4 v[32:35], v[2:3], off offset:320
	global_load_dwordx4 v[28:31], v[2:3], off offset:384
	global_load_dwordx4 v[54:57], v[0:1], off
	global_load_dwordx4 v[24:27], v[2:3], off offset:448

.LBB0_799:
	s_mov_b64 s[4:5], 0
	s_andn2_b64 vcc, exec, s[40:41]
	s_mov_b64 s[8:9], 0
	s_cbranch_vccnz .LBB0_809
	v_mov_b32_e32 v58, v194
	v_readlane_b32 s6, v234, 1
	v_lshlrev_b32_e32 v0, 4, v58
	v_and_b32_e32 v0, 0x1f0, v0
	v_ashrrev_i32_e32 v59, 31, v58
	v_readlane_b32 s7, v234, 2
	v_add_u32_e32 v6, 0, v0
	s_nop 0
	v_lshl_add_u64 v[0:1], v[58:59], 4, s[6:7]
	s_barrier
	global_load_dwordx4 v[92:95], v[0:1], off
	v_lshrrev_b32_e32 v2, 5, v58
	v_mul_lo_u32 v2, v2, s96
	v_add_u32_e32 v153, v6, v2
	v_add_co_u32_e32 v2, vcc, s92, v0
	v_add_u32_e32 v7, 0x200, v58
	s_nop 0
	v_addc_co_u32_e32 v3, vcc, 0, v1, vcc
	v_and_b32_e32 v4, 15, v58
	v_readlane_b32 s1, v234, 5
	v_readfirstlane_b32 s0, v58
	s_ashr_i32 s0, s0, 2
	v_or_b32_e32 v5, s1, v4
	s_movk_i32 s1, 0x6000
	s_and_b32 s0, s0, -16
	v_bfe_u32 v163, v58, 4, 2
	s_cmpk_lt_i32 s0, 0x80
	s_cselect_b64 s[8:9], -1, 0
	s_cmpk_gt_i32 s0, 0x7f
	v_add_u32_e32 v164, s0, v5
	v_lshlrev_b32_e32 v172, 4, v163
	global_load_dwordx4 v[96:99], v[2:3], off
	v_lshrrev_b32_e32 v2, 5, v7
	v_mul_lo_u32 v2, v2, s96
	v_add_u32_e32 v154, v6, v2
	v_add_co_u32_e32 v2, vcc, s75, v0
	v_add_u32_e32 v7, 0x400, v58
	s_nop 0
	v_addc_co_u32_e32 v3, vcc, 0, v1, vcc
	global_load_dwordx4 v[100:103], v[2:3], off
	v_lshrrev_b32_e32 v2, 5, v7
	v_mul_lo_u32 v2, v2, s96
	v_add_u32_e32 v155, v6, v2
	v_add_co_u32_e32 v2, vcc, s1, v0
	v_add_u32_e32 v7, 0x600, v58
	s_nop 0
	v_addc_co_u32_e32 v3, vcc, 0, v1, vcc
	s_mov_b32 s1, 0x8000
	global_load_dwordx4 v[104:107], v[2:3], off
	v_lshrrev_b32_e32 v2, 5, v7
	v_mul_lo_u32 v2, v2, s96
	v_add_u32_e32 v156, v6, v2
	v_add_co_u32_e32 v2, vcc, s1, v0
	v_add_u32_e32 v7, 0x800, v58
	s_nop 0
	v_addc_co_u32_e32 v3, vcc, 0, v1, vcc
	s_mov_b32 s1, 0xa000
	global_load_dwordx4 v[108:111], v[2:3], off
	v_lshrrev_b32_e32 v2, 5, v7
	v_mul_lo_u32 v2, v2, s96
	v_add_u32_e32 v157, v6, v2
	v_add_co_u32_e32 v2, vcc, s1, v0
	v_add_u32_e32 v7, 0xa00, v58
	s_nop 0
	v_addc_co_u32_e32 v3, vcc, 0, v1, vcc
	s_mov_b32 s1, 0xc000
	global_load_dwordx4 v[112:115], v[2:3], off
	v_lshrrev_b32_e32 v2, 5, v7
	v_mul_lo_u32 v2, v2, s96
	v_add_u32_e32 v158, v6, v2
	v_add_co_u32_e32 v2, vcc, s1, v0
	v_add_u32_e32 v7, 0xc00, v58
	s_nop 0
	v_addc_co_u32_e32 v3, vcc, 0, v1, vcc
	s_mov_b32 s1, 0xe000
	global_load_dwordx4 v[116:119], v[2:3], off
	v_lshrrev_b32_e32 v2, 5, v7
	v_mul_lo_u32 v2, v2, s96
	v_add_u32_e32 v159, v6, v2
	v_add_co_u32_e32 v2, vcc, s1, v0
	v_add_u32_e32 v7, 0xe00, v58
	s_nop 0
	v_addc_co_u32_e32 v3, vcc, 0, v1, vcc
	s_mov_b32 s1, 0x10000
	global_load_dwordx4 v[120:123], v[2:3], off
	v_lshrrev_b32_e32 v2, 5, v7
	v_mul_lo_u32 v2, v2, s96
	v_add_u32_e32 v160, v6, v2
	v_add_co_u32_e32 v2, vcc, s1, v0
	v_add_u32_e32 v7, 0x1000, v58
	s_nop 0
	v_addc_co_u32_e32 v3, vcc, 0, v1, vcc
	s_mov_b32 s1, 0x12000
	global_load_dwordx4 v[124:127], v[2:3], off
	v_lshrrev_b32_e32 v2, 5, v7
	v_mul_lo_u32 v2, v2, s96
	v_add_u32_e32 v161, v6, v2
	v_add_co_u32_e32 v2, vcc, s1, v0
	v_add_u32_e32 v7, 0x1200, v58
	s_nop 0
	v_addc_co_u32_e32 v3, vcc, 0, v1, vcc
	s_mov_b32 s1, 0x14000
	global_load_dwordx4 v[128:131], v[2:3], off
	v_lshrrev_b32_e32 v2, 5, v7
	v_mul_lo_u32 v2, v2, s96
	v_add_u32_e32 v162, v6, v2
	v_add_co_u32_e32 v2, vcc, s1, v0
	v_add_u32_e32 v7, 0x1400, v58
	s_nop 0
	v_addc_co_u32_e32 v3, vcc, 0, v1, vcc
	s_mov_b32 s1, 0x16000
	global_load_dwordx4 v[132:135], v[2:3], off
	v_lshrrev_b32_e32 v2, 5, v7
	v_mul_lo_u32 v2, v2, s96
	v_add_u32_e32 v165, v6, v2
	v_add_co_u32_e32 v2, vcc, s1, v0
	v_add_u32_e32 v7, 0x1600, v58
	s_nop 0
	v_addc_co_u32_e32 v3, vcc, 0, v1, vcc
	s_mov_b32 s1, 0x1a000
	global_load_dwordx4 v[136:139], v[2:3], off
	v_lshrrev_b32_e32 v2, 5, v7
	v_mul_lo_u32 v2, v2, s96
	v_add_u32_e32 v166, v6, v2
	v_add_co_u32_e32 v2, vcc, s97, v0
	v_add_u32_e32 v7, 0x1800, v58
	s_nop 0
	v_addc_co_u32_e32 v3, vcc, 0, v1, vcc
	global_load_dwordx4 v[140:143], v[2:3], off
	v_lshrrev_b32_e32 v2, 5, v7
	v_mul_lo_u32 v2, v2, s96
	v_add_u32_e32 v167, v6, v2
	v_add_co_u32_e32 v2, vcc, s1, v0
	v_add_u32_e32 v7, 0x1a00, v58
	s_nop 0
	v_addc_co_u32_e32 v3, vcc, 0, v1, vcc
	s_mov_b32 s1, 0x1c000
	global_load_dwordx4 v[144:147], v[2:3], off
	v_lshrrev_b32_e32 v2, 5, v7
	v_mul_lo_u32 v2, v2, s96
	v_add_u32_e32 v174, v6, v2
	v_add_co_u32_e32 v2, vcc, s1, v0
	v_add_u32_e32 v7, 0x1c00, v58
	s_nop 0
	v_addc_co_u32_e32 v3, vcc, 0, v1, vcc
	v_add_co_u32_e32 v0, vcc, 0x1e000, v0
	global_load_dwordx4 v[148:151], v[2:3], off
	v_lshrrev_b32_e32 v2, 5, v7
	v_mul_lo_u32 v2, v2, s96
	v_addc_co_u32_e32 v1, vcc, 0, v1, vcc
	v_add_u32_e32 v175, v6, v2
	global_load_dwordx4 v[180:183], v[0:1], off
	v_add_u32_e32 v7, 0x1e00, v58
	v_lshrrev_b32_e32 v7, 5, v7
	v_mul_lo_u32 v7, v7, s96
	v_add_u32_e32 v177, v6, v7
	s_waitcnt vmcnt(15)
	ds_write_b128 v153, v[92:95]
	s_waitcnt vmcnt(14)
	ds_write_b128 v154, v[96:99]
	s_waitcnt vmcnt(13)
	ds_write_b128 v155, v[100:103]
	s_waitcnt vmcnt(12)
	ds_write_b128 v156, v[104:107]
	s_waitcnt vmcnt(11)
	ds_write_b128 v157, v[108:111]
	s_waitcnt vmcnt(10)
	ds_write_b128 v158, v[112:115]
	s_waitcnt vmcnt(9)
	ds_write_b128 v159, v[116:119]
	s_waitcnt vmcnt(8)
	ds_write_b128 v160, v[120:123]
	s_waitcnt vmcnt(7)
	ds_write_b128 v161, v[124:127]
	s_waitcnt vmcnt(6)
	ds_write_b128 v162, v[128:131]
	s_waitcnt vmcnt(5)
	ds_write_b128 v165, v[132:135]
	s_waitcnt vmcnt(4)
	ds_write_b128 v166, v[136:139]
	s_waitcnt vmcnt(3)
	ds_write_b128 v167, v[140:143]
	s_waitcnt vmcnt(2)
	ds_write_b128 v174, v[144:147]
	s_waitcnt vmcnt(1)
	ds_write_b128 v175, v[148:151]
	s_waitcnt vmcnt(0)
	ds_write_b128 v177, v[180:183]
	s_cbranch_scc1 .LBB0_802
	v_mov_b64_e32 v[0:1], s[86:87]
	v_mad_i64_i32 v[0:1], s[0:1], v164, s66, v[0:1]
	v_readlane_b32 s0, v235, 9
	s_lshl_b32 s94, s0, 1
	v_lshl_add_u64 v[0:1], v[0:1], 0, s[94:95]
	v_lshl_add_u64 v[0:1], v[0:1], 0, v[172:173]
	s_mov_b64 s[0:1], 0x1000
	v_lshl_add_u64 v[2:3], v[0:1], 0, s[0:1]
	v_add_co_u32_e32 v0, vcc, 0x1000, v0
	s_nop 1
	v_addc_co_u32_e32 v1, vcc, 0, v1, vcc
	global_load_dwordx4 v[50:53], v[2:3], off offset:64
	global_load_dwordx4 v[46:49], v[2:3], off offset:128
	global_load_dwordx4 v[42:45], v[2:3], off offset:192
	global_load_dwordx4 v[36:39], v[2:3], off offset:256
	global_load_dwordx4 v[32:35], v[2:3], off offset:320
	global_load_dwordx4 v[28:31], v[2:3], off offset:384
	global_load_dwordx4 v[54:57], v[0:1], off
	global_load_dwordx4 v[24:27], v[2:3], off offset:448

.LBB0_809:
	s_and_b64 vcc, exec, s[4:5]
	s_cbranch_vccz .LBB0_820
	s_and_b64 vcc, exec, s[40:41]
	s_cbranch_vccz .LBB0_819
	v_mov_b32_e32 v58, v194
	v_readlane_b32 s4, v235, 10
	v_lshlrev_b32_e32 v0, 4, v58
	v_and_b32_e32 v0, 0x1f0, v0
	v_ashrrev_i32_e32 v59, 31, v58
	v_readlane_b32 s5, v235, 11
	v_add_u32_e32 v6, 0, v0
	s_nop 0
	v_lshl_add_u64 v[0:1], v[58:59], 4, s[4:5]
	s_barrier
	global_load_dwordx4 v[92:95], v[0:1], off
	v_lshrrev_b32_e32 v2, 5, v58
	v_mul_lo_u32 v2, v2, s96
	v_add_u32_e32 v153, v6, v2
	v_add_co_u32_e32 v2, vcc, s92, v0
	v_add_u32_e32 v7, 0x200, v58
	s_nop 0
	v_addc_co_u32_e32 v3, vcc, 0, v1, vcc
	v_and_b32_e32 v4, 15, v58
	v_readlane_b32 s1, v235, 60
	v_readfirstlane_b32 s0, v58
	s_ashr_i32 s0, s0, 2
	v_or_b32_e32 v5, s1, v4
	s_movk_i32 s1, 0x6000
	s_and_b32 s0, s0, -16
	v_bfe_u32 v163, v58, 4, 2
	s_cmpk_lt_i32 s0, 0x80
	s_cselect_b64 s[4:5], -1, 0
	s_cmpk_gt_i32 s0, 0x7f
	v_add_u32_e32 v164, s0, v5
	v_lshlrev_b32_e32 v172, 4, v163
	global_load_dwordx4 v[96:99], v[2:3], off
	v_lshrrev_b32_e32 v2, 5, v7
	v_mul_lo_u32 v2, v2, s96
	v_add_u32_e32 v154, v6, v2
	v_add_co_u32_e32 v2, vcc, s75, v0
	v_add_u32_e32 v7, 0x400, v58
	s_nop 0
	v_addc_co_u32_e32 v3, vcc, 0, v1, vcc
	global_load_dwordx4 v[100:103], v[2:3], off
	v_lshrrev_b32_e32 v2, 5, v7
	v_mul_lo_u32 v2, v2, s96
	v_add_u32_e32 v155, v6, v2
	v_add_co_u32_e32 v2, vcc, s1, v0
	v_add_u32_e32 v7, 0x600, v58
	s_nop 0
	v_addc_co_u32_e32 v3, vcc, 0, v1, vcc
	s_mov_b32 s1, 0x8000
	global_load_dwordx4 v[104:107], v[2:3], off
	v_lshrrev_b32_e32 v2, 5, v7
	v_mul_lo_u32 v2, v2, s96
	v_add_u32_e32 v156, v6, v2
	v_add_co_u32_e32 v2, vcc, s1, v0
	v_add_u32_e32 v7, 0x800, v58
	s_nop 0
	v_addc_co_u32_e32 v3, vcc, 0, v1, vcc
	s_mov_b32 s1, 0xa000
	global_load_dwordx4 v[108:111], v[2:3], off
	v_lshrrev_b32_e32 v2, 5, v7
	v_mul_lo_u32 v2, v2, s96
	v_add_u32_e32 v157, v6, v2
	v_add_co_u32_e32 v2, vcc, s1, v0
	v_add_u32_e32 v7, 0xa00, v58
	s_nop 0
	v_addc_co_u32_e32 v3, vcc, 0, v1, vcc
	s_mov_b32 s1, 0xc000
	global_load_dwordx4 v[112:115], v[2:3], off
	v_lshrrev_b32_e32 v2, 5, v7
	v_mul_lo_u32 v2, v2, s96
	v_add_u32_e32 v158, v6, v2
	v_add_co_u32_e32 v2, vcc, s1, v0
	v_add_u32_e32 v7, 0xc00, v58
	s_nop 0
	v_addc_co_u32_e32 v3, vcc, 0, v1, vcc
	s_mov_b32 s1, 0xe000
	global_load_dwordx4 v[116:119], v[2:3], off
	v_lshrrev_b32_e32 v2, 5, v7
	v_mul_lo_u32 v2, v2, s96
	v_add_u32_e32 v159, v6, v2
	v_add_co_u32_e32 v2, vcc, s1, v0
	v_add_u32_e32 v7, 0xe00, v58
	s_nop 0
	v_addc_co_u32_e32 v3, vcc, 0, v1, vcc
	s_mov_b32 s1, 0x10000
	global_load_dwordx4 v[120:123], v[2:3], off
	v_lshrrev_b32_e32 v2, 5, v7
	v_mul_lo_u32 v2, v2, s96
	v_add_u32_e32 v160, v6, v2
	v_add_co_u32_e32 v2, vcc, s1, v0
	v_add_u32_e32 v7, 0x1000, v58
	s_nop 0
	v_addc_co_u32_e32 v3, vcc, 0, v1, vcc
	s_mov_b32 s1, 0x12000
	global_load_dwordx4 v[124:127], v[2:3], off
	v_lshrrev_b32_e32 v2, 5, v7
	v_mul_lo_u32 v2, v2, s96
	v_add_u32_e32 v161, v6, v2
	v_add_co_u32_e32 v2, vcc, s1, v0
	v_add_u32_e32 v7, 0x1200, v58
	s_nop 0
	v_addc_co_u32_e32 v3, vcc, 0, v1, vcc
	s_mov_b32 s1, 0x14000
	global_load_dwordx4 v[128:131], v[2:3], off
	v_lshrrev_b32_e32 v2, 5, v7
	v_mul_lo_u32 v2, v2, s96
	v_add_u32_e32 v162, v6, v2
	v_add_co_u32_e32 v2, vcc, s1, v0
	v_add_u32_e32 v7, 0x1400, v58
	s_nop 0
	v_addc_co_u32_e32 v3, vcc, 0, v1, vcc
	s_mov_b32 s1, 0x16000
	global_load_dwordx4 v[132:135], v[2:3], off
	v_lshrrev_b32_e32 v2, 5, v7
	v_mul_lo_u32 v2, v2, s96
	v_add_u32_e32 v165, v6, v2
	v_add_co_u32_e32 v2, vcc, s1, v0
	v_add_u32_e32 v7, 0x1600, v58
	s_nop 0
	v_addc_co_u32_e32 v3, vcc, 0, v1, vcc
	s_mov_b32 s1, 0x1a000
	global_load_dwordx4 v[136:139], v[2:3], off
	v_lshrrev_b32_e32 v2, 5, v7
	v_mul_lo_u32 v2, v2, s96
	v_add_u32_e32 v166, v6, v2
	v_add_co_u32_e32 v2, vcc, s97, v0
	v_add_u32_e32 v7, 0x1800, v58
	s_nop 0
	v_addc_co_u32_e32 v3, vcc, 0, v1, vcc
	global_load_dwordx4 v[140:143], v[2:3], off
	v_lshrrev_b32_e32 v2, 5, v7
	v_mul_lo_u32 v2, v2, s96
	v_add_u32_e32 v167, v6, v2
	v_add_co_u32_e32 v2, vcc, s1, v0
	v_add_u32_e32 v7, 0x1a00, v58
	s_nop 0
	v_addc_co_u32_e32 v3, vcc, 0, v1, vcc
	s_mov_b32 s1, 0x1c000
	global_load_dwordx4 v[144:147], v[2:3], off
	v_lshrrev_b32_e32 v2, 5, v7
	v_mul_lo_u32 v2, v2, s96
	v_add_u32_e32 v174, v6, v2
	v_add_co_u32_e32 v2, vcc, s1, v0
	v_add_u32_e32 v7, 0x1c00, v58
	s_nop 0
	v_addc_co_u32_e32 v3, vcc, 0, v1, vcc
	v_add_co_u32_e32 v0, vcc, 0x1e000, v0
	global_load_dwordx4 v[148:151], v[2:3], off
	v_lshrrev_b32_e32 v2, 5, v7
	v_mul_lo_u32 v2, v2, s96
	v_addc_co_u32_e32 v1, vcc, 0, v1, vcc
	v_add_u32_e32 v175, v6, v2
	global_load_dwordx4 v[180:183], v[0:1], off
	v_add_u32_e32 v7, 0x1e00, v58
	v_lshrrev_b32_e32 v7, 5, v7
	v_mul_lo_u32 v7, v7, s96
	v_add_u32_e32 v177, v6, v7
	s_waitcnt vmcnt(15)
	ds_write_b128 v153, v[92:95]
	s_waitcnt vmcnt(14)
	ds_write_b128 v154, v[96:99]
	s_waitcnt vmcnt(13)
	ds_write_b128 v155, v[100:103]
	s_waitcnt vmcnt(12)
	ds_write_b128 v156, v[104:107]
	s_waitcnt vmcnt(11)
	ds_write_b128 v157, v[108:111]
	s_waitcnt vmcnt(10)
	ds_write_b128 v158, v[112:115]
	s_waitcnt vmcnt(9)
	ds_write_b128 v159, v[116:119]
	s_waitcnt vmcnt(8)
	ds_write_b128 v160, v[120:123]
	s_waitcnt vmcnt(7)
	ds_write_b128 v161, v[124:127]
	s_waitcnt vmcnt(6)
	ds_write_b128 v162, v[128:131]
	s_waitcnt vmcnt(5)
	ds_write_b128 v165, v[132:135]
	s_waitcnt vmcnt(4)
	ds_write_b128 v166, v[136:139]
	s_waitcnt vmcnt(3)
	ds_write_b128 v167, v[140:143]
	s_waitcnt vmcnt(2)
	ds_write_b128 v174, v[144:147]
	s_waitcnt vmcnt(1)
	ds_write_b128 v175, v[148:151]
	s_waitcnt vmcnt(0)
	ds_write_b128 v177, v[180:183]
	s_cbranch_scc1 .LBB0_813
	v_mov_b64_e32 v[0:1], s[86:87]
	v_mad_i64_i32 v[0:1], s[0:1], v164, s66, v[0:1]
	v_readlane_b32 s0, v235, 9
	s_lshl_b32 s94, s0, 1
	v_lshl_add_u64 v[0:1], v[0:1], 0, s[94:95]
	v_lshl_add_u64 v[0:1], v[0:1], 0, v[172:173]
	s_mov_b64 s[0:1], 0x1000
	v_lshl_add_u64 v[2:3], v[0:1], 0, s[0:1]
	v_add_co_u32_e32 v0, vcc, 0x1000, v0
	s_nop 1
	v_addc_co_u32_e32 v1, vcc, 0, v1, vcc
	global_load_dwordx4 v[50:53], v[2:3], off offset:64
	global_load_dwordx4 v[46:49], v[2:3], off offset:128
	global_load_dwordx4 v[42:45], v[2:3], off offset:192
	global_load_dwordx4 v[36:39], v[2:3], off offset:256
	global_load_dwordx4 v[32:35], v[2:3], off offset:320
	global_load_dwordx4 v[28:31], v[2:3], off offset:384
	global_load_dwordx4 v[54:57], v[0:1], off
	global_load_dwordx4 v[24:27], v[2:3], off offset:448

.LBB0_836:
	s_add_u32 s25, s34, 0xc002100
	s_addc_u32 s26, s35, 0
	s_add_i32 s27, 0, 0x10000
	v_add_u32_e32 v112, s27, v203
	ds_read_b128 v[92:95], v112
	ds_read_b128 v[100:103], v112 offset:1024
	ds_read_b128 v[104:107], v112 offset:2048
	ds_read_b128 v[112:115], v112 offset:3072
	s_cmp_eq_u32 s24, 12
	s_cselect_b32 s69, s73, s26
	s_cselect_b32 s68, s72, s25
	s_cselect_b32 s49, s9, s23
	s_cselect_b32 s48, s8, s5
	v_lshl_add_u64 v[192:193], s[34:35], 0, v[180:181]
	s_add_i32 m0, s18, 0xc000
	ds_read_b128 v[124:127], v204
	ds_read_b128 v[136:139], v204 offset:1024
	ds_read_b128 v[144:147], v204 offset:2048
	ds_read_b128 v[156:159], v204 offset:3072
	ds_read_b128 v[160:163], v204 offset:4096
	ds_read_b128 v[164:167], v204 offset:5120
	ds_read_b128 v[184:187], v204 offset:6144
	ds_read_b128 v[188:191], v204 offset:7168
	global_load_lds_dwordx4 v[192:193], off
	v_lshl_add_u64 v[192:193], s[34:35], 0, v[182:183]
	s_add_i32 m0, s18, 0xe000
	s_nop 0
	global_load_lds_dwordx4 v[192:193], off
	s_waitcnt lgkmcnt(8)
	s_barrier
	s_waitcnt lgkmcnt(0)
	s_setprio 1
	s_waitcnt lgkmcnt(0)
	v_mfma_f32_16x16x32_bf16 v[152:155], v[92:95], v[124:127], v[152:155]
	v_mfma_f32_16x16x32_bf16 v[148:151], v[104:107], v[124:127], v[148:151]
	v_mfma_f32_16x16x32_bf16 v[140:143], v[92:95], v[144:147], v[140:143]
	v_mfma_f32_16x16x32_bf16 v[132:135], v[104:107], v[144:147], v[132:135]
	v_mfma_f32_16x16x32_bf16 v[128:131], v[92:95], v[160:163], v[128:131]
	v_mfma_f32_16x16x32_bf16 v[120:123], v[104:107], v[160:163], v[120:123]
	v_mfma_f32_16x16x32_bf16 v[116:119], v[92:95], v[184:187], v[116:119]
	v_mfma_f32_16x16x32_bf16 v[108:111], v[104:107], v[184:187], v[108:111]
	v_mfma_f32_16x16x32_bf16 v[152:155], v[100:103], v[136:139], v[152:155]
	v_mfma_f32_16x16x32_bf16 v[148:151], v[112:115], v[136:139], v[148:151]
	v_mfma_f32_16x16x32_bf16 v[140:143], v[100:103], v[156:159], v[140:143]
	v_mfma_f32_16x16x32_bf16 v[132:135], v[112:115], v[156:159], v[132:135]
	v_mfma_f32_16x16x32_bf16 v[128:131], v[100:103], v[164:167], v[128:131]
	v_mfma_f32_16x16x32_bf16 v[120:123], v[112:115], v[164:167], v[120:123]
	v_mfma_f32_16x16x32_bf16 v[116:119], v[100:103], v[188:191], v[116:119]
	v_mfma_f32_16x16x32_bf16 v[108:111], v[112:115], v[188:191], v[108:111]
	s_setprio 0
	s_barrier
	s_add_i32 s25, 0, 0x14000
	v_add_u32_e32 v192, s25, v203
	s_add_i32 s26, s27, s17
	ds_read_b128 v[206:209], v192
	ds_read_b128 v[210:213], v192 offset:1024
	ds_read_b128 v[214:217], v192 offset:2048
	ds_read_b128 v[218:221], v192 offset:3072
	v_lshl_add_u64 v[192:193], s[48:49], 0, v[172:173]
	s_mov_b32 m0, s26
	v_lshl_add_u64 v[222:223], s[48:49], 0, v[174:175]
	global_load_lds_dwordx4 v[192:193], off
	s_add_i32 m0, s26, 0x2000
	s_nop 0
	global_load_lds_dwordx4 v[222:223], off
	s_barrier
	s_waitcnt lgkmcnt(0)
	s_setprio 1
	s_waitcnt lgkmcnt(0)
	v_mfma_f32_16x16x32_bf16 v[60:63], v[206:209], v[124:127], v[60:63]
	v_mfma_f32_16x16x32_bf16 v[56:59], v[214:217], v[124:127], v[56:59]
	v_mfma_f32_16x16x32_bf16 v[52:55], v[206:209], v[144:147], v[52:55]
	v_mfma_f32_16x16x32_bf16 v[48:51], v[214:217], v[144:147], v[48:51]
	v_mfma_f32_16x16x32_bf16 v[44:47], v[206:209], v[160:163], v[44:47]
	v_mfma_f32_16x16x32_bf16 v[40:43], v[214:217], v[160:163], v[40:43]
	v_mfma_f32_16x16x32_bf16 v[36:39], v[206:209], v[184:187], v[36:39]
	v_mfma_f32_16x16x32_bf16 v[32:35], v[214:217], v[184:187], v[32:35]
	v_mfma_f32_16x16x32_bf16 v[60:63], v[210:213], v[136:139], v[60:63]
	v_mfma_f32_16x16x32_bf16 v[56:59], v[218:221], v[136:139], v[56:59]
	v_mfma_f32_16x16x32_bf16 v[52:55], v[210:213], v[156:159], v[52:55]
	v_mfma_f32_16x16x32_bf16 v[48:51], v[218:221], v[156:159], v[48:51]
	v_mfma_f32_16x16x32_bf16 v[44:47], v[210:213], v[164:167], v[44:47]
	v_mfma_f32_16x16x32_bf16 v[40:43], v[218:221], v[164:167], v[40:43]
	v_mfma_f32_16x16x32_bf16 v[36:39], v[210:213], v[188:191], v[36:39]
	v_mfma_f32_16x16x32_bf16 v[32:35], v[218:221], v[188:191], v[32:35]
	s_setprio 0
	s_mov_b32 m0, s18
	v_lshl_add_u64 v[224:225], s[68:69], 0, v[178:179]
	s_barrier
	ds_read_b128 v[124:127], v204 offset:16384
	ds_read_b128 v[136:139], v204 offset:17408
	ds_read_b128 v[144:147], v204 offset:18432
	ds_read_b128 v[156:159], v204 offset:19456
	ds_read_b128 v[160:163], v204 offset:20480
	ds_read_b128 v[164:167], v204 offset:21504
	ds_read_b128 v[184:187], v204 offset:22528
	ds_read_b128 v[188:191], v204 offset:23552
	global_load_lds_dwordx4 v[224:225], off
	v_lshl_add_u64 v[226:227], s[68:69], 0, v[176:177]
	s_mov_b32 m0, s19
	s_nop 0
	global_load_lds_dwordx4 v[226:227], off
	s_barrier
	s_waitcnt lgkmcnt(0)
	s_setprio 1
	s_waitcnt lgkmcnt(0)
	v_mfma_f32_16x16x32_bf16 v[96:99], v[92:95], v[124:127], v[96:99]
	v_mfma_f32_16x16x32_bf16 v[88:91], v[104:107], v[124:127], v[88:91]
	v_mfma_f32_16x16x32_bf16 v[84:87], v[92:95], v[144:147], v[84:87]
	v_mfma_f32_16x16x32_bf16 v[80:83], v[104:107], v[144:147], v[80:83]
	v_mfma_f32_16x16x32_bf16 v[76:79], v[92:95], v[160:163], v[76:79]
	v_mfma_f32_16x16x32_bf16 v[72:75], v[104:107], v[160:163], v[72:75]
	v_mfma_f32_16x16x32_bf16 v[68:71], v[92:95], v[184:187], v[68:71]
	v_mfma_f32_16x16x32_bf16 v[64:67], v[104:107], v[184:187], v[64:67]
	v_mfma_f32_16x16x32_bf16 v[96:99], v[100:103], v[136:139], v[96:99]
	v_mfma_f32_16x16x32_bf16 v[88:91], v[112:115], v[136:139], v[88:91]
	v_mfma_f32_16x16x32_bf16 v[84:87], v[100:103], v[156:159], v[84:87]
	v_mfma_f32_16x16x32_bf16 v[80:83], v[112:115], v[156:159], v[80:83]
	v_mfma_f32_16x16x32_bf16 v[76:79], v[100:103], v[164:167], v[76:79]
	v_mfma_f32_16x16x32_bf16 v[72:75], v[112:115], v[164:167], v[72:75]
	v_mfma_f32_16x16x32_bf16 v[68:71], v[100:103], v[188:191], v[68:71]
	v_mfma_f32_16x16x32_bf16 v[64:67], v[112:115], v[188:191], v[64:67]
	s_setprio 0
	s_barrier
	s_add_u32 s26, s48, 0x40000
	s_addc_u32 s27, s49, 0
	s_add_i32 s25, s25, s17
	v_lshl_add_u64 v[92:93], s[26:27], 0, v[172:173]
	s_mov_b32 m0, s25
	s_nop 0
	global_load_lds_dwordx4 v[92:93], off
	v_lshl_add_u64 v[92:93], s[26:27], 0, v[174:175]
	s_add_i32 m0, s25, 0x2000
	s_nop 0
	global_load_lds_dwordx4 v[92:93], off
	s_waitcnt vmcnt(6)
	s_barrier
	s_setprio 1
	v_mfma_f32_16x16x32_bf16 v[28:31], v[206:209], v[124:127], v[28:31]
	v_mfma_f32_16x16x32_bf16 v[24:27], v[214:217], v[124:127], v[24:27]
	v_mfma_f32_16x16x32_bf16 v[20:23], v[206:209], v[144:147], v[20:23]
	v_mfma_f32_16x16x32_bf16 v[16:19], v[214:217], v[144:147], v[16:19]
	v_mfma_f32_16x16x32_bf16 v[12:15], v[206:209], v[160:163], v[12:15]
	v_mfma_f32_16x16x32_bf16 v[8:11], v[214:217], v[160:163], v[8:11]
	v_mfma_f32_16x16x32_bf16 v[4:7], v[206:209], v[184:187], v[4:7]
	v_mfma_f32_16x16x32_bf16 v[0:3], v[214:217], v[184:187], v[0:3]
	v_mfma_f32_16x16x32_bf16 v[28:31], v[210:213], v[136:139], v[28:31]
	v_mfma_f32_16x16x32_bf16 v[24:27], v[218:221], v[136:139], v[24:27]
	v_mfma_f32_16x16x32_bf16 v[20:23], v[210:213], v[156:159], v[20:23]
	v_mfma_f32_16x16x32_bf16 v[16:19], v[218:221], v[156:159], v[16:19]
	v_mfma_f32_16x16x32_bf16 v[12:15], v[210:213], v[164:167], v[12:15]
	v_mfma_f32_16x16x32_bf16 v[8:11], v[218:221], v[164:167], v[8:11]
	v_mfma_f32_16x16x32_bf16 v[4:7], v[210:213], v[188:191], v[4:7]
	v_mfma_f32_16x16x32_bf16 v[0:3], v[218:221], v[188:191], v[0:3]
	s_setprio 0
	s_add_i32 s25, 0, 0x18000
	v_add_u32_e32 v112, s25, v203
	s_barrier
	ds_read_b128 v[92:95], v112
	ds_read_b128 v[100:103], v112 offset:1024
	ds_read_b128 v[104:107], v112 offset:2048
	ds_read_b128 v[112:115], v112 offset:3072
	s_add_u32 s26, s68, 0x180000
	s_addc_u32 s27, s69, 0
	s_mov_b32 m0, s20
	v_lshl_add_u64 v[206:207], s[26:27], 0, v[178:179]
	ds_read_b128 v[124:127], v204 offset:32768
	ds_read_b128 v[136:139], v204 offset:33792
	ds_read_b128 v[144:147], v204 offset:34816
	ds_read_b128 v[156:159], v204 offset:35840
	ds_read_b128 v[160:163], v204 offset:36864
	ds_read_b128 v[164:167], v204 offset:37888
	ds_read_b128 v[184:187], v204 offset:38912
	ds_read_b128 v[188:191], v204 offset:39936
	global_load_lds_dwordx4 v[206:207], off
	v_lshl_add_u64 v[206:207], s[26:27], 0, v[176:177]
	s_mov_b32 m0, s21
	s_nop 0
	global_load_lds_dwordx4 v[206:207], off
	s_waitcnt lgkmcnt(8)
	s_barrier
	s_waitcnt lgkmcnt(0)
	s_setprio 1
	s_waitcnt lgkmcnt(0)
	v_mfma_f32_16x16x32_bf16 v[152:155], v[92:95], v[124:127], v[152:155]
	v_mfma_f32_16x16x32_bf16 v[148:151], v[104:107], v[124:127], v[148:151]
	v_mfma_f32_16x16x32_bf16 v[140:143], v[92:95], v[144:147], v[140:143]
	v_mfma_f32_16x16x32_bf16 v[132:135], v[104:107], v[144:147], v[132:135]
	v_mfma_f32_16x16x32_bf16 v[128:131], v[92:95], v[160:163], v[128:131]
	v_mfma_f32_16x16x32_bf16 v[120:123], v[104:107], v[160:163], v[120:123]
	v_mfma_f32_16x16x32_bf16 v[116:119], v[92:95], v[184:187], v[116:119]
	v_mfma_f32_16x16x32_bf16 v[108:111], v[104:107], v[184:187], v[108:111]
	v_mfma_f32_16x16x32_bf16 v[152:155], v[100:103], v[136:139], v[152:155]
	v_mfma_f32_16x16x32_bf16 v[148:151], v[112:115], v[136:139], v[148:151]
	v_mfma_f32_16x16x32_bf16 v[140:143], v[100:103], v[156:159], v[140:143]
	v_mfma_f32_16x16x32_bf16 v[132:135], v[112:115], v[156:159], v[132:135]
	v_mfma_f32_16x16x32_bf16 v[128:131], v[100:103], v[164:167], v[128:131]
	v_mfma_f32_16x16x32_bf16 v[120:123], v[112:115], v[164:167], v[120:123]
	v_mfma_f32_16x16x32_bf16 v[116:119], v[100:103], v[188:191], v[116:119]
	v_mfma_f32_16x16x32_bf16 v[108:111], v[112:115], v[188:191], v[108:111]
	s_setprio 0
	s_barrier
	s_add_i32 s68, 0, 0x1c000
	s_add_i32 s25, s25, s17
	v_add_u32_e32 v205, s68, v203
	v_lshl_add_u64 v[192:193], v[192:193], 0, s[76:77]
	s_mov_b32 m0, s25
	ds_read_b128 v[206:209], v205
	ds_read_b128 v[210:213], v205 offset:1024
	ds_read_b128 v[214:217], v205 offset:2048
	ds_read_b128 v[218:221], v205 offset:3072
	global_load_lds_dwordx4 v[192:193], off
	v_lshl_add_u64 v[192:193], v[222:223], 0, s[76:77]
	s_add_i32 m0, s25, 0x2000
	s_nop 0
	global_load_lds_dwordx4 v[192:193], off
	s_barrier
	s_waitcnt lgkmcnt(0)
	s_setprio 1
	s_waitcnt lgkmcnt(0)
	v_mfma_f32_16x16x32_bf16 v[60:63], v[206:209], v[124:127], v[60:63]
	v_mfma_f32_16x16x32_bf16 v[56:59], v[214:217], v[124:127], v[56:59]
	v_mfma_f32_16x16x32_bf16 v[52:55], v[206:209], v[144:147], v[52:55]
	v_mfma_f32_16x16x32_bf16 v[48:51], v[214:217], v[144:147], v[48:51]
	v_mfma_f32_16x16x32_bf16 v[44:47], v[206:209], v[160:163], v[44:47]
	v_mfma_f32_16x16x32_bf16 v[40:43], v[214:217], v[160:163], v[40:43]
	v_mfma_f32_16x16x32_bf16 v[36:39], v[206:209], v[184:187], v[36:39]
	v_mfma_f32_16x16x32_bf16 v[32:35], v[214:217], v[184:187], v[32:35]
	v_mfma_f32_16x16x32_bf16 v[60:63], v[210:213], v[136:139], v[60:63]
	v_mfma_f32_16x16x32_bf16 v[56:59], v[218:221], v[136:139], v[56:59]
	v_mfma_f32_16x16x32_bf16 v[52:55], v[210:213], v[156:159], v[52:55]
	v_mfma_f32_16x16x32_bf16 v[48:51], v[218:221], v[156:159], v[48:51]
	v_mfma_f32_16x16x32_bf16 v[44:47], v[210:213], v[164:167], v[44:47]
	v_mfma_f32_16x16x32_bf16 v[40:43], v[218:221], v[164:167], v[40:43]
	v_mfma_f32_16x16x32_bf16 v[36:39], v[210:213], v[188:191], v[36:39]
	v_mfma_f32_16x16x32_bf16 v[32:35], v[218:221], v[188:191], v[32:35]
	s_setprio 0
	s_mov_b32 m0, s61
	v_lshl_add_u64 v[192:193], v[224:225], 0, s[76:77]
	s_barrier
	ds_read_b128 v[124:127], v204 offset:49152
	ds_read_b128 v[136:139], v204 offset:50176
	ds_read_b128 v[144:147], v204 offset:51200
	ds_read_b128 v[156:159], v204 offset:52224
	ds_read_b128 v[160:163], v204 offset:53248
	ds_read_b128 v[164:167], v204 offset:54272
	ds_read_b128 v[184:187], v204 offset:55296
	ds_read_b128 v[188:191], v204 offset:56320
	global_load_lds_dwordx4 v[192:193], off
	v_lshl_add_u64 v[192:193], v[226:227], 0, s[76:77]
	s_mov_b32 m0, s62
	s_nop 0
	global_load_lds_dwordx4 v[192:193], off
	s_barrier
	s_waitcnt lgkmcnt(0)
	s_setprio 1
	s_waitcnt lgkmcnt(0)
	v_mfma_f32_16x16x32_bf16 v[96:99], v[92:95], v[124:127], v[96:99]
	v_mfma_f32_16x16x32_bf16 v[88:91], v[104:107], v[124:127], v[88:91]
	v_mfma_f32_16x16x32_bf16 v[84:87], v[92:95], v[144:147], v[84:87]
	v_mfma_f32_16x16x32_bf16 v[80:83], v[104:107], v[144:147], v[80:83]
	v_mfma_f32_16x16x32_bf16 v[76:79], v[92:95], v[160:163], v[76:79]
	v_mfma_f32_16x16x32_bf16 v[72:75], v[104:107], v[160:163], v[72:75]
	v_mfma_f32_16x16x32_bf16 v[68:71], v[92:95], v[184:187], v[68:71]
	v_mfma_f32_16x16x32_bf16 v[64:67], v[104:107], v[184:187], v[64:67]
	v_mfma_f32_16x16x32_bf16 v[96:99], v[100:103], v[136:139], v[96:99]
	v_mfma_f32_16x16x32_bf16 v[88:91], v[112:115], v[136:139], v[88:91]
	v_mfma_f32_16x16x32_bf16 v[84:87], v[100:103], v[156:159], v[84:87]
	v_mfma_f32_16x16x32_bf16 v[80:83], v[112:115], v[156:159], v[80:83]
	v_mfma_f32_16x16x32_bf16 v[76:79], v[100:103], v[164:167], v[76:79]
	v_mfma_f32_16x16x32_bf16 v[72:75], v[112:115], v[164:167], v[72:75]
	v_mfma_f32_16x16x32_bf16 v[68:71], v[100:103], v[188:191], v[68:71]
	v_mfma_f32_16x16x32_bf16 v[64:67], v[112:115], v[188:191], v[64:67]
	s_setprio 0
	s_barrier
	s_add_u32 s26, s48, 0x40080
	s_addc_u32 s27, s49, 0
	s_add_i32 s25, s68, s17
	v_lshl_add_u64 v[92:93], s[26:27], 0, v[172:173]
	s_mov_b32 m0, s25
	s_nop 0
	global_load_lds_dwordx4 v[92:93], off
	v_lshl_add_u64 v[92:93], s[26:27], 0, v[174:175]
	s_add_i32 m0, s25, 0x2000
	s_nop 0
	global_load_lds_dwordx4 v[92:93], off
	s_waitcnt vmcnt(6)
	s_barrier
	s_setprio 1
	v_mfma_f32_16x16x32_bf16 v[28:31], v[206:209], v[124:127], v[28:31]
	v_mfma_f32_16x16x32_bf16 v[24:27], v[214:217], v[124:127], v[24:27]
	v_mfma_f32_16x16x32_bf16 v[20:23], v[206:209], v[144:147], v[20:23]
	v_mfma_f32_16x16x32_bf16 v[16:19], v[214:217], v[144:147], v[16:19]
	v_mfma_f32_16x16x32_bf16 v[12:15], v[206:209], v[160:163], v[12:15]
	v_mfma_f32_16x16x32_bf16 v[8:11], v[214:217], v[160:163], v[8:11]
	v_mfma_f32_16x16x32_bf16 v[4:7], v[206:209], v[184:187], v[4:7]
	v_mfma_f32_16x16x32_bf16 v[0:3], v[214:217], v[184:187], v[0:3]
	v_mfma_f32_16x16x32_bf16 v[28:31], v[210:213], v[136:139], v[28:31]
	v_mfma_f32_16x16x32_bf16 v[24:27], v[218:221], v[136:139], v[24:27]
	v_mfma_f32_16x16x32_bf16 v[20:23], v[210:213], v[156:159], v[20:23]
	v_mfma_f32_16x16x32_bf16 v[16:19], v[218:221], v[156:159], v[16:19]
	v_mfma_f32_16x16x32_bf16 v[12:15], v[210:213], v[164:167], v[12:15]
	v_mfma_f32_16x16x32_bf16 v[8:11], v[218:221], v[164:167], v[8:11]
	v_mfma_f32_16x16x32_bf16 v[4:7], v[210:213], v[188:191], v[4:7]
	v_mfma_f32_16x16x32_bf16 v[0:3], v[218:221], v[188:191], v[0:3]
	s_setprio 0
	s_add_i32 s24, s24, 2
	s_add_u32 s34, s34, 0x100
	s_addc_u32 s35, s35, 0
	s_add_u32 s5, s5, 0x100
	s_addc_u32 s23, s23, 0
	s_cmp_gt_u32 s24, 13
	s_barrier
	s_cbranch_scc0 .LBB0_836
	s_lshl_b32 s5, s22, 8
	v_mov_b32_e32 v92, v201
	v_mov_b32_e32 v93, v202
	s_or_b32 s5, s5, s60
	v_mov_b64_e32 v[190:191], s[86:87]
	v_lshl_add_u32 v186, v93, 3, s5
	v_ashrrev_i32_e32 v187, 31, v186
	v_lshl_add_u64 v[184:185], v[186:187], 2, s[0:1]
	v_add_u32_e32 v205, s63, v92
	global_load_dwordx4 v[92:95], v[184:185], off offset:16
	global_load_dwordx4 v[104:107], v[184:185], off
	v_lshlrev_b64 v[188:189], 1, v[186:187]
	v_lshl_add_u64 v[100:101], s[86:87], 0, v[188:189]
	v_mad_i64_i32 v[102:103], s[22:23], v205, s66, v[100:101]
	global_load_dwordx4 v[164:167], v[102:103], off offset:2048
	v_add_u32_e32 v210, 16, v205
	v_mad_i64_i32 v[102:103], s[22:23], v210, s66, v[100:101]
	global_load_dwordx4 v[160:163], v[102:103], off offset:2048
	v_add_u32_e32 v211, 32, v205
	v_mad_i64_i32 v[102:103], s[22:23], v211, s66, v[100:101]
	global_load_dwordx4 v[156:159], v[102:103], off offset:2048
	v_add_u32_e32 v209, 48, v205
	v_mad_i64_i32 v[102:103], s[22:23], v209, s66, v[100:101]
	global_load_dwordx4 v[144:147], v[102:103], off offset:2048
	v_mad_i64_i32 v[192:193], s[22:23], v205, s66, v[190:191]
	v_add_u32_e32 v208, 0x80, v205
	v_mad_i64_i32 v[102:103], s[22:23], v208, s66, v[100:101]
	global_load_dwordx4 v[136:139], v[102:103], off offset:2048
	v_add_u32_e32 v207, 0x90, v205
	v_mad_i64_i32 v[102:103], s[22:23], v207, s66, v[100:101]
	global_load_dwordx4 v[124:127], v[102:103], off offset:2048
	v_add_u32_e32 v206, 0xa0, v205
	v_mad_i64_i32 v[102:103], s[22:23], v206, s66, v[100:101]
	global_load_dwordx4 v[112:115], v[102:103], off offset:2048
	v_add_u32_e32 v187, 0xb0, v205
	v_mad_i64_i32 v[100:101], s[22:23], v187, s66, v[100:101]
	global_load_dwordx4 v[100:103], v[100:101], off offset:2048
	v_add_u32_e32 v246, 0x80, v186
	v_ashrrev_i32_e32 v247, 31, v246
	v_lshl_add_u64 v[246:247], v[246:247], 1, s[86:87]
	v_mad_i64_i32 v[248:249], s[22:23], v205, s66, v[246:247]
	global_load_dwordx4 v[214:217], v[248:249], off offset:2048
	v_mad_i64_i32 v[248:249], s[22:23], v210, s66, v[246:247]
	global_load_dwordx4 v[218:221], v[248:249], off offset:2048
	v_mad_i64_i32 v[248:249], s[22:23], v211, s66, v[246:247]
	global_load_dwordx4 v[222:225], v[248:249], off offset:2048
	v_mad_i64_i32 v[248:249], s[22:23], v209, s66, v[246:247]
	global_load_dwordx4 v[226:229], v[248:249], off offset:2048
	v_mad_i64_i32 v[248:249], s[22:23], v208, s66, v[246:247]
	global_load_dwordx4 v[230:233], v[248:249], off offset:2048
	v_mad_i64_i32 v[248:249], s[22:23], v207, s66, v[246:247]
	global_load_dwordx4 v[238:241], v[248:249], off offset:2048
	v_mad_i64_i32 v[248:249], s[22:23], v206, s66, v[246:247]
	global_load_dwordx4 v[242:245], v[248:249], off offset:2048
	v_mad_i64_i32 v[248:249], s[22:23], v187, s66, v[246:247]
	global_load_dwordx4 v[250:253], v[248:249], off offset:2048
	s_nop 0
	s_nop 0
	s_nop 0
	s_nop 0
	s_nop 0
	s_nop 0
	s_nop 0
	s_nop 0
	s_nop 0
	s_nop 0
	s_nop 0
	s_nop 0
	s_nop 0
	s_nop 0
	s_nop 0
	s_nop 0
	s_nop 0
	s_nop 0
	s_nop 0
	s_nop 0
	s_nop 0
	s_nop 0
	s_nop 0
	s_nop 0
	s_nop 0
	s_nop 0
	s_nop 0
	s_and_b64 vcc, exec, s[46:47]
	s_mov_b64 s[34:35], s[8:9]
	s_waitcnt vmcnt(0)
	v_add_f32_e32 v148, v148, v92
	v_add_f32_e32 v153, v153, v105
	v_mul_f32_e32 v153, 0xbfb8aa3b, v153
	v_add_f32_e32 v154, v154, v106
	v_exp_f32_e32 v153, v153
	v_mul_f32_e32 v154, 0xbfb8aa3b, v154
	v_add_f32_e32 v155, v155, v107
	v_exp_f32_e32 v154, v154
	v_mul_f32_e32 v155, 0xbfb8aa3b, v155
	v_exp_f32_e32 v155, v155
	v_mul_f32_e32 v148, 0xbfb8aa3b, v148
	v_add_f32_e32 v149, v149, v93
	v_exp_f32_e32 v148, v148
	v_mul_f32_e32 v149, 0xbfb8aa3b, v149
	v_add_f32_e32 v153, 1.0, v153
	v_exp_f32_e32 v149, v149
	v_rcp_f32_e32 v153, v153
	v_add_f32_e32 v154, 1.0, v154
	v_rcp_f32_e32 v154, v154
	v_add_f32_e32 v155, 1.0, v155
	v_rcp_f32_e32 v155, v155
	v_add_f32_e32 v148, 1.0, v148
	v_lshlrev_b32_e32 v212, 16, v164
	v_and_b32_e32 v164, 0xffff0000, v164
	v_rcp_f32_e32 v148, v148
	v_add_f32_e32 v149, 1.0, v149
	v_mul_f32_e32 v153, v153, v164
	v_lshlrev_b32_e32 v164, 16, v165
	v_rcp_f32_e32 v149, v149
	v_mul_f32_e32 v154, v154, v164
	v_and_b32_e32 v164, 0xffff0000, v165
	v_mul_f32_e32 v155, v155, v164
	v_lshlrev_b32_e32 v164, 16, v166
	v_mul_f32_e32 v164, v148, v164
	v_and_b32_e32 v148, 0xffff0000, v166
	v_mul_f32_e32 v165, v149, v148
	v_add_f32_e32 v149, v150, v94
	v_mul_f32_e32 v149, 0xbfb8aa3b, v149
	v_exp_f32_e32 v149, v149
	v_add_f32_e32 v152, v152, v104
	v_lshlrev_b32_e32 v148, 16, v167
	v_mul_f32_e32 v152, 0xbfb8aa3b, v152
	v_add_f32_e32 v149, 1.0, v149
	v_rcp_f32_e32 v149, v149
	v_exp_f32_e32 v152, v152
	v_add_f32_e32 v140, v140, v104
	v_mul_f32_e32 v140, 0xbfb8aa3b, v140
	v_mul_f32_e32 v166, v149, v148
	v_add_f32_e32 v149, v151, v95
	v_mul_f32_e32 v149, 0xbfb8aa3b, v149
	v_exp_f32_e32 v149, v149
	v_add_f32_e32 v141, v141, v105
	v_exp_f32_e32 v140, v140
	v_mul_f32_e32 v141, 0xbfb8aa3b, v141
	v_add_f32_e32 v142, v142, v106
	v_add_f32_e32 v152, 1.0, v152
	v_exp_f32_e32 v141, v141
	v_mul_f32_e32 v142, 0xbfb8aa3b, v142
	v_add_f32_e32 v143, v143, v107
	v_rcp_f32_e32 v152, v152
	v_add_f32_e32 v149, 1.0, v149
	v_exp_f32_e32 v142, v142
	v_mul_f32_e32 v143, 0xbfb8aa3b, v143
	v_add_f32_e32 v132, v132, v92
	v_rcp_f32_e32 v149, v149
	v_exp_f32_e32 v143, v143
	v_mul_f32_e32 v132, 0xbfb8aa3b, v132
	v_add_f32_e32 v133, v133, v93
	v_add_f32_e32 v140, 1.0, v140
	v_exp_f32_e32 v132, v132
	v_mul_f32_e32 v133, 0xbfb8aa3b, v133
	v_rcp_f32_e32 v140, v140
	v_add_f32_e32 v141, 1.0, v141
	v_exp_f32_e32 v133, v133
	v_mul_f32_e32 v152, v152, v212
	v_and_b32_e32 v148, 0xffff0000, v167
	v_rcp_f32_e32 v141, v141
	v_add_f32_e32 v142, 1.0, v142
	v_mul_f32_e32 v167, v149, v148
	v_lshl_add_u64 v[148:149], v[192:193], 0, v[188:189]
	v_cvt_pk_bf16_f32 v150, v152, v153
	v_cvt_pk_bf16_f32 v152, v164, v165
	v_rcp_f32_e32 v142, v142
	v_add_f32_e32 v143, 1.0, v143
	v_cvt_pk_bf16_f32 v151, v154, v155
	v_cvt_pk_bf16_f32 v153, v166, v167
	global_store_dwordx4 v[148:149], v[150:153], off offset:2048
	v_rcp_f32_e32 v143, v143
	v_add_f32_e32 v132, 1.0, v132
	v_lshlrev_b32_e32 v152, 16, v160
	v_mul_f32_e32 v140, v140, v152
	v_and_b32_e32 v152, 0xffff0000, v160
	v_rcp_f32_e32 v132, v132
	v_add_f32_e32 v133, 1.0, v133
	v_mul_f32_e32 v141, v141, v152
	v_lshlrev_b32_e32 v152, 16, v161
	v_rcp_f32_e32 v133, v133
	v_mul_f32_e32 v142, v142, v152
	v_and_b32_e32 v152, 0xffff0000, v161
	v_mul_f32_e32 v143, v143, v152
	v_lshlrev_b32_e32 v152, 16, v162
	v_mul_f32_e32 v152, v132, v152
	v_and_b32_e32 v132, 0xffff0000, v162
	v_mul_f32_e32 v153, v133, v132
	v_add_f32_e32 v133, v134, v94
	v_mul_f32_e32 v133, 0xbfb8aa3b, v133
	v_exp_f32_e32 v133, v133
	v_lshlrev_b32_e32 v132, 16, v163
	v_add_f32_e32 v128, v128, v104
	v_mul_f32_e32 v128, 0xbfb8aa3b, v128
	v_add_f32_e32 v133, 1.0, v133
	v_rcp_f32_e32 v133, v133
	v_add_f32_e32 v129, v129, v105
	v_exp_f32_e32 v128, v128
	v_mul_f32_e32 v129, 0xbfb8aa3b, v129
	v_mul_f32_e32 v134, v133, v132
	v_add_f32_e32 v133, v135, v95
	v_mul_f32_e32 v133, 0xbfb8aa3b, v133
	v_exp_f32_e32 v133, v133
	v_add_f32_e32 v130, v130, v106
	v_exp_f32_e32 v129, v129
	v_mul_f32_e32 v130, 0xbfb8aa3b, v130
	v_add_f32_e32 v131, v131, v107
	v_add_f32_e32 v133, 1.0, v133
	v_exp_f32_e32 v130, v130
	v_mul_f32_e32 v131, 0xbfb8aa3b, v131
	v_add_f32_e32 v120, v120, v92
	v_rcp_f32_e32 v133, v133
	v_exp_f32_e32 v131, v131
	v_mul_f32_e32 v120, 0xbfb8aa3b, v120
	v_add_f32_e32 v121, v121, v93
	v_add_f32_e32 v128, 1.0, v128
	v_exp_f32_e32 v120, v120
	v_mul_f32_e32 v121, 0xbfb8aa3b, v121
	v_rcp_f32_e32 v128, v128
	v_add_f32_e32 v129, 1.0, v129
	v_exp_f32_e32 v121, v121
	v_mad_i64_i32 v[150:151], s[22:23], v210, s66, v[190:191]
	v_and_b32_e32 v132, 0xffff0000, v163
	v_rcp_f32_e32 v129, v129
	v_add_f32_e32 v130, 1.0, v130
	v_mul_f32_e32 v135, v133, v132
	v_lshl_add_u64 v[132:133], v[150:151], 0, v[188:189]
	v_cvt_pk_bf16_f32 v140, v140, v141
	v_rcp_f32_e32 v130, v130
	v_add_f32_e32 v131, 1.0, v131
	v_cvt_pk_bf16_f32 v141, v142, v143
	v_cvt_pk_bf16_f32 v142, v152, v153
	v_cvt_pk_bf16_f32 v143, v134, v135
	global_store_dwordx4 v[132:133], v[140:143], off offset:2048
	v_rcp_f32_e32 v131, v131
	v_add_f32_e32 v120, 1.0, v120
	v_lshlrev_b32_e32 v140, 16, v156
	v_mul_f32_e32 v128, v128, v140
	v_and_b32_e32 v140, 0xffff0000, v156
	v_rcp_f32_e32 v120, v120
	v_add_f32_e32 v121, 1.0, v121
	v_mul_f32_e32 v129, v129, v140
	v_lshlrev_b32_e32 v140, 16, v157
	v_rcp_f32_e32 v121, v121
	v_mul_f32_e32 v130, v130, v140
	v_and_b32_e32 v140, 0xffff0000, v157
	v_mul_f32_e32 v131, v131, v140
	v_lshlrev_b32_e32 v140, 16, v158
	v_mul_f32_e32 v140, v120, v140
	v_and_b32_e32 v120, 0xffff0000, v158
	v_mul_f32_e32 v141, v121, v120
	v_add_f32_e32 v121, v122, v94
	v_mul_f32_e32 v121, 0xbfb8aa3b, v121
	v_exp_f32_e32 v121, v121
	v_lshlrev_b32_e32 v120, 16, v159
	v_add_f32_e32 v116, v116, v104
	v_mul_f32_e32 v116, 0xbfb8aa3b, v116
	v_add_f32_e32 v121, 1.0, v121
	v_rcp_f32_e32 v121, v121
	v_add_f32_e32 v117, v117, v105
	v_exp_f32_e32 v116, v116
	v_mul_f32_e32 v117, 0xbfb8aa3b, v117
	v_mul_f32_e32 v122, v121, v120
	v_add_f32_e32 v121, v123, v95
	v_mul_f32_e32 v121, 0xbfb8aa3b, v121
	v_exp_f32_e32 v121, v121
	v_add_f32_e32 v118, v118, v106
	v_exp_f32_e32 v117, v117
	v_mul_f32_e32 v118, 0xbfb8aa3b, v118
	v_add_f32_e32 v119, v119, v107
	v_add_f32_e32 v121, 1.0, v121
	v_exp_f32_e32 v118, v118
	v_mul_f32_e32 v119, 0xbfb8aa3b, v119
	v_add_f32_e32 v108, v108, v92
	v_rcp_f32_e32 v121, v121
	v_exp_f32_e32 v119, v119
	v_mul_f32_e32 v108, 0xbfb8aa3b, v108
	v_add_f32_e32 v109, v109, v93
	v_add_f32_e32 v116, 1.0, v116
	v_exp_f32_e32 v108, v108
	v_mul_f32_e32 v109, 0xbfb8aa3b, v109
	v_rcp_f32_e32 v116, v116
	v_add_f32_e32 v117, 1.0, v117
	v_exp_f32_e32 v109, v109
	v_mad_i64_i32 v[134:135], s[22:23], v211, s66, v[190:191]
	v_and_b32_e32 v120, 0xffff0000, v159
	v_rcp_f32_e32 v117, v117
	v_add_f32_e32 v118, 1.0, v118
	v_mul_f32_e32 v123, v121, v120
	v_lshl_add_u64 v[120:121], v[134:135], 0, v[188:189]
	v_cvt_pk_bf16_f32 v128, v128, v129
	v_rcp_f32_e32 v118, v118
	v_add_f32_e32 v119, 1.0, v119
	v_cvt_pk_bf16_f32 v129, v130, v131
	v_cvt_pk_bf16_f32 v130, v140, v141
	v_cvt_pk_bf16_f32 v131, v122, v123
	global_store_dwordx4 v[120:121], v[128:131], off offset:2048
	v_rcp_f32_e32 v119, v119
	v_add_f32_e32 v108, 1.0, v108
	v_lshlrev_b32_e32 v128, 16, v144
	v_mul_f32_e32 v116, v116, v128
	v_and_b32_e32 v128, 0xffff0000, v144
	v_rcp_f32_e32 v108, v108
	v_add_f32_e32 v109, 1.0, v109
	v_mul_f32_e32 v117, v117, v128
	v_lshlrev_b32_e32 v128, 16, v145
	v_rcp_f32_e32 v109, v109
	v_mul_f32_e32 v118, v118, v128
	v_and_b32_e32 v128, 0xffff0000, v145
	v_mul_f32_e32 v119, v119, v128
	v_lshlrev_b32_e32 v128, 16, v146
	v_mul_f32_e32 v128, v108, v128
	v_and_b32_e32 v108, 0xffff0000, v146
	v_mul_f32_e32 v129, v109, v108
	v_add_f32_e32 v109, v110, v94
	v_mul_f32_e32 v109, 0xbfb8aa3b, v109
	v_exp_f32_e32 v109, v109
	v_lshlrev_b32_e32 v108, 16, v147
	v_add_f32_e32 v96, v96, v104
	v_mul_f32_e32 v96, 0xbfb8aa3b, v96
	v_add_f32_e32 v109, 1.0, v109
	v_rcp_f32_e32 v109, v109
	v_add_f32_e32 v97, v97, v105
	v_exp_f32_e32 v96, v96
	v_mul_f32_e32 v97, 0xbfb8aa3b, v97
	v_mul_f32_e32 v110, v109, v108
	v_add_f32_e32 v109, v111, v95
	v_mul_f32_e32 v109, 0xbfb8aa3b, v109
	v_exp_f32_e32 v109, v109
	v_add_f32_e32 v98, v98, v106
	v_exp_f32_e32 v97, v97
	v_mul_f32_e32 v98, 0xbfb8aa3b, v98
	v_add_f32_e32 v99, v99, v107
	v_add_f32_e32 v109, 1.0, v109
	v_exp_f32_e32 v98, v98
	v_mul_f32_e32 v99, 0xbfb8aa3b, v99
	v_add_f32_e32 v88, v88, v92
	v_rcp_f32_e32 v109, v109
	v_exp_f32_e32 v99, v99
	v_mul_f32_e32 v88, 0xbfb8aa3b, v88
	v_add_f32_e32 v89, v89, v93
	v_add_f32_e32 v96, 1.0, v96
	v_exp_f32_e32 v88, v88
	v_mul_f32_e32 v89, 0xbfb8aa3b, v89
	v_rcp_f32_e32 v96, v96
	v_add_f32_e32 v97, 1.0, v97
	v_exp_f32_e32 v89, v89
	v_mad_i64_i32 v[122:123], s[22:23], v209, s66, v[190:191]
	v_and_b32_e32 v108, 0xffff0000, v147
	v_rcp_f32_e32 v97, v97
	v_add_f32_e32 v98, 1.0, v98
	v_mul_f32_e32 v111, v109, v108
	v_lshl_add_u64 v[108:109], v[122:123], 0, v[188:189]
	v_cvt_pk_bf16_f32 v116, v116, v117
	v_rcp_f32_e32 v98, v98
	v_add_f32_e32 v99, 1.0, v99
	v_cvt_pk_bf16_f32 v117, v118, v119
	v_cvt_pk_bf16_f32 v118, v128, v129
	v_cvt_pk_bf16_f32 v119, v110, v111
	global_store_dwordx4 v[108:109], v[116:119], off offset:2048
	v_rcp_f32_e32 v99, v99
	v_add_f32_e32 v88, 1.0, v88
	v_lshlrev_b32_e32 v116, 16, v136
	v_mul_f32_e32 v96, v96, v116
	v_and_b32_e32 v116, 0xffff0000, v136
	v_rcp_f32_e32 v88, v88
	v_add_f32_e32 v89, 1.0, v89
	v_mul_f32_e32 v97, v97, v116
	v_lshlrev_b32_e32 v116, 16, v137
	v_rcp_f32_e32 v89, v89
	v_mul_f32_e32 v98, v98, v116
	v_and_b32_e32 v116, 0xffff0000, v137
	v_mul_f32_e32 v99, v99, v116
	v_lshlrev_b32_e32 v116, 16, v138
	v_mul_f32_e32 v116, v88, v116
	v_and_b32_e32 v88, 0xffff0000, v138
	v_mul_f32_e32 v117, v89, v88
	v_add_f32_e32 v89, v90, v94
	v_mul_f32_e32 v89, 0xbfb8aa3b, v89
	v_exp_f32_e32 v89, v89
	v_lshlrev_b32_e32 v88, 16, v139
	v_add_f32_e32 v84, v84, v104
	v_mul_f32_e32 v84, 0xbfb8aa3b, v84
	v_add_f32_e32 v89, 1.0, v89
	v_rcp_f32_e32 v89, v89
	v_add_f32_e32 v85, v85, v105
	v_exp_f32_e32 v84, v84
	v_mul_f32_e32 v85, 0xbfb8aa3b, v85
	v_mul_f32_e32 v118, v89, v88
	v_add_f32_e32 v89, v91, v95
	v_mul_f32_e32 v89, 0xbfb8aa3b, v89
	v_exp_f32_e32 v89, v89
	v_add_f32_e32 v86, v86, v106
	v_exp_f32_e32 v85, v85
	v_mul_f32_e32 v86, 0xbfb8aa3b, v86
	v_add_f32_e32 v87, v87, v107
	v_add_f32_e32 v89, 1.0, v89
	v_exp_f32_e32 v86, v86
	v_mul_f32_e32 v87, 0xbfb8aa3b, v87
	v_add_f32_e32 v80, v80, v92
	v_rcp_f32_e32 v89, v89
	v_exp_f32_e32 v87, v87
	v_mul_f32_e32 v80, 0xbfb8aa3b, v80
	v_add_f32_e32 v81, v81, v93
	v_add_f32_e32 v84, 1.0, v84
	v_exp_f32_e32 v80, v80
	v_mul_f32_e32 v81, 0xbfb8aa3b, v81
	v_rcp_f32_e32 v84, v84
	v_add_f32_e32 v85, 1.0, v85
	v_exp_f32_e32 v81, v81
	v_mad_i64_i32 v[110:111], s[22:23], v208, s66, v[190:191]
	v_and_b32_e32 v88, 0xffff0000, v139
	v_rcp_f32_e32 v85, v85
	v_add_f32_e32 v86, 1.0, v86
	v_mul_f32_e32 v91, v89, v88
	v_lshl_add_u64 v[110:111], v[110:111], 0, v[188:189]
	v_cvt_pk_bf16_f32 v90, v116, v117
	v_rcp_f32_e32 v86, v86
	v_add_f32_e32 v87, 1.0, v87
	v_cvt_pk_bf16_f32 v88, v96, v97
	v_cvt_pk_bf16_f32 v89, v98, v99
	v_cvt_pk_bf16_f32 v91, v118, v91
	global_store_dwordx4 v[110:111], v[88:91], off offset:2048
	v_rcp_f32_e32 v87, v87
	v_add_f32_e32 v80, 1.0, v80
	v_lshlrev_b32_e32 v90, 16, v124
	v_mul_f32_e32 v84, v84, v90
	v_and_b32_e32 v90, 0xffff0000, v124
	v_rcp_f32_e32 v80, v80
	v_add_f32_e32 v81, 1.0, v81
	v_mul_f32_e32 v85, v85, v90
	v_lshlrev_b32_e32 v90, 16, v125
	v_rcp_f32_e32 v81, v81
	v_mul_f32_e32 v86, v86, v90
	v_and_b32_e32 v90, 0xffff0000, v125
	v_mul_f32_e32 v87, v87, v90
	v_lshlrev_b32_e32 v90, 16, v126
	v_mul_f32_e32 v90, v80, v90
	v_and_b32_e32 v80, 0xffff0000, v126
	v_mul_f32_e32 v91, v81, v80
	v_add_f32_e32 v81, v82, v94
	v_mul_f32_e32 v81, 0xbfb8aa3b, v81
	v_exp_f32_e32 v81, v81
	v_lshlrev_b32_e32 v80, 16, v127
	v_add_f32_e32 v76, v76, v104
	v_mul_f32_e32 v76, 0xbfb8aa3b, v76
	v_add_f32_e32 v81, 1.0, v81
	v_rcp_f32_e32 v81, v81
	v_add_f32_e32 v77, v77, v105
	v_exp_f32_e32 v76, v76
	v_mul_f32_e32 v77, 0xbfb8aa3b, v77
	v_mul_f32_e32 v96, v81, v80
	v_add_f32_e32 v81, v83, v95
	v_mul_f32_e32 v81, 0xbfb8aa3b, v81
	v_exp_f32_e32 v81, v81
	v_add_f32_e32 v78, v78, v106
	v_exp_f32_e32 v77, v77
	v_mul_f32_e32 v78, 0xbfb8aa3b, v78
	v_add_f32_e32 v79, v79, v107
	v_add_f32_e32 v81, 1.0, v81
	v_exp_f32_e32 v78, v78
	v_mul_f32_e32 v79, 0xbfb8aa3b, v79
	v_add_f32_e32 v72, v72, v92
	v_rcp_f32_e32 v81, v81
	v_exp_f32_e32 v79, v79
	v_mul_f32_e32 v72, 0xbfb8aa3b, v72
	v_add_f32_e32 v73, v73, v93
	v_add_f32_e32 v76, 1.0, v76
	v_exp_f32_e32 v72, v72
	v_mul_f32_e32 v73, 0xbfb8aa3b, v73
	v_rcp_f32_e32 v76, v76
	v_add_f32_e32 v77, 1.0, v77
	v_exp_f32_e32 v73, v73
	v_mad_i64_i32 v[88:89], s[22:23], v207, s66, v[190:191]
	v_and_b32_e32 v80, 0xffff0000, v127
	v_rcp_f32_e32 v77, v77
	v_add_f32_e32 v78, 1.0, v78
	v_mul_f32_e32 v83, v81, v80
	v_lshl_add_u64 v[116:117], v[88:89], 0, v[188:189]
	v_cvt_pk_bf16_f32 v82, v90, v91
	v_rcp_f32_e32 v78, v78
	v_add_f32_e32 v79, 1.0, v79
	v_cvt_pk_bf16_f32 v80, v84, v85
	v_cvt_pk_bf16_f32 v81, v86, v87
	v_cvt_pk_bf16_f32 v83, v96, v83
	global_store_dwordx4 v[116:117], v[80:83], off offset:2048
	v_rcp_f32_e32 v79, v79
	v_add_f32_e32 v72, 1.0, v72
	v_lshlrev_b32_e32 v82, 16, v112
	v_mul_f32_e32 v76, v76, v82
	v_and_b32_e32 v82, 0xffff0000, v112
	v_rcp_f32_e32 v72, v72
	v_add_f32_e32 v73, 1.0, v73
	v_mul_f32_e32 v77, v77, v82
	v_lshlrev_b32_e32 v82, 16, v113
	v_rcp_f32_e32 v73, v73
	v_mul_f32_e32 v78, v78, v82
	v_and_b32_e32 v82, 0xffff0000, v113
	v_mul_f32_e32 v79, v79, v82
	v_lshlrev_b32_e32 v82, 16, v114
	v_mul_f32_e32 v82, v72, v82
	v_and_b32_e32 v72, 0xffff0000, v114
	v_mul_f32_e32 v83, v73, v72
	v_add_f32_e32 v73, v74, v94
	v_mul_f32_e32 v73, 0xbfb8aa3b, v73
	v_exp_f32_e32 v73, v73
	v_lshlrev_b32_e32 v72, 16, v115
	v_add_f32_e32 v68, v68, v104
	v_mul_f32_e32 v68, 0xbfb8aa3b, v68
	v_add_f32_e32 v73, 1.0, v73
	v_rcp_f32_e32 v73, v73
	v_add_f32_e32 v69, v69, v105
	v_exp_f32_e32 v68, v68
	v_mul_f32_e32 v69, 0xbfb8aa3b, v69
	v_mul_f32_e32 v84, v73, v72
	v_add_f32_e32 v73, v75, v95
	v_mul_f32_e32 v73, 0xbfb8aa3b, v73
	v_exp_f32_e32 v73, v73
	v_add_f32_e32 v70, v70, v106
	v_exp_f32_e32 v69, v69
	v_mul_f32_e32 v70, 0xbfb8aa3b, v70
	v_add_f32_e32 v71, v71, v107
	v_add_f32_e32 v73, 1.0, v73
	v_exp_f32_e32 v70, v70
	v_mul_f32_e32 v71, 0xbfb8aa3b, v71
	v_add_f32_e32 v64, v64, v92
	v_rcp_f32_e32 v73, v73
	v_exp_f32_e32 v71, v71
	v_mul_f32_e32 v64, 0xbfb8aa3b, v64
	v_add_f32_e32 v65, v65, v93
	v_add_f32_e32 v68, 1.0, v68
	v_exp_f32_e32 v64, v64
	v_mul_f32_e32 v65, 0xbfb8aa3b, v65
	v_rcp_f32_e32 v68, v68
	v_add_f32_e32 v69, 1.0, v69
	v_exp_f32_e32 v65, v65
	v_mad_i64_i32 v[80:81], s[22:23], v206, s66, v[190:191]
	v_and_b32_e32 v72, 0xffff0000, v115
	v_rcp_f32_e32 v69, v69
	v_add_f32_e32 v70, 1.0, v70
	v_mul_f32_e32 v75, v73, v72
	v_lshl_add_u64 v[112:113], v[80:81], 0, v[188:189]
	v_cvt_pk_bf16_f32 v74, v82, v83
	v_rcp_f32_e32 v70, v70
	v_add_f32_e32 v71, 1.0, v71
	v_cvt_pk_bf16_f32 v72, v76, v77
	v_cvt_pk_bf16_f32 v73, v78, v79
	v_cvt_pk_bf16_f32 v75, v84, v75
	global_store_dwordx4 v[112:113], v[72:75], off offset:2048
	v_rcp_f32_e32 v71, v71
	v_add_f32_e32 v64, 1.0, v64
	v_lshlrev_b32_e32 v74, 16, v100
	v_mul_f32_e32 v68, v68, v74
	v_and_b32_e32 v74, 0xffff0000, v100
	v_rcp_f32_e32 v64, v64
	v_add_f32_e32 v65, 1.0, v65
	v_mul_f32_e32 v69, v69, v74
	v_lshlrev_b32_e32 v74, 16, v101
	v_rcp_f32_e32 v65, v65
	v_mul_f32_e32 v70, v70, v74
	v_and_b32_e32 v74, 0xffff0000, v101
	v_mul_f32_e32 v71, v71, v74
	v_lshlrev_b32_e32 v74, 16, v102
	v_mul_f32_e32 v74, v64, v74
	v_and_b32_e32 v64, 0xffff0000, v102
	v_mul_f32_e32 v75, v65, v64
	v_add_f32_e32 v65, v66, v94
	v_mul_f32_e32 v65, 0xbfb8aa3b, v65
	v_exp_f32_e32 v65, v65
	v_lshlrev_b32_e32 v64, 16, v103
	v_mad_i64_i32 v[72:73], s[22:23], v187, s66, v[190:191]
	v_add_f32_e32 v65, 1.0, v65
	v_rcp_f32_e32 v65, v65
	v_lshl_add_u64 v[100:101], v[72:73], 0, v[188:189]
	v_cvt_pk_bf16_f32 v66, v74, v75
	v_mul_f32_e32 v76, v65, v64
	v_add_f32_e32 v65, v67, v95
	v_mul_f32_e32 v65, 0xbfb8aa3b, v65
	v_exp_f32_e32 v65, v65
	v_and_b32_e32 v64, 0xffff0000, v103
	v_add_f32_e32 v65, 1.0, v65
	v_rcp_f32_e32 v65, v65
	s_nop 0
	v_mul_f32_e32 v67, v65, v64
	v_cvt_pk_bf16_f32 v64, v68, v69
	v_cvt_pk_bf16_f32 v65, v70, v71
	v_cvt_pk_bf16_f32 v67, v76, v67
	global_store_dwordx4 v[100:101], v[64:67], off offset:2048
	global_load_dwordx4 v[64:67], v[184:185], off offset:528
	s_nop 0
	global_load_dwordx4 v[72:75], v[184:185], off offset:512
	v_add_u32_e32 v68, 0x80, v186
	v_ashrrev_i32_e32 v69, 31, v68
	v_lshl_add_u64 v[68:69], v[68:69], 1, s[86:87]
	v_mad_i64_i32 v[70:71], s[22:23], v205, s66, v[68:69]
	v_mov_b64_e32 v[102:103], v[214:215]
	v_mov_b64_e32 v[104:105], v[216:217]
	v_mad_i64_i32 v[70:71], s[22:23], v210, s66, v[68:69]
	v_mov_b64_e32 v[96:97], v[218:219]
	v_mov_b64_e32 v[98:99], v[220:221]
	v_mad_i64_i32 v[70:71], s[22:23], v211, s66, v[68:69]
	v_mov_b64_e32 v[92:93], v[222:223]
	v_mov_b64_e32 v[94:95], v[224:225]
	v_mad_i64_i32 v[70:71], s[22:23], v209, s66, v[68:69]
	v_mov_b64_e32 v[88:89], v[226:227]
	v_mov_b64_e32 v[90:91], v[228:229]
	v_mad_i64_i32 v[70:71], s[22:23], v208, s66, v[68:69]
	v_mov_b64_e32 v[84:85], v[230:231]
	v_mov_b64_e32 v[86:87], v[232:233]
	v_mad_i64_i32 v[70:71], s[22:23], v207, s66, v[68:69]
	v_mov_b64_e32 v[80:81], v[238:239]
	v_mov_b64_e32 v[82:83], v[240:241]
	v_mad_i64_i32 v[70:71], s[22:23], v206, s66, v[68:69]
	v_mad_i64_i32 v[68:69], s[22:23], v187, s66, v[68:69]
	v_mov_b64_e32 v[76:77], v[242:243]
	v_mov_b64_e32 v[78:79], v[244:245]
	s_mov_b32 s22, s4
	v_mov_b64_e32 v[68:69], v[250:251]
	v_mov_b64_e32 v[70:71], v[252:253]
	s_waitcnt vmcnt(0)
	v_add_f32_e32 v56, v56, v64
	v_add_f32_e32 v61, v61, v73
	v_mul_f32_e32 v61, 0xbfb8aa3b, v61
	v_add_f32_e32 v62, v62, v74
	v_exp_f32_e32 v61, v61
	v_mul_f32_e32 v62, 0xbfb8aa3b, v62
	v_add_f32_e32 v63, v63, v75
	v_exp_f32_e32 v62, v62
	v_mul_f32_e32 v63, 0xbfb8aa3b, v63
	v_exp_f32_e32 v63, v63
	v_mul_f32_e32 v56, 0xbfb8aa3b, v56
	v_add_f32_e32 v57, v57, v65
	v_exp_f32_e32 v56, v56
	v_mul_f32_e32 v57, 0xbfb8aa3b, v57
	v_add_f32_e32 v61, 1.0, v61
	v_exp_f32_e32 v57, v57
	v_rcp_f32_e32 v61, v61
	v_add_f32_e32 v62, 1.0, v62
	v_rcp_f32_e32 v62, v62
	v_add_f32_e32 v63, 1.0, v63
	v_rcp_f32_e32 v63, v63
	v_add_f32_e32 v56, 1.0, v56
	v_lshlrev_b32_e32 v106, 16, v102
	v_and_b32_e32 v102, 0xffff0000, v102
	v_rcp_f32_e32 v56, v56
	v_add_f32_e32 v57, 1.0, v57
	v_mul_f32_e32 v61, v61, v102
	v_lshlrev_b32_e32 v102, 16, v103
	v_rcp_f32_e32 v57, v57
	v_mul_f32_e32 v62, v62, v102
	v_and_b32_e32 v102, 0xffff0000, v103
	v_mul_f32_e32 v63, v63, v102
	v_lshlrev_b32_e32 v102, 16, v104
	v_mul_f32_e32 v102, v56, v102
	v_and_b32_e32 v56, 0xffff0000, v104
	v_mul_f32_e32 v103, v57, v56
	v_add_f32_e32 v57, v58, v66
	v_mul_f32_e32 v57, 0xbfb8aa3b, v57
	v_exp_f32_e32 v57, v57
	v_lshlrev_b32_e32 v56, 16, v105
	v_add_f32_e32 v60, v60, v72
	v_mul_f32_e32 v60, 0xbfb8aa3b, v60
	v_add_f32_e32 v57, 1.0, v57
	v_rcp_f32_e32 v57, v57
	v_exp_f32_e32 v60, v60
	v_add_f32_e32 v52, v52, v72
	v_mul_f32_e32 v52, 0xbfb8aa3b, v52
	v_mul_f32_e32 v104, v57, v56
	v_add_f32_e32 v57, v59, v67
	v_mul_f32_e32 v57, 0xbfb8aa3b, v57
	v_exp_f32_e32 v57, v57
	v_add_f32_e32 v53, v53, v73
	v_exp_f32_e32 v52, v52
	v_mul_f32_e32 v53, 0xbfb8aa3b, v53
	v_add_f32_e32 v54, v54, v74
	v_exp_f32_e32 v53, v53
	v_mul_f32_e32 v54, 0xbfb8aa3b, v54
	v_add_f32_e32 v55, v55, v75
	v_add_f32_e32 v60, 1.0, v60
	v_add_f32_e32 v57, 1.0, v57
	v_exp_f32_e32 v54, v54
	v_mul_f32_e32 v55, 0xbfb8aa3b, v55
	v_add_f32_e32 v48, v48, v64
	v_rcp_f32_e32 v60, v60
	v_rcp_f32_e32 v57, v57
	v_exp_f32_e32 v55, v55
	v_mul_f32_e32 v48, 0xbfb8aa3b, v48
	v_add_f32_e32 v49, v49, v65
	v_add_f32_e32 v52, 1.0, v52
	v_exp_f32_e32 v48, v48
	v_mul_f32_e32 v49, 0xbfb8aa3b, v49
	v_rcp_f32_e32 v52, v52
	v_add_f32_e32 v53, 1.0, v53
	v_exp_f32_e32 v49, v49
	v_and_b32_e32 v56, 0xffff0000, v105
	v_rcp_f32_e32 v53, v53
	v_add_f32_e32 v54, 1.0, v54
	v_mul_f32_e32 v60, v60, v106
	v_mul_f32_e32 v59, v57, v56
	v_cvt_pk_bf16_f32 v56, v60, v61
	v_rcp_f32_e32 v54, v54
	v_add_f32_e32 v55, 1.0, v55
	v_cvt_pk_bf16_f32 v57, v62, v63
	v_cvt_pk_bf16_f32 v58, v102, v103
	v_cvt_pk_bf16_f32 v59, v104, v59
	global_store_dwordx4 v[148:149], v[56:59], off offset:2304
	v_rcp_f32_e32 v55, v55
	v_add_f32_e32 v48, 1.0, v48
	v_lshlrev_b32_e32 v56, 16, v96
	v_mul_f32_e32 v52, v52, v56
	v_and_b32_e32 v56, 0xffff0000, v96
	v_rcp_f32_e32 v48, v48
	v_add_f32_e32 v49, 1.0, v49
	v_mul_f32_e32 v53, v53, v56
	v_lshlrev_b32_e32 v56, 16, v97
	v_rcp_f32_e32 v49, v49
	v_mul_f32_e32 v54, v54, v56
	v_and_b32_e32 v56, 0xffff0000, v97
	v_mul_f32_e32 v55, v55, v56
	v_lshlrev_b32_e32 v56, 16, v98
	v_mul_f32_e32 v56, v48, v56
	v_and_b32_e32 v48, 0xffff0000, v98
	v_mul_f32_e32 v57, v49, v48
	v_add_f32_e32 v49, v50, v66
	v_mul_f32_e32 v49, 0xbfb8aa3b, v49
	v_exp_f32_e32 v49, v49
	v_lshlrev_b32_e32 v48, 16, v99
	v_add_f32_e32 v44, v44, v72
	v_mul_f32_e32 v44, 0xbfb8aa3b, v44
	v_add_f32_e32 v49, 1.0, v49
	v_rcp_f32_e32 v49, v49
	v_add_f32_e32 v45, v45, v73
	v_exp_f32_e32 v44, v44
	v_mul_f32_e32 v45, 0xbfb8aa3b, v45
	v_mul_f32_e32 v58, v49, v48
	v_add_f32_e32 v49, v51, v67
	v_mul_f32_e32 v49, 0xbfb8aa3b, v49
	v_exp_f32_e32 v49, v49
	v_add_f32_e32 v46, v46, v74
	v_exp_f32_e32 v45, v45
	v_mul_f32_e32 v46, 0xbfb8aa3b, v46
	v_add_f32_e32 v47, v47, v75
	v_add_f32_e32 v49, 1.0, v49
	v_exp_f32_e32 v46, v46
	v_mul_f32_e32 v47, 0xbfb8aa3b, v47
	v_add_f32_e32 v40, v40, v64
	v_rcp_f32_e32 v49, v49
	v_exp_f32_e32 v47, v47
	v_mul_f32_e32 v40, 0xbfb8aa3b, v40
	v_add_f32_e32 v41, v41, v65
	v_add_f32_e32 v44, 1.0, v44
	v_exp_f32_e32 v40, v40
	v_mul_f32_e32 v41, 0xbfb8aa3b, v41
	v_rcp_f32_e32 v44, v44
	v_add_f32_e32 v45, 1.0, v45
	v_exp_f32_e32 v41, v41
	v_and_b32_e32 v48, 0xffff0000, v99
	v_rcp_f32_e32 v45, v45
	v_add_f32_e32 v46, 1.0, v46
	v_mul_f32_e32 v51, v49, v48
	v_cvt_pk_bf16_f32 v48, v52, v53
	v_rcp_f32_e32 v46, v46
	v_add_f32_e32 v47, 1.0, v47
	v_cvt_pk_bf16_f32 v49, v54, v55
	v_cvt_pk_bf16_f32 v50, v56, v57
	v_cvt_pk_bf16_f32 v51, v58, v51
	global_store_dwordx4 v[132:133], v[48:51], off offset:2304
	v_rcp_f32_e32 v47, v47
	v_add_f32_e32 v40, 1.0, v40
	v_lshlrev_b32_e32 v48, 16, v92
	v_mul_f32_e32 v44, v44, v48
	v_and_b32_e32 v48, 0xffff0000, v92
	v_rcp_f32_e32 v40, v40
	v_add_f32_e32 v41, 1.0, v41
	v_mul_f32_e32 v45, v45, v48
	v_lshlrev_b32_e32 v48, 16, v93
	v_rcp_f32_e32 v41, v41
	v_mul_f32_e32 v46, v46, v48
	v_and_b32_e32 v48, 0xffff0000, v93
	v_mul_f32_e32 v47, v47, v48
	v_lshlrev_b32_e32 v48, 16, v94
	v_mul_f32_e32 v48, v40, v48
	v_and_b32_e32 v40, 0xffff0000, v94
	v_mul_f32_e32 v49, v41, v40
	v_add_f32_e32 v41, v42, v66
	v_mul_f32_e32 v41, 0xbfb8aa3b, v41
	v_exp_f32_e32 v41, v41
	v_lshlrev_b32_e32 v40, 16, v95
	v_add_f32_e32 v36, v36, v72
	v_mul_f32_e32 v36, 0xbfb8aa3b, v36
	v_add_f32_e32 v41, 1.0, v41
	v_rcp_f32_e32 v41, v41
	v_add_f32_e32 v37, v37, v73
	v_exp_f32_e32 v36, v36
	v_mul_f32_e32 v37, 0xbfb8aa3b, v37
	v_mul_f32_e32 v50, v41, v40
	v_add_f32_e32 v41, v43, v67
	v_mul_f32_e32 v41, 0xbfb8aa3b, v41
	v_exp_f32_e32 v41, v41
	v_add_f32_e32 v38, v38, v74
	v_exp_f32_e32 v37, v37
	v_mul_f32_e32 v38, 0xbfb8aa3b, v38
	v_add_f32_e32 v39, v39, v75
	v_add_f32_e32 v41, 1.0, v41
	v_exp_f32_e32 v38, v38
	v_mul_f32_e32 v39, 0xbfb8aa3b, v39
	v_add_f32_e32 v32, v32, v64
	v_rcp_f32_e32 v41, v41
	v_exp_f32_e32 v39, v39
	v_mul_f32_e32 v32, 0xbfb8aa3b, v32
	v_add_f32_e32 v33, v33, v65
	v_add_f32_e32 v36, 1.0, v36
	v_exp_f32_e32 v32, v32
	v_mul_f32_e32 v33, 0xbfb8aa3b, v33
	v_rcp_f32_e32 v36, v36
	v_add_f32_e32 v37, 1.0, v37
	v_exp_f32_e32 v33, v33
	v_and_b32_e32 v40, 0xffff0000, v95
	v_rcp_f32_e32 v37, v37
	v_add_f32_e32 v38, 1.0, v38
	v_mul_f32_e32 v43, v41, v40
	v_cvt_pk_bf16_f32 v40, v44, v45
	v_rcp_f32_e32 v38, v38
	v_add_f32_e32 v39, 1.0, v39
	v_cvt_pk_bf16_f32 v41, v46, v47
	v_cvt_pk_bf16_f32 v42, v48, v49
	v_cvt_pk_bf16_f32 v43, v50, v43
	global_store_dwordx4 v[120:121], v[40:43], off offset:2304
	v_rcp_f32_e32 v39, v39
	v_add_f32_e32 v32, 1.0, v32
	v_lshlrev_b32_e32 v40, 16, v88
	v_mul_f32_e32 v36, v36, v40
	v_and_b32_e32 v40, 0xffff0000, v88
	v_rcp_f32_e32 v32, v32
	v_add_f32_e32 v33, 1.0, v33
	v_mul_f32_e32 v37, v37, v40
	v_lshlrev_b32_e32 v40, 16, v89
	v_rcp_f32_e32 v33, v33
	v_mul_f32_e32 v38, v38, v40
	v_and_b32_e32 v40, 0xffff0000, v89
	v_mul_f32_e32 v39, v39, v40
	v_lshlrev_b32_e32 v40, 16, v90
	v_mul_f32_e32 v40, v32, v40
	v_and_b32_e32 v32, 0xffff0000, v90
	v_mul_f32_e32 v41, v33, v32
	v_add_f32_e32 v33, v34, v66
	v_mul_f32_e32 v33, 0xbfb8aa3b, v33
	v_exp_f32_e32 v33, v33
	v_lshlrev_b32_e32 v32, 16, v91
	v_add_f32_e32 v28, v28, v72
	v_mul_f32_e32 v28, 0xbfb8aa3b, v28
	v_add_f32_e32 v33, 1.0, v33
	v_rcp_f32_e32 v33, v33
	v_add_f32_e32 v29, v29, v73
	v_exp_f32_e32 v28, v28
	v_mul_f32_e32 v29, 0xbfb8aa3b, v29
	v_mul_f32_e32 v42, v33, v32
	v_add_f32_e32 v33, v35, v67
	v_mul_f32_e32 v33, 0xbfb8aa3b, v33
	v_exp_f32_e32 v33, v33
	v_add_f32_e32 v30, v30, v74
	v_exp_f32_e32 v29, v29
	v_mul_f32_e32 v30, 0xbfb8aa3b, v30
	v_add_f32_e32 v31, v31, v75
	v_add_f32_e32 v33, 1.0, v33
	v_exp_f32_e32 v30, v30
	v_mul_f32_e32 v31, 0xbfb8aa3b, v31
	v_add_f32_e32 v24, v24, v64
	v_rcp_f32_e32 v33, v33
	v_exp_f32_e32 v31, v31
	v_mul_f32_e32 v24, 0xbfb8aa3b, v24
	v_add_f32_e32 v25, v25, v65
	v_add_f32_e32 v28, 1.0, v28
	v_exp_f32_e32 v24, v24
	v_mul_f32_e32 v25, 0xbfb8aa3b, v25
	v_rcp_f32_e32 v28, v28
	v_add_f32_e32 v29, 1.0, v29
	v_exp_f32_e32 v25, v25
	v_and_b32_e32 v32, 0xffff0000, v91
	v_rcp_f32_e32 v29, v29
	v_add_f32_e32 v30, 1.0, v30
	v_mul_f32_e32 v35, v33, v32
	v_cvt_pk_bf16_f32 v32, v36, v37
	v_rcp_f32_e32 v30, v30
	v_add_f32_e32 v31, 1.0, v31
	v_cvt_pk_bf16_f32 v33, v38, v39
	v_cvt_pk_bf16_f32 v34, v40, v41
	v_cvt_pk_bf16_f32 v35, v42, v35
	global_store_dwordx4 v[108:109], v[32:35], off offset:2304
	v_rcp_f32_e32 v31, v31
	v_add_f32_e32 v24, 1.0, v24
	v_lshlrev_b32_e32 v32, 16, v84
	v_mul_f32_e32 v28, v28, v32
	v_and_b32_e32 v32, 0xffff0000, v84
	v_rcp_f32_e32 v24, v24
	v_add_f32_e32 v25, 1.0, v25
	v_mul_f32_e32 v29, v29, v32
	v_lshlrev_b32_e32 v32, 16, v85
	v_rcp_f32_e32 v25, v25
	v_mul_f32_e32 v30, v30, v32
	v_and_b32_e32 v32, 0xffff0000, v85
	v_mul_f32_e32 v31, v31, v32
	v_lshlrev_b32_e32 v32, 16, v86
	v_mul_f32_e32 v32, v24, v32
	v_and_b32_e32 v24, 0xffff0000, v86
	v_mul_f32_e32 v33, v25, v24
	v_add_f32_e32 v25, v26, v66
	v_mul_f32_e32 v25, 0xbfb8aa3b, v25
	v_exp_f32_e32 v25, v25
	v_lshlrev_b32_e32 v24, 16, v87
	v_add_f32_e32 v20, v20, v72
	v_mul_f32_e32 v20, 0xbfb8aa3b, v20
	v_add_f32_e32 v25, 1.0, v25
	v_rcp_f32_e32 v25, v25
	v_add_f32_e32 v21, v21, v73
	v_exp_f32_e32 v20, v20
	v_mul_f32_e32 v21, 0xbfb8aa3b, v21
	v_mul_f32_e32 v34, v25, v24
	v_add_f32_e32 v25, v27, v67
	v_mul_f32_e32 v25, 0xbfb8aa3b, v25
	v_exp_f32_e32 v25, v25
	v_add_f32_e32 v22, v22, v74
	v_exp_f32_e32 v21, v21
	v_mul_f32_e32 v22, 0xbfb8aa3b, v22
	v_add_f32_e32 v23, v23, v75
	v_add_f32_e32 v25, 1.0, v25
	v_exp_f32_e32 v22, v22
	v_mul_f32_e32 v23, 0xbfb8aa3b, v23
	v_add_f32_e32 v16, v16, v64
	v_rcp_f32_e32 v25, v25
	v_exp_f32_e32 v23, v23
	v_mul_f32_e32 v16, 0xbfb8aa3b, v16
	v_add_f32_e32 v17, v17, v65
	v_add_f32_e32 v20, 1.0, v20
	v_exp_f32_e32 v16, v16
	v_mul_f32_e32 v17, 0xbfb8aa3b, v17
	v_rcp_f32_e32 v20, v20
	v_add_f32_e32 v21, 1.0, v21
	v_exp_f32_e32 v17, v17
	v_and_b32_e32 v24, 0xffff0000, v87
	v_rcp_f32_e32 v21, v21
	v_add_f32_e32 v22, 1.0, v22
	v_mul_f32_e32 v27, v25, v24
	v_cvt_pk_bf16_f32 v24, v28, v29
	v_rcp_f32_e32 v22, v22
	v_add_f32_e32 v23, 1.0, v23
	v_cvt_pk_bf16_f32 v25, v30, v31
	v_cvt_pk_bf16_f32 v26, v32, v33
	v_cvt_pk_bf16_f32 v27, v34, v27
	global_store_dwordx4 v[110:111], v[24:27], off offset:2304
	v_rcp_f32_e32 v23, v23
	v_add_f32_e32 v16, 1.0, v16
	v_lshlrev_b32_e32 v24, 16, v80
	v_mul_f32_e32 v20, v20, v24
	v_and_b32_e32 v24, 0xffff0000, v80
	v_rcp_f32_e32 v16, v16
	v_add_f32_e32 v17, 1.0, v17
	v_mul_f32_e32 v21, v21, v24
	v_lshlrev_b32_e32 v24, 16, v81
	v_rcp_f32_e32 v17, v17
	v_mul_f32_e32 v22, v22, v24
	v_and_b32_e32 v24, 0xffff0000, v81
	v_mul_f32_e32 v23, v23, v24
	v_lshlrev_b32_e32 v24, 16, v82
	v_mul_f32_e32 v24, v16, v24
	v_and_b32_e32 v16, 0xffff0000, v82
	v_mul_f32_e32 v25, v17, v16
	v_add_f32_e32 v17, v18, v66
	v_mul_f32_e32 v17, 0xbfb8aa3b, v17
	v_exp_f32_e32 v17, v17
	v_lshlrev_b32_e32 v16, 16, v83
	v_add_f32_e32 v12, v12, v72
	v_mul_f32_e32 v12, 0xbfb8aa3b, v12
	v_add_f32_e32 v17, 1.0, v17
	v_rcp_f32_e32 v17, v17
	v_add_f32_e32 v13, v13, v73
	v_exp_f32_e32 v12, v12
	v_mul_f32_e32 v13, 0xbfb8aa3b, v13
	v_mul_f32_e32 v26, v17, v16
	v_add_f32_e32 v17, v19, v67
	v_mul_f32_e32 v17, 0xbfb8aa3b, v17
	v_exp_f32_e32 v17, v17
	v_add_f32_e32 v14, v14, v74
	v_exp_f32_e32 v13, v13
	v_mul_f32_e32 v14, 0xbfb8aa3b, v14
	v_add_f32_e32 v15, v15, v75
	v_add_f32_e32 v17, 1.0, v17
	v_exp_f32_e32 v14, v14
	v_mul_f32_e32 v15, 0xbfb8aa3b, v15
	v_add_f32_e32 v8, v8, v64
	v_rcp_f32_e32 v17, v17
	v_exp_f32_e32 v15, v15
	v_mul_f32_e32 v8, 0xbfb8aa3b, v8
	v_add_f32_e32 v9, v9, v65
	v_add_f32_e32 v12, 1.0, v12
	v_exp_f32_e32 v8, v8
	v_mul_f32_e32 v9, 0xbfb8aa3b, v9
	v_rcp_f32_e32 v12, v12
	v_add_f32_e32 v13, 1.0, v13
	v_exp_f32_e32 v9, v9
	v_and_b32_e32 v16, 0xffff0000, v83
	v_rcp_f32_e32 v13, v13
	v_add_f32_e32 v14, 1.0, v14
	v_mul_f32_e32 v19, v17, v16
	v_cvt_pk_bf16_f32 v16, v20, v21
	v_rcp_f32_e32 v14, v14
	v_add_f32_e32 v15, 1.0, v15
	v_cvt_pk_bf16_f32 v17, v22, v23
	v_cvt_pk_bf16_f32 v18, v24, v25
	v_cvt_pk_bf16_f32 v19, v26, v19
	global_store_dwordx4 v[116:117], v[16:19], off offset:2304
	v_rcp_f32_e32 v15, v15
	v_add_f32_e32 v8, 1.0, v8
	v_lshlrev_b32_e32 v16, 16, v76
	v_mul_f32_e32 v12, v12, v16
	v_and_b32_e32 v16, 0xffff0000, v76
	v_rcp_f32_e32 v8, v8
	v_add_f32_e32 v9, 1.0, v9
	v_mul_f32_e32 v13, v13, v16
	v_lshlrev_b32_e32 v16, 16, v77
	v_rcp_f32_e32 v9, v9
	v_mul_f32_e32 v14, v14, v16
	v_and_b32_e32 v16, 0xffff0000, v77
	v_mul_f32_e32 v15, v15, v16
	v_lshlrev_b32_e32 v16, 16, v78
	v_mul_f32_e32 v16, v8, v16
	v_and_b32_e32 v8, 0xffff0000, v78
	v_mul_f32_e32 v17, v9, v8
	v_add_f32_e32 v9, v10, v66
	v_mul_f32_e32 v9, 0xbfb8aa3b, v9
	v_exp_f32_e32 v9, v9
	v_lshlrev_b32_e32 v8, 16, v79
	v_add_f32_e32 v4, v4, v72
	v_mul_f32_e32 v4, 0xbfb8aa3b, v4
	v_add_f32_e32 v9, 1.0, v9
	v_rcp_f32_e32 v9, v9
	v_add_f32_e32 v5, v5, v73
	v_exp_f32_e32 v4, v4
	v_mul_f32_e32 v5, 0xbfb8aa3b, v5
	v_mul_f32_e32 v18, v9, v8
	v_add_f32_e32 v9, v11, v67
	v_mul_f32_e32 v9, 0xbfb8aa3b, v9
	v_exp_f32_e32 v9, v9
	v_add_f32_e32 v6, v6, v74
	v_exp_f32_e32 v5, v5
	v_mul_f32_e32 v6, 0xbfb8aa3b, v6
	v_add_f32_e32 v7, v7, v75
	v_add_f32_e32 v9, 1.0, v9
	v_exp_f32_e32 v6, v6
	v_mul_f32_e32 v7, 0xbfb8aa3b, v7
	v_add_f32_e32 v0, v0, v64
	v_rcp_f32_e32 v9, v9
	v_exp_f32_e32 v7, v7
	v_mul_f32_e32 v0, 0xbfb8aa3b, v0
	v_add_f32_e32 v1, v1, v65
	v_add_f32_e32 v4, 1.0, v4
	v_exp_f32_e32 v0, v0
	v_mul_f32_e32 v1, 0xbfb8aa3b, v1
	v_rcp_f32_e32 v4, v4
	v_add_f32_e32 v5, 1.0, v5
	v_exp_f32_e32 v1, v1
	v_and_b32_e32 v8, 0xffff0000, v79
	v_rcp_f32_e32 v5, v5
	v_add_f32_e32 v6, 1.0, v6
	v_mul_f32_e32 v11, v9, v8
	v_cvt_pk_bf16_f32 v8, v12, v13
	v_rcp_f32_e32 v6, v6
	v_add_f32_e32 v7, 1.0, v7
	v_cvt_pk_bf16_f32 v9, v14, v15
	v_cvt_pk_bf16_f32 v10, v16, v17
	v_cvt_pk_bf16_f32 v11, v18, v11
	global_store_dwordx4 v[112:113], v[8:11], off offset:2304
	v_rcp_f32_e32 v7, v7
	v_add_f32_e32 v0, 1.0, v0
	v_lshlrev_b32_e32 v8, 16, v68
	v_mul_f32_e32 v4, v4, v8
	v_and_b32_e32 v8, 0xffff0000, v68
	v_rcp_f32_e32 v0, v0
	v_add_f32_e32 v1, 1.0, v1
	v_mul_f32_e32 v5, v5, v8
	v_lshlrev_b32_e32 v8, 16, v69
	v_rcp_f32_e32 v1, v1
	v_mul_f32_e32 v6, v6, v8
	v_and_b32_e32 v8, 0xffff0000, v69
	v_mul_f32_e32 v7, v7, v8
	v_lshlrev_b32_e32 v8, 16, v70
	v_mul_f32_e32 v8, v0, v8
	v_and_b32_e32 v0, 0xffff0000, v70
	v_mul_f32_e32 v9, v1, v0
	v_add_f32_e32 v1, v2, v66
	v_mul_f32_e32 v1, 0xbfb8aa3b, v1
	v_exp_f32_e32 v1, v1
	v_lshlrev_b32_e32 v0, 16, v71
	v_cvt_pk_bf16_f32 v2, v8, v9
	v_add_f32_e32 v1, 1.0, v1
	v_rcp_f32_e32 v1, v1
	s_nop 0
	v_mul_f32_e32 v10, v1, v0
	v_add_f32_e32 v1, v3, v67
	v_mul_f32_e32 v1, 0xbfb8aa3b, v1
	v_exp_f32_e32 v1, v1
	v_and_b32_e32 v0, 0xffff0000, v71
	v_add_f32_e32 v1, 1.0, v1
	v_rcp_f32_e32 v1, v1
	s_nop 0
	v_mul_f32_e32 v3, v1, v0
	v_cvt_pk_bf16_f32 v0, v4, v5
	v_cvt_pk_bf16_f32 v1, v6, v7
	v_cvt_pk_bf16_f32 v3, v10, v3
	global_store_dwordx4 v[100:101], v[0:3], off offset:2304
	s_cbranch_vccz .LBB0_833
	s_waitcnt vmcnt(0)
	v_readlane_b32 s70, v234, 55
	s_cmpk_gt_u32 s16, 0xff
	v_readlane_b32 s71, v234, 56
	s_cbranch_scc1 .LBB0_840
	s_barrier

.LBB0_920:
	s_add_u32 s42, s34, 0x100
	s_addc_u32 s43, s35, 0
	s_add_i32 s27, 0, 0x10000
	v_add_u32_e32 v112, s27, v203
	ds_read_b128 v[92:95], v112
	ds_read_b128 v[100:103], v112 offset:1024
	ds_read_b128 v[104:107], v112 offset:2048
	ds_read_b128 v[112:115], v112 offset:3072
	s_cmp_eq_u32 s26, 12
	s_cselect_b32 s47, s9, s43
	s_cselect_b32 s46, s8, s42
	s_cselect_b32 s45, s41, s25
	s_cselect_b32 s44, s40, s24
	v_lshl_add_u64 v[192:193], s[34:35], 0, v[180:181]
	s_add_i32 m0, s18, 0xc000
	ds_read_b128 v[124:127], v204
	ds_read_b128 v[136:139], v204 offset:1024
	ds_read_b128 v[144:147], v204 offset:2048
	ds_read_b128 v[156:159], v204 offset:3072
	ds_read_b128 v[160:163], v204 offset:4096
	ds_read_b128 v[164:167], v204 offset:5120
	ds_read_b128 v[184:187], v204 offset:6144
	ds_read_b128 v[188:191], v204 offset:7168
	global_load_lds_dwordx4 v[192:193], off
	v_lshl_add_u64 v[192:193], s[34:35], 0, v[182:183]
	s_add_i32 m0, s18, 0xe000
	s_nop 0
	global_load_lds_dwordx4 v[192:193], off
	s_waitcnt lgkmcnt(8)
	s_barrier
	s_waitcnt lgkmcnt(0)
	s_setprio 1
	s_waitcnt lgkmcnt(0)
	v_mfma_f32_16x16x32_bf16 v[152:155], v[92:95], v[124:127], v[152:155]
	v_mfma_f32_16x16x32_bf16 v[148:151], v[104:107], v[124:127], v[148:151]
	v_mfma_f32_16x16x32_bf16 v[140:143], v[92:95], v[144:147], v[140:143]
	v_mfma_f32_16x16x32_bf16 v[132:135], v[104:107], v[144:147], v[132:135]
	v_mfma_f32_16x16x32_bf16 v[128:131], v[92:95], v[160:163], v[128:131]
	v_mfma_f32_16x16x32_bf16 v[120:123], v[104:107], v[160:163], v[120:123]
	v_mfma_f32_16x16x32_bf16 v[116:119], v[92:95], v[184:187], v[116:119]
	v_mfma_f32_16x16x32_bf16 v[108:111], v[104:107], v[184:187], v[108:111]
	v_mfma_f32_16x16x32_bf16 v[152:155], v[100:103], v[136:139], v[152:155]
	v_mfma_f32_16x16x32_bf16 v[148:151], v[112:115], v[136:139], v[148:151]
	v_mfma_f32_16x16x32_bf16 v[140:143], v[100:103], v[156:159], v[140:143]
	v_mfma_f32_16x16x32_bf16 v[132:135], v[112:115], v[156:159], v[132:135]
	v_mfma_f32_16x16x32_bf16 v[128:131], v[100:103], v[164:167], v[128:131]
	v_mfma_f32_16x16x32_bf16 v[120:123], v[112:115], v[164:167], v[120:123]
	v_mfma_f32_16x16x32_bf16 v[116:119], v[100:103], v[188:191], v[116:119]
	v_mfma_f32_16x16x32_bf16 v[108:111], v[112:115], v[188:191], v[108:111]
	s_setprio 0
	s_barrier
	s_add_i32 s28, 0, 0x14000
	v_add_u32_e32 v192, s28, v203
	s_add_i32 s27, s27, s17
	ds_read_b128 v[206:209], v192
	ds_read_b128 v[210:213], v192 offset:1024
	ds_read_b128 v[214:217], v192 offset:2048
	ds_read_b128 v[218:221], v192 offset:3072
	v_lshl_add_u64 v[192:193], s[44:45], 0, v[172:173]
	s_mov_b32 m0, s27
	v_lshl_add_u64 v[222:223], s[44:45], 0, v[174:175]
	global_load_lds_dwordx4 v[192:193], off
	s_add_i32 m0, s27, 0x2000
	s_nop 0
	global_load_lds_dwordx4 v[222:223], off
	s_barrier
	s_waitcnt lgkmcnt(0)
	s_setprio 1
	s_waitcnt lgkmcnt(0)
	v_mfma_f32_16x16x32_bf16 v[60:63], v[206:209], v[124:127], v[60:63]
	v_mfma_f32_16x16x32_bf16 v[56:59], v[214:217], v[124:127], v[56:59]
	v_mfma_f32_16x16x32_bf16 v[52:55], v[206:209], v[144:147], v[52:55]
	v_mfma_f32_16x16x32_bf16 v[48:51], v[214:217], v[144:147], v[48:51]
	v_mfma_f32_16x16x32_bf16 v[44:47], v[206:209], v[160:163], v[44:47]
	v_mfma_f32_16x16x32_bf16 v[40:43], v[214:217], v[160:163], v[40:43]
	v_mfma_f32_16x16x32_bf16 v[36:39], v[206:209], v[184:187], v[36:39]
	v_mfma_f32_16x16x32_bf16 v[32:35], v[214:217], v[184:187], v[32:35]
	v_mfma_f32_16x16x32_bf16 v[60:63], v[210:213], v[136:139], v[60:63]
	v_mfma_f32_16x16x32_bf16 v[56:59], v[218:221], v[136:139], v[56:59]
	v_mfma_f32_16x16x32_bf16 v[52:55], v[210:213], v[156:159], v[52:55]
	v_mfma_f32_16x16x32_bf16 v[48:51], v[218:221], v[156:159], v[48:51]
	v_mfma_f32_16x16x32_bf16 v[44:47], v[210:213], v[164:167], v[44:47]
	v_mfma_f32_16x16x32_bf16 v[40:43], v[218:221], v[164:167], v[40:43]
	v_mfma_f32_16x16x32_bf16 v[36:39], v[210:213], v[188:191], v[36:39]
	v_mfma_f32_16x16x32_bf16 v[32:35], v[218:221], v[188:191], v[32:35]
	s_setprio 0
	s_mov_b32 m0, s18
	v_lshl_add_u64 v[224:225], s[46:47], 0, v[178:179]
	s_barrier
	ds_read_b128 v[124:127], v204 offset:16384
	ds_read_b128 v[136:139], v204 offset:17408
	ds_read_b128 v[144:147], v204 offset:18432
	ds_read_b128 v[156:159], v204 offset:19456
	ds_read_b128 v[160:163], v204 offset:20480
	ds_read_b128 v[164:167], v204 offset:21504
	ds_read_b128 v[184:187], v204 offset:22528
	ds_read_b128 v[188:191], v204 offset:23552
	global_load_lds_dwordx4 v[224:225], off
	v_lshl_add_u64 v[226:227], s[46:47], 0, v[176:177]
	s_mov_b32 m0, s19
	s_nop 0
	global_load_lds_dwordx4 v[226:227], off
	s_barrier
	s_waitcnt lgkmcnt(0)
	s_setprio 1
	s_waitcnt lgkmcnt(0)
	v_mfma_f32_16x16x32_bf16 v[96:99], v[92:95], v[124:127], v[96:99]
	v_mfma_f32_16x16x32_bf16 v[88:91], v[104:107], v[124:127], v[88:91]
	v_mfma_f32_16x16x32_bf16 v[84:87], v[92:95], v[144:147], v[84:87]
	v_mfma_f32_16x16x32_bf16 v[80:83], v[104:107], v[144:147], v[80:83]
	v_mfma_f32_16x16x32_bf16 v[76:79], v[92:95], v[160:163], v[76:79]
	v_mfma_f32_16x16x32_bf16 v[72:75], v[104:107], v[160:163], v[72:75]
	v_mfma_f32_16x16x32_bf16 v[68:71], v[92:95], v[184:187], v[68:71]
	v_mfma_f32_16x16x32_bf16 v[64:67], v[104:107], v[184:187], v[64:67]
	v_mfma_f32_16x16x32_bf16 v[96:99], v[100:103], v[136:139], v[96:99]
	v_mfma_f32_16x16x32_bf16 v[88:91], v[112:115], v[136:139], v[88:91]
	v_mfma_f32_16x16x32_bf16 v[84:87], v[100:103], v[156:159], v[84:87]
	v_mfma_f32_16x16x32_bf16 v[80:83], v[112:115], v[156:159], v[80:83]
	v_mfma_f32_16x16x32_bf16 v[76:79], v[100:103], v[164:167], v[76:79]
	v_mfma_f32_16x16x32_bf16 v[72:75], v[112:115], v[164:167], v[72:75]
	v_mfma_f32_16x16x32_bf16 v[68:71], v[100:103], v[188:191], v[68:71]
	v_mfma_f32_16x16x32_bf16 v[64:67], v[112:115], v[188:191], v[64:67]
	s_setprio 0
	s_barrier
	s_add_u32 s34, s44, 0x40000
	s_addc_u32 s35, s45, 0
	s_add_i32 s27, s28, s17
	v_lshl_add_u64 v[92:93], s[34:35], 0, v[172:173]
	s_mov_b32 m0, s27
	s_nop 0
	global_load_lds_dwordx4 v[92:93], off
	v_lshl_add_u64 v[92:93], s[34:35], 0, v[174:175]
	s_add_i32 m0, s27, 0x2000
	s_nop 0
	global_load_lds_dwordx4 v[92:93], off
	s_waitcnt vmcnt(6)
	s_barrier
	s_setprio 1
	v_mfma_f32_16x16x32_bf16 v[28:31], v[206:209], v[124:127], v[28:31]
	v_mfma_f32_16x16x32_bf16 v[24:27], v[214:217], v[124:127], v[24:27]
	v_mfma_f32_16x16x32_bf16 v[20:23], v[206:209], v[144:147], v[20:23]
	v_mfma_f32_16x16x32_bf16 v[16:19], v[214:217], v[144:147], v[16:19]
	v_mfma_f32_16x16x32_bf16 v[12:15], v[206:209], v[160:163], v[12:15]
	v_mfma_f32_16x16x32_bf16 v[8:11], v[214:217], v[160:163], v[8:11]
	v_mfma_f32_16x16x32_bf16 v[4:7], v[206:209], v[184:187], v[4:7]
	v_mfma_f32_16x16x32_bf16 v[0:3], v[214:217], v[184:187], v[0:3]
	v_mfma_f32_16x16x32_bf16 v[28:31], v[210:213], v[136:139], v[28:31]
	v_mfma_f32_16x16x32_bf16 v[24:27], v[218:221], v[136:139], v[24:27]
	v_mfma_f32_16x16x32_bf16 v[20:23], v[210:213], v[156:159], v[20:23]
	v_mfma_f32_16x16x32_bf16 v[16:19], v[218:221], v[156:159], v[16:19]
	v_mfma_f32_16x16x32_bf16 v[12:15], v[210:213], v[164:167], v[12:15]
	v_mfma_f32_16x16x32_bf16 v[8:11], v[218:221], v[164:167], v[8:11]
	v_mfma_f32_16x16x32_bf16 v[4:7], v[210:213], v[188:191], v[4:7]
	v_mfma_f32_16x16x32_bf16 v[0:3], v[218:221], v[188:191], v[0:3]
	s_setprio 0
	s_add_i32 s27, 0, 0x18000
	v_add_u32_e32 v112, s27, v203
	s_barrier
	ds_read_b128 v[92:95], v112
	ds_read_b128 v[100:103], v112 offset:1024
	ds_read_b128 v[104:107], v112 offset:2048
	ds_read_b128 v[112:115], v112 offset:3072
	s_add_u32 s34, s46, 0x180000
	s_addc_u32 s35, s47, 0
	s_mov_b32 m0, s20
	v_lshl_add_u64 v[206:207], s[34:35], 0, v[178:179]
	ds_read_b128 v[124:127], v204 offset:32768
	ds_read_b128 v[136:139], v204 offset:33792
	ds_read_b128 v[144:147], v204 offset:34816
	ds_read_b128 v[156:159], v204 offset:35840
	ds_read_b128 v[160:163], v204 offset:36864
	ds_read_b128 v[164:167], v204 offset:37888
	ds_read_b128 v[184:187], v204 offset:38912
	ds_read_b128 v[188:191], v204 offset:39936
	global_load_lds_dwordx4 v[206:207], off
	v_lshl_add_u64 v[206:207], s[34:35], 0, v[176:177]
	s_mov_b32 m0, s21
	s_nop 0
	global_load_lds_dwordx4 v[206:207], off
	s_waitcnt lgkmcnt(8)
	s_barrier
	s_waitcnt lgkmcnt(0)
	s_setprio 1
	s_waitcnt lgkmcnt(0)
	v_mfma_f32_16x16x32_bf16 v[152:155], v[92:95], v[124:127], v[152:155]
	v_mfma_f32_16x16x32_bf16 v[148:151], v[104:107], v[124:127], v[148:151]
	v_mfma_f32_16x16x32_bf16 v[140:143], v[92:95], v[144:147], v[140:143]
	v_mfma_f32_16x16x32_bf16 v[132:135], v[104:107], v[144:147], v[132:135]
	v_mfma_f32_16x16x32_bf16 v[128:131], v[92:95], v[160:163], v[128:131]
	v_mfma_f32_16x16x32_bf16 v[120:123], v[104:107], v[160:163], v[120:123]
	v_mfma_f32_16x16x32_bf16 v[116:119], v[92:95], v[184:187], v[116:119]
	v_mfma_f32_16x16x32_bf16 v[108:111], v[104:107], v[184:187], v[108:111]
	v_mfma_f32_16x16x32_bf16 v[152:155], v[100:103], v[136:139], v[152:155]
	v_mfma_f32_16x16x32_bf16 v[148:151], v[112:115], v[136:139], v[148:151]
	v_mfma_f32_16x16x32_bf16 v[140:143], v[100:103], v[156:159], v[140:143]
	v_mfma_f32_16x16x32_bf16 v[132:135], v[112:115], v[156:159], v[132:135]
	v_mfma_f32_16x16x32_bf16 v[128:131], v[100:103], v[164:167], v[128:131]
	v_mfma_f32_16x16x32_bf16 v[120:123], v[112:115], v[164:167], v[120:123]
	v_mfma_f32_16x16x32_bf16 v[116:119], v[100:103], v[188:191], v[116:119]
	v_mfma_f32_16x16x32_bf16 v[108:111], v[112:115], v[188:191], v[108:111]
	s_setprio 0
	s_barrier
	s_add_i32 s28, 0, 0x1c000
	s_add_i32 s27, s27, s17
	v_add_u32_e32 v205, s28, v203
	v_lshl_add_u64 v[192:193], v[192:193], 0, s[76:77]
	s_mov_b32 m0, s27
	ds_read_b128 v[206:209], v205
	ds_read_b128 v[210:213], v205 offset:1024
	ds_read_b128 v[214:217], v205 offset:2048
	ds_read_b128 v[218:221], v205 offset:3072
	global_load_lds_dwordx4 v[192:193], off
	v_lshl_add_u64 v[192:193], v[222:223], 0, s[76:77]
	s_add_i32 m0, s27, 0x2000
	s_nop 0
	global_load_lds_dwordx4 v[192:193], off
	s_barrier
	s_waitcnt lgkmcnt(0)
	s_setprio 1
	s_waitcnt lgkmcnt(0)
	v_mfma_f32_16x16x32_bf16 v[60:63], v[206:209], v[124:127], v[60:63]
	v_mfma_f32_16x16x32_bf16 v[56:59], v[214:217], v[124:127], v[56:59]
	v_mfma_f32_16x16x32_bf16 v[52:55], v[206:209], v[144:147], v[52:55]
	v_mfma_f32_16x16x32_bf16 v[48:51], v[214:217], v[144:147], v[48:51]
	v_mfma_f32_16x16x32_bf16 v[44:47], v[206:209], v[160:163], v[44:47]
	v_mfma_f32_16x16x32_bf16 v[40:43], v[214:217], v[160:163], v[40:43]
	v_mfma_f32_16x16x32_bf16 v[36:39], v[206:209], v[184:187], v[36:39]
	v_mfma_f32_16x16x32_bf16 v[32:35], v[214:217], v[184:187], v[32:35]
	v_mfma_f32_16x16x32_bf16 v[60:63], v[210:213], v[136:139], v[60:63]
	v_mfma_f32_16x16x32_bf16 v[56:59], v[218:221], v[136:139], v[56:59]
	v_mfma_f32_16x16x32_bf16 v[52:55], v[210:213], v[156:159], v[52:55]
	v_mfma_f32_16x16x32_bf16 v[48:51], v[218:221], v[156:159], v[48:51]
	v_mfma_f32_16x16x32_bf16 v[44:47], v[210:213], v[164:167], v[44:47]
	v_mfma_f32_16x16x32_bf16 v[40:43], v[218:221], v[164:167], v[40:43]
	v_mfma_f32_16x16x32_bf16 v[36:39], v[210:213], v[188:191], v[36:39]
	v_mfma_f32_16x16x32_bf16 v[32:35], v[218:221], v[188:191], v[32:35]
	s_setprio 0
	s_mov_b32 m0, s54
	v_lshl_add_u64 v[192:193], v[224:225], 0, s[76:77]
	s_barrier
	ds_read_b128 v[124:127], v204 offset:49152
	ds_read_b128 v[136:139], v204 offset:50176
	ds_read_b128 v[144:147], v204 offset:51200
	ds_read_b128 v[156:159], v204 offset:52224
	ds_read_b128 v[160:163], v204 offset:53248
	ds_read_b128 v[164:167], v204 offset:54272
	ds_read_b128 v[184:187], v204 offset:55296
	ds_read_b128 v[188:191], v204 offset:56320
	global_load_lds_dwordx4 v[192:193], off
	v_lshl_add_u64 v[192:193], v[226:227], 0, s[76:77]
	s_mov_b32 m0, s55
	s_nop 0
	global_load_lds_dwordx4 v[192:193], off
	s_barrier
	s_waitcnt lgkmcnt(0)
	s_setprio 1
	s_waitcnt lgkmcnt(0)
	v_mfma_f32_16x16x32_bf16 v[96:99], v[92:95], v[124:127], v[96:99]
	v_mfma_f32_16x16x32_bf16 v[88:91], v[104:107], v[124:127], v[88:91]
	v_mfma_f32_16x16x32_bf16 v[84:87], v[92:95], v[144:147], v[84:87]
	v_mfma_f32_16x16x32_bf16 v[80:83], v[104:107], v[144:147], v[80:83]
	v_mfma_f32_16x16x32_bf16 v[76:79], v[92:95], v[160:163], v[76:79]
	v_mfma_f32_16x16x32_bf16 v[72:75], v[104:107], v[160:163], v[72:75]
	v_mfma_f32_16x16x32_bf16 v[68:71], v[92:95], v[184:187], v[68:71]
	v_mfma_f32_16x16x32_bf16 v[64:67], v[104:107], v[184:187], v[64:67]
	v_mfma_f32_16x16x32_bf16 v[96:99], v[100:103], v[136:139], v[96:99]
	v_mfma_f32_16x16x32_bf16 v[88:91], v[112:115], v[136:139], v[88:91]
	v_mfma_f32_16x16x32_bf16 v[84:87], v[100:103], v[156:159], v[84:87]
	v_mfma_f32_16x16x32_bf16 v[80:83], v[112:115], v[156:159], v[80:83]
	v_mfma_f32_16x16x32_bf16 v[76:79], v[100:103], v[164:167], v[76:79]
	v_mfma_f32_16x16x32_bf16 v[72:75], v[112:115], v[164:167], v[72:75]
	v_mfma_f32_16x16x32_bf16 v[68:71], v[100:103], v[188:191], v[68:71]
	v_mfma_f32_16x16x32_bf16 v[64:67], v[112:115], v[188:191], v[64:67]
	s_setprio 0
	s_barrier
	s_add_u32 s34, s44, 0x40080
	s_addc_u32 s35, s45, 0
	s_add_i32 s27, s28, s17
	v_lshl_add_u64 v[92:93], s[34:35], 0, v[172:173]
	s_mov_b32 m0, s27
	s_nop 0
	global_load_lds_dwordx4 v[92:93], off
	v_lshl_add_u64 v[92:93], s[34:35], 0, v[174:175]
	s_add_i32 m0, s27, 0x2000
	s_nop 0
	global_load_lds_dwordx4 v[92:93], off
	s_waitcnt vmcnt(6)
	s_barrier
	s_setprio 1
	v_mfma_f32_16x16x32_bf16 v[28:31], v[206:209], v[124:127], v[28:31]
	v_mfma_f32_16x16x32_bf16 v[24:27], v[214:217], v[124:127], v[24:27]
	v_mfma_f32_16x16x32_bf16 v[20:23], v[206:209], v[144:147], v[20:23]
	v_mfma_f32_16x16x32_bf16 v[16:19], v[214:217], v[144:147], v[16:19]
	v_mfma_f32_16x16x32_bf16 v[12:15], v[206:209], v[160:163], v[12:15]
	v_mfma_f32_16x16x32_bf16 v[8:11], v[214:217], v[160:163], v[8:11]
	v_mfma_f32_16x16x32_bf16 v[4:7], v[206:209], v[184:187], v[4:7]
	v_mfma_f32_16x16x32_bf16 v[0:3], v[214:217], v[184:187], v[0:3]
	v_mfma_f32_16x16x32_bf16 v[28:31], v[210:213], v[136:139], v[28:31]
	v_mfma_f32_16x16x32_bf16 v[24:27], v[218:221], v[136:139], v[24:27]
	v_mfma_f32_16x16x32_bf16 v[20:23], v[210:213], v[156:159], v[20:23]
	v_mfma_f32_16x16x32_bf16 v[16:19], v[218:221], v[156:159], v[16:19]
	v_mfma_f32_16x16x32_bf16 v[12:15], v[210:213], v[164:167], v[12:15]
	v_mfma_f32_16x16x32_bf16 v[8:11], v[218:221], v[164:167], v[8:11]
	v_mfma_f32_16x16x32_bf16 v[4:7], v[210:213], v[188:191], v[4:7]
	v_mfma_f32_16x16x32_bf16 v[0:3], v[218:221], v[188:191], v[0:3]
	s_setprio 0
	s_add_i32 s26, s26, 2
	s_add_u32 s24, s24, 0x100
	s_addc_u32 s25, s25, 0
	s_cmp_gt_u32 s26, 13
	s_mov_b64 s[34:35], s[42:43]
	s_barrier
	s_cbranch_scc0 .LBB0_920
	s_lshl_b32 s23, s23, 8
	v_mov_b32_e32 v92, v201
	v_mov_b32_e32 v93, v202
	s_or_b32 s23, s23, s49
	s_lshl_b32 s22, s22, 8
	v_lshl_add_u32 v184, v93, 3, s23
	v_ashrrev_i32_e32 v185, 31, v184
	s_add_i32 s22, s22, s48
	v_lshl_add_u64 v[186:187], v[184:185], 2, s[0:1]
	v_add_u32_e32 v205, s22, v92
	global_load_dwordx4 v[92:95], v[186:187], off offset:16
	global_load_dwordx4 v[104:107], v[186:187], off
	v_lshlrev_b64 v[188:189], 1, v[184:185]
	v_lshl_add_u64 v[100:101], s[86:87], 0, v[188:189]
	v_mad_i64_i32 v[102:103], s[22:23], v205, s66, v[100:101]
	global_load_dwordx4 v[164:167], v[102:103], off offset:2048
	v_add_u32_e32 v210, 16, v205
	v_mad_i64_i32 v[102:103], s[22:23], v210, s66, v[100:101]
	global_load_dwordx4 v[160:163], v[102:103], off offset:2048
	v_add_u32_e32 v211, 32, v205
	v_mad_i64_i32 v[102:103], s[22:23], v211, s66, v[100:101]
	global_load_dwordx4 v[156:159], v[102:103], off offset:2048
	v_add_u32_e32 v209, 48, v205
	v_mad_i64_i32 v[102:103], s[22:23], v209, s66, v[100:101]
	global_load_dwordx4 v[144:147], v[102:103], off offset:2048
	v_mov_b64_e32 v[190:191], s[86:87]
	v_mad_i64_i32 v[192:193], s[22:23], v205, s66, v[190:191]
	v_add_u32_e32 v208, 0x80, v205
	v_mad_i64_i32 v[102:103], s[22:23], v208, s66, v[100:101]
	global_load_dwordx4 v[136:139], v[102:103], off offset:2048
	v_add_u32_e32 v207, 0x90, v205
	v_mad_i64_i32 v[102:103], s[22:23], v207, s66, v[100:101]
	global_load_dwordx4 v[124:127], v[102:103], off offset:2048
	v_add_u32_e32 v206, 0xa0, v205
	v_mad_i64_i32 v[102:103], s[22:23], v206, s66, v[100:101]
	global_load_dwordx4 v[112:115], v[102:103], off offset:2048
	v_add_u32_e32 v185, 0xb0, v205
	v_mad_i64_i32 v[100:101], s[22:23], v185, s66, v[100:101]
	global_load_dwordx4 v[100:103], v[100:101], off offset:2048
	v_add_u32_e32 v246, 0x80, v184
	v_ashrrev_i32_e32 v247, 31, v246
	v_lshl_add_u64 v[246:247], v[246:247], 1, s[86:87]
	v_mad_i64_i32 v[248:249], s[22:23], v205, s66, v[246:247]
	global_load_dwordx4 v[214:217], v[248:249], off offset:2048
	v_mad_i64_i32 v[248:249], s[22:23], v210, s66, v[246:247]
	global_load_dwordx4 v[218:221], v[248:249], off offset:2048
	v_mad_i64_i32 v[248:249], s[22:23], v211, s66, v[246:247]
	global_load_dwordx4 v[222:225], v[248:249], off offset:2048
	v_mad_i64_i32 v[248:249], s[22:23], v209, s66, v[246:247]
	global_load_dwordx4 v[226:229], v[248:249], off offset:2048
	v_mad_i64_i32 v[248:249], s[22:23], v208, s66, v[246:247]
	global_load_dwordx4 v[230:233], v[248:249], off offset:2048
	v_mad_i64_i32 v[248:249], s[22:23], v207, s66, v[246:247]
	global_load_dwordx4 v[238:241], v[248:249], off offset:2048
	v_mad_i64_i32 v[248:249], s[22:23], v206, s66, v[246:247]
	global_load_dwordx4 v[242:245], v[248:249], off offset:2048
	v_mad_i64_i32 v[248:249], s[22:23], v185, s66, v[246:247]
	global_load_dwordx4 v[250:253], v[248:249], off offset:2048
	s_nop 0
	s_nop 0
	s_nop 0
	s_nop 0
	s_nop 0
	s_nop 0
	s_nop 0
	s_nop 0
	s_nop 0
	s_nop 0
	s_nop 0
	s_nop 0
	s_nop 0
	s_nop 0
	s_nop 0
	s_nop 0
	s_nop 0
	s_nop 0
	s_nop 0
	s_nop 0
	s_nop 0
	s_nop 0
	s_nop 0
	s_nop 0
	s_nop 0
	s_nop 0
	s_nop 0
	s_and_b64 vcc, exec, s[4:5]
	s_mov_b64 s[42:43], s[40:41]
	s_mov_b64 s[34:35], s[8:9]
	s_waitcnt vmcnt(0)
	v_add_f32_e32 v148, v148, v92
	v_add_f32_e32 v153, v153, v105
	v_mul_f32_e32 v153, 0xbfb8aa3b, v153
	v_add_f32_e32 v154, v154, v106
	v_exp_f32_e32 v153, v153
	v_mul_f32_e32 v154, 0xbfb8aa3b, v154
	v_add_f32_e32 v155, v155, v107
	v_exp_f32_e32 v154, v154
	v_mul_f32_e32 v155, 0xbfb8aa3b, v155
	v_exp_f32_e32 v155, v155
	v_mul_f32_e32 v148, 0xbfb8aa3b, v148
	v_add_f32_e32 v149, v149, v93
	v_exp_f32_e32 v148, v148
	v_mul_f32_e32 v149, 0xbfb8aa3b, v149
	v_add_f32_e32 v153, 1.0, v153
	v_exp_f32_e32 v149, v149
	v_rcp_f32_e32 v153, v153
	v_add_f32_e32 v154, 1.0, v154
	v_rcp_f32_e32 v154, v154
	v_add_f32_e32 v155, 1.0, v155
	v_rcp_f32_e32 v155, v155
	v_add_f32_e32 v148, 1.0, v148
	v_lshlrev_b32_e32 v212, 16, v164
	v_and_b32_e32 v164, 0xffff0000, v164
	v_rcp_f32_e32 v148, v148
	v_add_f32_e32 v149, 1.0, v149
	v_mul_f32_e32 v153, v153, v164
	v_lshlrev_b32_e32 v164, 16, v165
	v_rcp_f32_e32 v149, v149
	v_mul_f32_e32 v154, v154, v164
	v_and_b32_e32 v164, 0xffff0000, v165
	v_mul_f32_e32 v155, v155, v164
	v_lshlrev_b32_e32 v164, 16, v166
	v_mul_f32_e32 v164, v148, v164
	v_and_b32_e32 v148, 0xffff0000, v166
	v_mul_f32_e32 v165, v149, v148
	v_add_f32_e32 v149, v150, v94
	v_mul_f32_e32 v149, 0xbfb8aa3b, v149
	v_exp_f32_e32 v149, v149
	v_add_f32_e32 v152, v152, v104
	v_lshlrev_b32_e32 v148, 16, v167
	v_mul_f32_e32 v152, 0xbfb8aa3b, v152
	v_add_f32_e32 v149, 1.0, v149
	v_rcp_f32_e32 v149, v149
	v_exp_f32_e32 v152, v152
	v_add_f32_e32 v140, v140, v104
	v_mul_f32_e32 v140, 0xbfb8aa3b, v140
	v_mul_f32_e32 v166, v149, v148
	v_add_f32_e32 v149, v151, v95
	v_mul_f32_e32 v149, 0xbfb8aa3b, v149
	v_exp_f32_e32 v149, v149
	v_add_f32_e32 v141, v141, v105
	v_exp_f32_e32 v140, v140
	v_mul_f32_e32 v141, 0xbfb8aa3b, v141
	v_add_f32_e32 v142, v142, v106
	v_add_f32_e32 v152, 1.0, v152
	v_exp_f32_e32 v141, v141
	v_mul_f32_e32 v142, 0xbfb8aa3b, v142
	v_add_f32_e32 v143, v143, v107
	v_rcp_f32_e32 v152, v152
	v_add_f32_e32 v149, 1.0, v149
	v_exp_f32_e32 v142, v142
	v_mul_f32_e32 v143, 0xbfb8aa3b, v143
	v_add_f32_e32 v132, v132, v92
	v_rcp_f32_e32 v149, v149
	v_exp_f32_e32 v143, v143
	v_mul_f32_e32 v132, 0xbfb8aa3b, v132
	v_add_f32_e32 v133, v133, v93
	v_add_f32_e32 v140, 1.0, v140
	v_exp_f32_e32 v132, v132
	v_mul_f32_e32 v133, 0xbfb8aa3b, v133
	v_rcp_f32_e32 v140, v140
	v_add_f32_e32 v141, 1.0, v141
	v_exp_f32_e32 v133, v133
	v_mul_f32_e32 v152, v152, v212
	v_and_b32_e32 v148, 0xffff0000, v167
	v_rcp_f32_e32 v141, v141
	v_add_f32_e32 v142, 1.0, v142
	v_mul_f32_e32 v167, v149, v148
	v_lshl_add_u64 v[148:149], v[192:193], 0, v[188:189]
	v_cvt_pk_bf16_f32 v150, v152, v153
	v_cvt_pk_bf16_f32 v152, v164, v165
	v_rcp_f32_e32 v142, v142
	v_add_f32_e32 v143, 1.0, v143
	v_cvt_pk_bf16_f32 v151, v154, v155
	v_cvt_pk_bf16_f32 v153, v166, v167
	global_store_dwordx4 v[148:149], v[150:153], off offset:2048
	v_rcp_f32_e32 v143, v143
	v_add_f32_e32 v132, 1.0, v132
	v_lshlrev_b32_e32 v152, 16, v160
	v_mul_f32_e32 v140, v140, v152
	v_and_b32_e32 v152, 0xffff0000, v160
	v_rcp_f32_e32 v132, v132
	v_add_f32_e32 v133, 1.0, v133
	v_mul_f32_e32 v141, v141, v152
	v_lshlrev_b32_e32 v152, 16, v161
	v_rcp_f32_e32 v133, v133
	v_mul_f32_e32 v142, v142, v152
	v_and_b32_e32 v152, 0xffff0000, v161
	v_mul_f32_e32 v143, v143, v152
	v_lshlrev_b32_e32 v152, 16, v162
	v_mul_f32_e32 v152, v132, v152
	v_and_b32_e32 v132, 0xffff0000, v162
	v_mul_f32_e32 v153, v133, v132
	v_add_f32_e32 v133, v134, v94
	v_mul_f32_e32 v133, 0xbfb8aa3b, v133
	v_exp_f32_e32 v133, v133
	v_lshlrev_b32_e32 v132, 16, v163
	v_add_f32_e32 v128, v128, v104
	v_mul_f32_e32 v128, 0xbfb8aa3b, v128
	v_add_f32_e32 v133, 1.0, v133
	v_rcp_f32_e32 v133, v133
	v_add_f32_e32 v129, v129, v105
	v_exp_f32_e32 v128, v128
	v_mul_f32_e32 v129, 0xbfb8aa3b, v129
	v_mul_f32_e32 v134, v133, v132
	v_add_f32_e32 v133, v135, v95
	v_mul_f32_e32 v133, 0xbfb8aa3b, v133
	v_exp_f32_e32 v133, v133
	v_add_f32_e32 v130, v130, v106
	v_exp_f32_e32 v129, v129
	v_mul_f32_e32 v130, 0xbfb8aa3b, v130
	v_add_f32_e32 v131, v131, v107
	v_add_f32_e32 v133, 1.0, v133
	v_exp_f32_e32 v130, v130
	v_mul_f32_e32 v131, 0xbfb8aa3b, v131
	v_add_f32_e32 v120, v120, v92
	v_rcp_f32_e32 v133, v133
	v_exp_f32_e32 v131, v131
	v_mul_f32_e32 v120, 0xbfb8aa3b, v120
	v_add_f32_e32 v121, v121, v93
	v_add_f32_e32 v128, 1.0, v128
	v_exp_f32_e32 v120, v120
	v_mul_f32_e32 v121, 0xbfb8aa3b, v121
	v_rcp_f32_e32 v128, v128
	v_add_f32_e32 v129, 1.0, v129
	v_exp_f32_e32 v121, v121
	v_mad_i64_i32 v[150:151], s[22:23], v210, s66, v[190:191]
	v_and_b32_e32 v132, 0xffff0000, v163
	v_rcp_f32_e32 v129, v129
	v_add_f32_e32 v130, 1.0, v130
	v_mul_f32_e32 v135, v133, v132
	v_lshl_add_u64 v[132:133], v[150:151], 0, v[188:189]
	v_cvt_pk_bf16_f32 v140, v140, v141
	v_rcp_f32_e32 v130, v130
	v_add_f32_e32 v131, 1.0, v131
	v_cvt_pk_bf16_f32 v141, v142, v143
	v_cvt_pk_bf16_f32 v142, v152, v153
	v_cvt_pk_bf16_f32 v143, v134, v135
	global_store_dwordx4 v[132:133], v[140:143], off offset:2048
	v_rcp_f32_e32 v131, v131
	v_add_f32_e32 v120, 1.0, v120
	v_lshlrev_b32_e32 v140, 16, v156
	v_mul_f32_e32 v128, v128, v140
	v_and_b32_e32 v140, 0xffff0000, v156
	v_rcp_f32_e32 v120, v120
	v_add_f32_e32 v121, 1.0, v121
	v_mul_f32_e32 v129, v129, v140
	v_lshlrev_b32_e32 v140, 16, v157
	v_rcp_f32_e32 v121, v121
	v_mul_f32_e32 v130, v130, v140
	v_and_b32_e32 v140, 0xffff0000, v157
	v_mul_f32_e32 v131, v131, v140
	v_lshlrev_b32_e32 v140, 16, v158
	v_mul_f32_e32 v140, v120, v140
	v_and_b32_e32 v120, 0xffff0000, v158
	v_mul_f32_e32 v141, v121, v120
	v_add_f32_e32 v121, v122, v94
	v_mul_f32_e32 v121, 0xbfb8aa3b, v121
	v_exp_f32_e32 v121, v121
	v_lshlrev_b32_e32 v120, 16, v159
	v_add_f32_e32 v116, v116, v104
	v_mul_f32_e32 v116, 0xbfb8aa3b, v116
	v_add_f32_e32 v121, 1.0, v121
	v_rcp_f32_e32 v121, v121
	v_add_f32_e32 v117, v117, v105
	v_exp_f32_e32 v116, v116
	v_mul_f32_e32 v117, 0xbfb8aa3b, v117
	v_mul_f32_e32 v122, v121, v120
	v_add_f32_e32 v121, v123, v95
	v_mul_f32_e32 v121, 0xbfb8aa3b, v121
	v_exp_f32_e32 v121, v121
	v_add_f32_e32 v118, v118, v106
	v_exp_f32_e32 v117, v117
	v_mul_f32_e32 v118, 0xbfb8aa3b, v118
	v_add_f32_e32 v119, v119, v107
	v_add_f32_e32 v121, 1.0, v121
	v_exp_f32_e32 v118, v118
	v_mul_f32_e32 v119, 0xbfb8aa3b, v119
	v_add_f32_e32 v108, v108, v92
	v_rcp_f32_e32 v121, v121
	v_exp_f32_e32 v119, v119
	v_mul_f32_e32 v108, 0xbfb8aa3b, v108
	v_add_f32_e32 v109, v109, v93
	v_add_f32_e32 v116, 1.0, v116
	v_exp_f32_e32 v108, v108
	v_mul_f32_e32 v109, 0xbfb8aa3b, v109
	v_rcp_f32_e32 v116, v116
	v_add_f32_e32 v117, 1.0, v117
	v_exp_f32_e32 v109, v109
	v_mad_i64_i32 v[134:135], s[22:23], v211, s66, v[190:191]
	v_and_b32_e32 v120, 0xffff0000, v159
	v_rcp_f32_e32 v117, v117
	v_add_f32_e32 v118, 1.0, v118
	v_mul_f32_e32 v123, v121, v120
	v_lshl_add_u64 v[120:121], v[134:135], 0, v[188:189]
	v_cvt_pk_bf16_f32 v128, v128, v129
	v_rcp_f32_e32 v118, v118
	v_add_f32_e32 v119, 1.0, v119
	v_cvt_pk_bf16_f32 v129, v130, v131
	v_cvt_pk_bf16_f32 v130, v140, v141
	v_cvt_pk_bf16_f32 v131, v122, v123
	global_store_dwordx4 v[120:121], v[128:131], off offset:2048
	v_rcp_f32_e32 v119, v119
	v_add_f32_e32 v108, 1.0, v108
	v_lshlrev_b32_e32 v128, 16, v144
	v_mul_f32_e32 v116, v116, v128
	v_and_b32_e32 v128, 0xffff0000, v144
	v_rcp_f32_e32 v108, v108
	v_add_f32_e32 v109, 1.0, v109
	v_mul_f32_e32 v117, v117, v128
	v_lshlrev_b32_e32 v128, 16, v145
	v_rcp_f32_e32 v109, v109
	v_mul_f32_e32 v118, v118, v128
	v_and_b32_e32 v128, 0xffff0000, v145
	v_mul_f32_e32 v119, v119, v128
	v_lshlrev_b32_e32 v128, 16, v146
	v_mul_f32_e32 v128, v108, v128
	v_and_b32_e32 v108, 0xffff0000, v146
	v_mul_f32_e32 v129, v109, v108
	v_add_f32_e32 v109, v110, v94
	v_mul_f32_e32 v109, 0xbfb8aa3b, v109
	v_exp_f32_e32 v109, v109
	v_lshlrev_b32_e32 v108, 16, v147
	v_add_f32_e32 v96, v96, v104
	v_mul_f32_e32 v96, 0xbfb8aa3b, v96
	v_add_f32_e32 v109, 1.0, v109
	v_rcp_f32_e32 v109, v109
	v_add_f32_e32 v97, v97, v105
	v_exp_f32_e32 v96, v96
	v_mul_f32_e32 v97, 0xbfb8aa3b, v97
	v_mul_f32_e32 v110, v109, v108
	v_add_f32_e32 v109, v111, v95
	v_mul_f32_e32 v109, 0xbfb8aa3b, v109
	v_exp_f32_e32 v109, v109
	v_add_f32_e32 v98, v98, v106
	v_exp_f32_e32 v97, v97
	v_mul_f32_e32 v98, 0xbfb8aa3b, v98
	v_add_f32_e32 v99, v99, v107
	v_add_f32_e32 v109, 1.0, v109
	v_exp_f32_e32 v98, v98
	v_mul_f32_e32 v99, 0xbfb8aa3b, v99
	v_add_f32_e32 v88, v88, v92
	v_rcp_f32_e32 v109, v109
	v_exp_f32_e32 v99, v99
	v_mul_f32_e32 v88, 0xbfb8aa3b, v88
	v_add_f32_e32 v89, v89, v93
	v_add_f32_e32 v96, 1.0, v96
	v_exp_f32_e32 v88, v88
	v_mul_f32_e32 v89, 0xbfb8aa3b, v89
	v_rcp_f32_e32 v96, v96
	v_add_f32_e32 v97, 1.0, v97
	v_exp_f32_e32 v89, v89
	v_mad_i64_i32 v[122:123], s[22:23], v209, s66, v[190:191]
	v_and_b32_e32 v108, 0xffff0000, v147
	v_rcp_f32_e32 v97, v97
	v_add_f32_e32 v98, 1.0, v98
	v_mul_f32_e32 v111, v109, v108
	v_lshl_add_u64 v[108:109], v[122:123], 0, v[188:189]
	v_cvt_pk_bf16_f32 v116, v116, v117
	v_rcp_f32_e32 v98, v98
	v_add_f32_e32 v99, 1.0, v99
	v_cvt_pk_bf16_f32 v117, v118, v119
	v_cvt_pk_bf16_f32 v118, v128, v129
	v_cvt_pk_bf16_f32 v119, v110, v111
	global_store_dwordx4 v[108:109], v[116:119], off offset:2048
	v_rcp_f32_e32 v99, v99
	v_add_f32_e32 v88, 1.0, v88
	v_lshlrev_b32_e32 v116, 16, v136
	v_mul_f32_e32 v96, v96, v116
	v_and_b32_e32 v116, 0xffff0000, v136
	v_rcp_f32_e32 v88, v88
	v_add_f32_e32 v89, 1.0, v89
	v_mul_f32_e32 v97, v97, v116
	v_lshlrev_b32_e32 v116, 16, v137
	v_rcp_f32_e32 v89, v89
	v_mul_f32_e32 v98, v98, v116
	v_and_b32_e32 v116, 0xffff0000, v137
	v_mul_f32_e32 v99, v99, v116
	v_lshlrev_b32_e32 v116, 16, v138
	v_mul_f32_e32 v116, v88, v116
	v_and_b32_e32 v88, 0xffff0000, v138
	v_mul_f32_e32 v117, v89, v88
	v_add_f32_e32 v89, v90, v94
	v_mul_f32_e32 v89, 0xbfb8aa3b, v89
	v_exp_f32_e32 v89, v89
	v_lshlrev_b32_e32 v88, 16, v139
	v_add_f32_e32 v84, v84, v104
	v_mul_f32_e32 v84, 0xbfb8aa3b, v84
	v_add_f32_e32 v89, 1.0, v89
	v_rcp_f32_e32 v89, v89
	v_add_f32_e32 v85, v85, v105
	v_exp_f32_e32 v84, v84
	v_mul_f32_e32 v85, 0xbfb8aa3b, v85
	v_mul_f32_e32 v118, v89, v88
	v_add_f32_e32 v89, v91, v95
	v_mul_f32_e32 v89, 0xbfb8aa3b, v89
	v_exp_f32_e32 v89, v89
	v_add_f32_e32 v86, v86, v106
	v_exp_f32_e32 v85, v85
	v_mul_f32_e32 v86, 0xbfb8aa3b, v86
	v_add_f32_e32 v87, v87, v107
	v_add_f32_e32 v89, 1.0, v89
	v_exp_f32_e32 v86, v86
	v_mul_f32_e32 v87, 0xbfb8aa3b, v87
	v_add_f32_e32 v80, v80, v92
	v_rcp_f32_e32 v89, v89
	v_exp_f32_e32 v87, v87
	v_mul_f32_e32 v80, 0xbfb8aa3b, v80
	v_add_f32_e32 v81, v81, v93
	v_add_f32_e32 v84, 1.0, v84
	v_exp_f32_e32 v80, v80
	v_mul_f32_e32 v81, 0xbfb8aa3b, v81
	v_rcp_f32_e32 v84, v84
	v_add_f32_e32 v85, 1.0, v85
	v_exp_f32_e32 v81, v81
	v_mad_i64_i32 v[110:111], s[22:23], v208, s66, v[190:191]
	v_and_b32_e32 v88, 0xffff0000, v139
	v_rcp_f32_e32 v85, v85
	v_add_f32_e32 v86, 1.0, v86
	v_mul_f32_e32 v91, v89, v88
	v_lshl_add_u64 v[110:111], v[110:111], 0, v[188:189]
	v_cvt_pk_bf16_f32 v90, v116, v117
	v_rcp_f32_e32 v86, v86
	v_add_f32_e32 v87, 1.0, v87
	v_cvt_pk_bf16_f32 v88, v96, v97
	v_cvt_pk_bf16_f32 v89, v98, v99
	v_cvt_pk_bf16_f32 v91, v118, v91
	global_store_dwordx4 v[110:111], v[88:91], off offset:2048
	v_rcp_f32_e32 v87, v87
	v_add_f32_e32 v80, 1.0, v80
	v_lshlrev_b32_e32 v90, 16, v124
	v_mul_f32_e32 v84, v84, v90
	v_and_b32_e32 v90, 0xffff0000, v124
	v_rcp_f32_e32 v80, v80
	v_add_f32_e32 v81, 1.0, v81
	v_mul_f32_e32 v85, v85, v90
	v_lshlrev_b32_e32 v90, 16, v125
	v_rcp_f32_e32 v81, v81
	v_mul_f32_e32 v86, v86, v90
	v_and_b32_e32 v90, 0xffff0000, v125
	v_mul_f32_e32 v87, v87, v90
	v_lshlrev_b32_e32 v90, 16, v126
	v_mul_f32_e32 v90, v80, v90
	v_and_b32_e32 v80, 0xffff0000, v126
	v_mul_f32_e32 v91, v81, v80
	v_add_f32_e32 v81, v82, v94
	v_mul_f32_e32 v81, 0xbfb8aa3b, v81
	v_exp_f32_e32 v81, v81
	v_lshlrev_b32_e32 v80, 16, v127
	v_add_f32_e32 v76, v76, v104
	v_mul_f32_e32 v76, 0xbfb8aa3b, v76
	v_add_f32_e32 v81, 1.0, v81
	v_rcp_f32_e32 v81, v81
	v_add_f32_e32 v77, v77, v105
	v_exp_f32_e32 v76, v76
	v_mul_f32_e32 v77, 0xbfb8aa3b, v77
	v_mul_f32_e32 v96, v81, v80
	v_add_f32_e32 v81, v83, v95
	v_mul_f32_e32 v81, 0xbfb8aa3b, v81
	v_exp_f32_e32 v81, v81
	v_add_f32_e32 v78, v78, v106
	v_exp_f32_e32 v77, v77
	v_mul_f32_e32 v78, 0xbfb8aa3b, v78
	v_add_f32_e32 v79, v79, v107
	v_add_f32_e32 v81, 1.0, v81
	v_exp_f32_e32 v78, v78
	v_mul_f32_e32 v79, 0xbfb8aa3b, v79
	v_add_f32_e32 v72, v72, v92
	v_rcp_f32_e32 v81, v81
	v_exp_f32_e32 v79, v79
	v_mul_f32_e32 v72, 0xbfb8aa3b, v72
	v_add_f32_e32 v73, v73, v93
	v_add_f32_e32 v76, 1.0, v76
	v_exp_f32_e32 v72, v72
	v_mul_f32_e32 v73, 0xbfb8aa3b, v73
	v_rcp_f32_e32 v76, v76
	v_add_f32_e32 v77, 1.0, v77
	v_exp_f32_e32 v73, v73
	v_mad_i64_i32 v[88:89], s[22:23], v207, s66, v[190:191]
	v_and_b32_e32 v80, 0xffff0000, v127
	v_rcp_f32_e32 v77, v77
	v_add_f32_e32 v78, 1.0, v78
	v_mul_f32_e32 v83, v81, v80
	v_lshl_add_u64 v[116:117], v[88:89], 0, v[188:189]
	v_cvt_pk_bf16_f32 v82, v90, v91
	v_rcp_f32_e32 v78, v78
	v_add_f32_e32 v79, 1.0, v79
	v_cvt_pk_bf16_f32 v80, v84, v85
	v_cvt_pk_bf16_f32 v81, v86, v87
	v_cvt_pk_bf16_f32 v83, v96, v83
	global_store_dwordx4 v[116:117], v[80:83], off offset:2048
	v_rcp_f32_e32 v79, v79
	v_add_f32_e32 v72, 1.0, v72
	v_lshlrev_b32_e32 v82, 16, v112
	v_mul_f32_e32 v76, v76, v82
	v_and_b32_e32 v82, 0xffff0000, v112
	v_rcp_f32_e32 v72, v72
	v_add_f32_e32 v73, 1.0, v73
	v_mul_f32_e32 v77, v77, v82
	v_lshlrev_b32_e32 v82, 16, v113
	v_rcp_f32_e32 v73, v73
	v_mul_f32_e32 v78, v78, v82
	v_and_b32_e32 v82, 0xffff0000, v113
	v_mul_f32_e32 v79, v79, v82
	v_lshlrev_b32_e32 v82, 16, v114
	v_mul_f32_e32 v82, v72, v82
	v_and_b32_e32 v72, 0xffff0000, v114
	v_mul_f32_e32 v83, v73, v72
	v_add_f32_e32 v73, v74, v94
	v_mul_f32_e32 v73, 0xbfb8aa3b, v73
	v_exp_f32_e32 v73, v73
	v_lshlrev_b32_e32 v72, 16, v115
	v_add_f32_e32 v68, v68, v104
	v_mul_f32_e32 v68, 0xbfb8aa3b, v68
	v_add_f32_e32 v73, 1.0, v73
	v_rcp_f32_e32 v73, v73
	v_add_f32_e32 v69, v69, v105
	v_exp_f32_e32 v68, v68
	v_mul_f32_e32 v69, 0xbfb8aa3b, v69
	v_mul_f32_e32 v84, v73, v72
	v_add_f32_e32 v73, v75, v95
	v_mul_f32_e32 v73, 0xbfb8aa3b, v73
	v_exp_f32_e32 v73, v73
	v_add_f32_e32 v70, v70, v106
	v_exp_f32_e32 v69, v69
	v_mul_f32_e32 v70, 0xbfb8aa3b, v70
	v_add_f32_e32 v71, v71, v107
	v_add_f32_e32 v73, 1.0, v73
	v_exp_f32_e32 v70, v70
	v_mul_f32_e32 v71, 0xbfb8aa3b, v71
	v_add_f32_e32 v64, v64, v92
	v_rcp_f32_e32 v73, v73
	v_exp_f32_e32 v71, v71
	v_mul_f32_e32 v64, 0xbfb8aa3b, v64
	v_add_f32_e32 v65, v65, v93
	v_add_f32_e32 v68, 1.0, v68
	v_exp_f32_e32 v64, v64
	v_mul_f32_e32 v65, 0xbfb8aa3b, v65
	v_rcp_f32_e32 v68, v68
	v_add_f32_e32 v69, 1.0, v69
	v_exp_f32_e32 v65, v65
	v_mad_i64_i32 v[80:81], s[22:23], v206, s66, v[190:191]
	v_and_b32_e32 v72, 0xffff0000, v115
	v_rcp_f32_e32 v69, v69
	v_add_f32_e32 v70, 1.0, v70
	v_mul_f32_e32 v75, v73, v72
	v_lshl_add_u64 v[112:113], v[80:81], 0, v[188:189]
	v_cvt_pk_bf16_f32 v74, v82, v83
	v_rcp_f32_e32 v70, v70
	v_add_f32_e32 v71, 1.0, v71
	v_cvt_pk_bf16_f32 v72, v76, v77
	v_cvt_pk_bf16_f32 v73, v78, v79
	v_cvt_pk_bf16_f32 v75, v84, v75
	global_store_dwordx4 v[112:113], v[72:75], off offset:2048
	v_rcp_f32_e32 v71, v71
	v_add_f32_e32 v64, 1.0, v64
	v_lshlrev_b32_e32 v74, 16, v100
	v_mul_f32_e32 v68, v68, v74
	v_and_b32_e32 v74, 0xffff0000, v100
	v_rcp_f32_e32 v64, v64
	v_add_f32_e32 v65, 1.0, v65
	v_mul_f32_e32 v69, v69, v74
	v_lshlrev_b32_e32 v74, 16, v101
	v_rcp_f32_e32 v65, v65
	v_mul_f32_e32 v70, v70, v74
	v_and_b32_e32 v74, 0xffff0000, v101
	v_mul_f32_e32 v71, v71, v74
	v_lshlrev_b32_e32 v74, 16, v102
	v_mul_f32_e32 v74, v64, v74
	v_and_b32_e32 v64, 0xffff0000, v102
	v_mul_f32_e32 v75, v65, v64
	v_add_f32_e32 v65, v66, v94
	v_mul_f32_e32 v65, 0xbfb8aa3b, v65
	v_exp_f32_e32 v65, v65
	v_lshlrev_b32_e32 v64, 16, v103
	v_mad_i64_i32 v[72:73], s[22:23], v185, s66, v[190:191]
	v_add_f32_e32 v65, 1.0, v65
	v_rcp_f32_e32 v65, v65
	v_lshl_add_u64 v[100:101], v[72:73], 0, v[188:189]
	v_cvt_pk_bf16_f32 v66, v74, v75
	v_mul_f32_e32 v76, v65, v64
	v_add_f32_e32 v65, v67, v95
	v_mul_f32_e32 v65, 0xbfb8aa3b, v65
	v_exp_f32_e32 v65, v65
	v_and_b32_e32 v64, 0xffff0000, v103
	v_add_f32_e32 v65, 1.0, v65
	v_rcp_f32_e32 v65, v65
	s_nop 0
	v_mul_f32_e32 v67, v65, v64
	v_cvt_pk_bf16_f32 v64, v68, v69
	v_cvt_pk_bf16_f32 v65, v70, v71
	v_cvt_pk_bf16_f32 v67, v76, v67
	global_store_dwordx4 v[100:101], v[64:67], off offset:2048
	global_load_dwordx4 v[64:67], v[186:187], off offset:528
	s_nop 0
	global_load_dwordx4 v[72:75], v[186:187], off offset:512
	v_add_u32_e32 v68, 0x80, v184
	v_ashrrev_i32_e32 v69, 31, v68
	v_lshl_add_u64 v[68:69], v[68:69], 1, s[86:87]
	v_mad_i64_i32 v[70:71], s[22:23], v205, s66, v[68:69]
	v_mov_b64_e32 v[102:103], v[214:215]
	v_mov_b64_e32 v[104:105], v[216:217]
	v_mad_i64_i32 v[70:71], s[22:23], v210, s66, v[68:69]
	v_mov_b64_e32 v[96:97], v[218:219]
	v_mov_b64_e32 v[98:99], v[220:221]
	v_mad_i64_i32 v[70:71], s[22:23], v211, s66, v[68:69]
	v_mov_b64_e32 v[92:93], v[222:223]
	v_mov_b64_e32 v[94:95], v[224:225]
	v_mad_i64_i32 v[70:71], s[22:23], v209, s66, v[68:69]
	v_mov_b64_e32 v[88:89], v[226:227]
	v_mov_b64_e32 v[90:91], v[228:229]
	v_mad_i64_i32 v[70:71], s[22:23], v208, s66, v[68:69]
	v_mov_b64_e32 v[84:85], v[230:231]
	v_mov_b64_e32 v[86:87], v[232:233]
	v_mad_i64_i32 v[70:71], s[22:23], v207, s66, v[68:69]
	v_mov_b64_e32 v[80:81], v[238:239]
	v_mov_b64_e32 v[82:83], v[240:241]
	v_mad_i64_i32 v[70:71], s[22:23], v206, s66, v[68:69]
	v_mad_i64_i32 v[68:69], s[22:23], v185, s66, v[68:69]
	v_mov_b64_e32 v[76:77], v[242:243]
	v_mov_b64_e32 v[78:79], v[244:245]
	s_mov_b32 s23, s61
	v_mov_b64_e32 v[68:69], v[250:251]
	v_mov_b64_e32 v[70:71], v[252:253]
	s_mov_b32 s22, s60
	s_waitcnt vmcnt(0)
	v_add_f32_e32 v56, v56, v64
	v_add_f32_e32 v61, v61, v73
	v_mul_f32_e32 v61, 0xbfb8aa3b, v61
	v_add_f32_e32 v62, v62, v74
	v_exp_f32_e32 v61, v61
	v_mul_f32_e32 v62, 0xbfb8aa3b, v62
	v_add_f32_e32 v63, v63, v75
	v_exp_f32_e32 v62, v62
	v_mul_f32_e32 v63, 0xbfb8aa3b, v63
	v_exp_f32_e32 v63, v63
	v_mul_f32_e32 v56, 0xbfb8aa3b, v56
	v_add_f32_e32 v57, v57, v65
	v_exp_f32_e32 v56, v56
	v_mul_f32_e32 v57, 0xbfb8aa3b, v57
	v_add_f32_e32 v61, 1.0, v61
	v_exp_f32_e32 v57, v57
	v_rcp_f32_e32 v61, v61
	v_add_f32_e32 v62, 1.0, v62
	v_rcp_f32_e32 v62, v62
	v_add_f32_e32 v63, 1.0, v63
	v_rcp_f32_e32 v63, v63
	v_add_f32_e32 v56, 1.0, v56
	v_lshlrev_b32_e32 v106, 16, v102
	v_and_b32_e32 v102, 0xffff0000, v102
	v_rcp_f32_e32 v56, v56
	v_add_f32_e32 v57, 1.0, v57
	v_mul_f32_e32 v61, v61, v102
	v_lshlrev_b32_e32 v102, 16, v103
	v_rcp_f32_e32 v57, v57
	v_mul_f32_e32 v62, v62, v102
	v_and_b32_e32 v102, 0xffff0000, v103
	v_mul_f32_e32 v63, v63, v102
	v_lshlrev_b32_e32 v102, 16, v104
	v_mul_f32_e32 v102, v56, v102
	v_and_b32_e32 v56, 0xffff0000, v104
	v_mul_f32_e32 v103, v57, v56
	v_add_f32_e32 v57, v58, v66
	v_mul_f32_e32 v57, 0xbfb8aa3b, v57
	v_exp_f32_e32 v57, v57
	v_lshlrev_b32_e32 v56, 16, v105
	v_add_f32_e32 v60, v60, v72
	v_mul_f32_e32 v60, 0xbfb8aa3b, v60
	v_add_f32_e32 v57, 1.0, v57
	v_rcp_f32_e32 v57, v57
	v_exp_f32_e32 v60, v60
	v_add_f32_e32 v52, v52, v72
	v_mul_f32_e32 v52, 0xbfb8aa3b, v52
	v_mul_f32_e32 v104, v57, v56
	v_add_f32_e32 v57, v59, v67
	v_mul_f32_e32 v57, 0xbfb8aa3b, v57
	v_exp_f32_e32 v57, v57
	v_add_f32_e32 v53, v53, v73
	v_exp_f32_e32 v52, v52
	v_mul_f32_e32 v53, 0xbfb8aa3b, v53
	v_add_f32_e32 v54, v54, v74
	v_exp_f32_e32 v53, v53
	v_mul_f32_e32 v54, 0xbfb8aa3b, v54
	v_add_f32_e32 v55, v55, v75
	v_add_f32_e32 v60, 1.0, v60
	v_add_f32_e32 v57, 1.0, v57
	v_exp_f32_e32 v54, v54
	v_mul_f32_e32 v55, 0xbfb8aa3b, v55
	v_add_f32_e32 v48, v48, v64
	v_rcp_f32_e32 v60, v60
	v_rcp_f32_e32 v57, v57
	v_exp_f32_e32 v55, v55
	v_mul_f32_e32 v48, 0xbfb8aa3b, v48
	v_add_f32_e32 v49, v49, v65
	v_add_f32_e32 v52, 1.0, v52
	v_exp_f32_e32 v48, v48
	v_mul_f32_e32 v49, 0xbfb8aa3b, v49
	v_rcp_f32_e32 v52, v52
	v_add_f32_e32 v53, 1.0, v53
	v_exp_f32_e32 v49, v49
	v_and_b32_e32 v56, 0xffff0000, v105
	v_rcp_f32_e32 v53, v53
	v_add_f32_e32 v54, 1.0, v54
	v_mul_f32_e32 v60, v60, v106
	v_mul_f32_e32 v59, v57, v56
	v_cvt_pk_bf16_f32 v56, v60, v61
	v_rcp_f32_e32 v54, v54
	v_add_f32_e32 v55, 1.0, v55
	v_cvt_pk_bf16_f32 v57, v62, v63
	v_cvt_pk_bf16_f32 v58, v102, v103
	v_cvt_pk_bf16_f32 v59, v104, v59
	global_store_dwordx4 v[148:149], v[56:59], off offset:2304
	v_rcp_f32_e32 v55, v55
	v_add_f32_e32 v48, 1.0, v48
	v_lshlrev_b32_e32 v56, 16, v96
	v_mul_f32_e32 v52, v52, v56
	v_and_b32_e32 v56, 0xffff0000, v96
	v_rcp_f32_e32 v48, v48
	v_add_f32_e32 v49, 1.0, v49
	v_mul_f32_e32 v53, v53, v56
	v_lshlrev_b32_e32 v56, 16, v97
	v_rcp_f32_e32 v49, v49
	v_mul_f32_e32 v54, v54, v56
	v_and_b32_e32 v56, 0xffff0000, v97
	v_mul_f32_e32 v55, v55, v56
	v_lshlrev_b32_e32 v56, 16, v98
	v_mul_f32_e32 v56, v48, v56
	v_and_b32_e32 v48, 0xffff0000, v98
	v_mul_f32_e32 v57, v49, v48
	v_add_f32_e32 v49, v50, v66
	v_mul_f32_e32 v49, 0xbfb8aa3b, v49
	v_exp_f32_e32 v49, v49
	v_lshlrev_b32_e32 v48, 16, v99
	v_add_f32_e32 v44, v44, v72
	v_mul_f32_e32 v44, 0xbfb8aa3b, v44
	v_add_f32_e32 v49, 1.0, v49
	v_rcp_f32_e32 v49, v49
	v_add_f32_e32 v45, v45, v73
	v_exp_f32_e32 v44, v44
	v_mul_f32_e32 v45, 0xbfb8aa3b, v45
	v_mul_f32_e32 v58, v49, v48
	v_add_f32_e32 v49, v51, v67
	v_mul_f32_e32 v49, 0xbfb8aa3b, v49
	v_exp_f32_e32 v49, v49
	v_add_f32_e32 v46, v46, v74
	v_exp_f32_e32 v45, v45
	v_mul_f32_e32 v46, 0xbfb8aa3b, v46
	v_add_f32_e32 v47, v47, v75
	v_add_f32_e32 v49, 1.0, v49
	v_exp_f32_e32 v46, v46
	v_mul_f32_e32 v47, 0xbfb8aa3b, v47
	v_add_f32_e32 v40, v40, v64
	v_rcp_f32_e32 v49, v49
	v_exp_f32_e32 v47, v47
	v_mul_f32_e32 v40, 0xbfb8aa3b, v40
	v_add_f32_e32 v41, v41, v65
	v_add_f32_e32 v44, 1.0, v44
	v_exp_f32_e32 v40, v40
	v_mul_f32_e32 v41, 0xbfb8aa3b, v41
	v_rcp_f32_e32 v44, v44
	v_add_f32_e32 v45, 1.0, v45
	v_exp_f32_e32 v41, v41
	v_and_b32_e32 v48, 0xffff0000, v99
	v_rcp_f32_e32 v45, v45
	v_add_f32_e32 v46, 1.0, v46
	v_mul_f32_e32 v51, v49, v48
	v_cvt_pk_bf16_f32 v48, v52, v53
	v_rcp_f32_e32 v46, v46
	v_add_f32_e32 v47, 1.0, v47
	v_cvt_pk_bf16_f32 v49, v54, v55
	v_cvt_pk_bf16_f32 v50, v56, v57
	v_cvt_pk_bf16_f32 v51, v58, v51
	global_store_dwordx4 v[132:133], v[48:51], off offset:2304
	v_rcp_f32_e32 v47, v47
	v_add_f32_e32 v40, 1.0, v40
	v_lshlrev_b32_e32 v48, 16, v92
	v_mul_f32_e32 v44, v44, v48
	v_and_b32_e32 v48, 0xffff0000, v92
	v_rcp_f32_e32 v40, v40
	v_add_f32_e32 v41, 1.0, v41
	v_mul_f32_e32 v45, v45, v48
	v_lshlrev_b32_e32 v48, 16, v93
	v_rcp_f32_e32 v41, v41
	v_mul_f32_e32 v46, v46, v48
	v_and_b32_e32 v48, 0xffff0000, v93
	v_mul_f32_e32 v47, v47, v48
	v_lshlrev_b32_e32 v48, 16, v94
	v_mul_f32_e32 v48, v40, v48
	v_and_b32_e32 v40, 0xffff0000, v94
	v_mul_f32_e32 v49, v41, v40
	v_add_f32_e32 v41, v42, v66
	v_mul_f32_e32 v41, 0xbfb8aa3b, v41
	v_exp_f32_e32 v41, v41
	v_lshlrev_b32_e32 v40, 16, v95
	v_add_f32_e32 v36, v36, v72
	v_mul_f32_e32 v36, 0xbfb8aa3b, v36
	v_add_f32_e32 v41, 1.0, v41
	v_rcp_f32_e32 v41, v41
	v_add_f32_e32 v37, v37, v73
	v_exp_f32_e32 v36, v36
	v_mul_f32_e32 v37, 0xbfb8aa3b, v37
	v_mul_f32_e32 v50, v41, v40
	v_add_f32_e32 v41, v43, v67
	v_mul_f32_e32 v41, 0xbfb8aa3b, v41
	v_exp_f32_e32 v41, v41
	v_add_f32_e32 v38, v38, v74
	v_exp_f32_e32 v37, v37
	v_mul_f32_e32 v38, 0xbfb8aa3b, v38
	v_add_f32_e32 v39, v39, v75
	v_add_f32_e32 v41, 1.0, v41
	v_exp_f32_e32 v38, v38
	v_mul_f32_e32 v39, 0xbfb8aa3b, v39
	v_add_f32_e32 v32, v32, v64
	v_rcp_f32_e32 v41, v41
	v_exp_f32_e32 v39, v39
	v_mul_f32_e32 v32, 0xbfb8aa3b, v32
	v_add_f32_e32 v33, v33, v65
	v_add_f32_e32 v36, 1.0, v36
	v_exp_f32_e32 v32, v32
	v_mul_f32_e32 v33, 0xbfb8aa3b, v33
	v_rcp_f32_e32 v36, v36
	v_add_f32_e32 v37, 1.0, v37
	v_exp_f32_e32 v33, v33
	v_and_b32_e32 v40, 0xffff0000, v95
	v_rcp_f32_e32 v37, v37
	v_add_f32_e32 v38, 1.0, v38
	v_mul_f32_e32 v43, v41, v40
	v_cvt_pk_bf16_f32 v40, v44, v45
	v_rcp_f32_e32 v38, v38
	v_add_f32_e32 v39, 1.0, v39
	v_cvt_pk_bf16_f32 v41, v46, v47
	v_cvt_pk_bf16_f32 v42, v48, v49
	v_cvt_pk_bf16_f32 v43, v50, v43
	global_store_dwordx4 v[120:121], v[40:43], off offset:2304
	v_rcp_f32_e32 v39, v39
	v_add_f32_e32 v32, 1.0, v32
	v_lshlrev_b32_e32 v40, 16, v88
	v_mul_f32_e32 v36, v36, v40
	v_and_b32_e32 v40, 0xffff0000, v88
	v_rcp_f32_e32 v32, v32
	v_add_f32_e32 v33, 1.0, v33
	v_mul_f32_e32 v37, v37, v40
	v_lshlrev_b32_e32 v40, 16, v89
	v_rcp_f32_e32 v33, v33
	v_mul_f32_e32 v38, v38, v40
	v_and_b32_e32 v40, 0xffff0000, v89
	v_mul_f32_e32 v39, v39, v40
	v_lshlrev_b32_e32 v40, 16, v90
	v_mul_f32_e32 v40, v32, v40
	v_and_b32_e32 v32, 0xffff0000, v90
	v_mul_f32_e32 v41, v33, v32
	v_add_f32_e32 v33, v34, v66
	v_mul_f32_e32 v33, 0xbfb8aa3b, v33
	v_exp_f32_e32 v33, v33
	v_lshlrev_b32_e32 v32, 16, v91
	v_add_f32_e32 v28, v28, v72
	v_mul_f32_e32 v28, 0xbfb8aa3b, v28
	v_add_f32_e32 v33, 1.0, v33
	v_rcp_f32_e32 v33, v33
	v_add_f32_e32 v29, v29, v73
	v_exp_f32_e32 v28, v28
	v_mul_f32_e32 v29, 0xbfb8aa3b, v29
	v_mul_f32_e32 v42, v33, v32
	v_add_f32_e32 v33, v35, v67
	v_mul_f32_e32 v33, 0xbfb8aa3b, v33
	v_exp_f32_e32 v33, v33
	v_add_f32_e32 v30, v30, v74
	v_exp_f32_e32 v29, v29
	v_mul_f32_e32 v30, 0xbfb8aa3b, v30
	v_add_f32_e32 v31, v31, v75
	v_add_f32_e32 v33, 1.0, v33
	v_exp_f32_e32 v30, v30
	v_mul_f32_e32 v31, 0xbfb8aa3b, v31
	v_add_f32_e32 v24, v24, v64
	v_rcp_f32_e32 v33, v33
	v_exp_f32_e32 v31, v31
	v_mul_f32_e32 v24, 0xbfb8aa3b, v24
	v_add_f32_e32 v25, v25, v65
	v_add_f32_e32 v28, 1.0, v28
	v_exp_f32_e32 v24, v24
	v_mul_f32_e32 v25, 0xbfb8aa3b, v25
	v_rcp_f32_e32 v28, v28
	v_add_f32_e32 v29, 1.0, v29
	v_exp_f32_e32 v25, v25
	v_and_b32_e32 v32, 0xffff0000, v91
	v_rcp_f32_e32 v29, v29
	v_add_f32_e32 v30, 1.0, v30
	v_mul_f32_e32 v35, v33, v32
	v_cvt_pk_bf16_f32 v32, v36, v37
	v_rcp_f32_e32 v30, v30
	v_add_f32_e32 v31, 1.0, v31
	v_cvt_pk_bf16_f32 v33, v38, v39
	v_cvt_pk_bf16_f32 v34, v40, v41
	v_cvt_pk_bf16_f32 v35, v42, v35
	global_store_dwordx4 v[108:109], v[32:35], off offset:2304
	v_rcp_f32_e32 v31, v31
	v_add_f32_e32 v24, 1.0, v24
	v_lshlrev_b32_e32 v32, 16, v84
	v_mul_f32_e32 v28, v28, v32
	v_and_b32_e32 v32, 0xffff0000, v84
	v_rcp_f32_e32 v24, v24
	v_add_f32_e32 v25, 1.0, v25
	v_mul_f32_e32 v29, v29, v32
	v_lshlrev_b32_e32 v32, 16, v85
	v_rcp_f32_e32 v25, v25
	v_mul_f32_e32 v30, v30, v32
	v_and_b32_e32 v32, 0xffff0000, v85
	v_mul_f32_e32 v31, v31, v32
	v_lshlrev_b32_e32 v32, 16, v86
	v_mul_f32_e32 v32, v24, v32
	v_and_b32_e32 v24, 0xffff0000, v86
	v_mul_f32_e32 v33, v25, v24
	v_add_f32_e32 v25, v26, v66
	v_mul_f32_e32 v25, 0xbfb8aa3b, v25
	v_exp_f32_e32 v25, v25
	v_lshlrev_b32_e32 v24, 16, v87
	v_add_f32_e32 v20, v20, v72
	v_mul_f32_e32 v20, 0xbfb8aa3b, v20
	v_add_f32_e32 v25, 1.0, v25
	v_rcp_f32_e32 v25, v25
	v_add_f32_e32 v21, v21, v73
	v_exp_f32_e32 v20, v20
	v_mul_f32_e32 v21, 0xbfb8aa3b, v21
	v_mul_f32_e32 v34, v25, v24
	v_add_f32_e32 v25, v27, v67
	v_mul_f32_e32 v25, 0xbfb8aa3b, v25
	v_exp_f32_e32 v25, v25
	v_add_f32_e32 v22, v22, v74
	v_exp_f32_e32 v21, v21
	v_mul_f32_e32 v22, 0xbfb8aa3b, v22
	v_add_f32_e32 v23, v23, v75
	v_add_f32_e32 v25, 1.0, v25
	v_exp_f32_e32 v22, v22
	v_mul_f32_e32 v23, 0xbfb8aa3b, v23
	v_add_f32_e32 v16, v16, v64
	v_rcp_f32_e32 v25, v25
	v_exp_f32_e32 v23, v23
	v_mul_f32_e32 v16, 0xbfb8aa3b, v16
	v_add_f32_e32 v17, v17, v65
	v_add_f32_e32 v20, 1.0, v20
	v_exp_f32_e32 v16, v16
	v_mul_f32_e32 v17, 0xbfb8aa3b, v17
	v_rcp_f32_e32 v20, v20
	v_add_f32_e32 v21, 1.0, v21
	v_exp_f32_e32 v17, v17
	v_and_b32_e32 v24, 0xffff0000, v87
	v_rcp_f32_e32 v21, v21
	v_add_f32_e32 v22, 1.0, v22
	v_mul_f32_e32 v27, v25, v24
	v_cvt_pk_bf16_f32 v24, v28, v29
	v_rcp_f32_e32 v22, v22
	v_add_f32_e32 v23, 1.0, v23
	v_cvt_pk_bf16_f32 v25, v30, v31
	v_cvt_pk_bf16_f32 v26, v32, v33
	v_cvt_pk_bf16_f32 v27, v34, v27
	global_store_dwordx4 v[110:111], v[24:27], off offset:2304
	v_rcp_f32_e32 v23, v23
	v_add_f32_e32 v16, 1.0, v16
	v_lshlrev_b32_e32 v24, 16, v80
	v_mul_f32_e32 v20, v20, v24
	v_and_b32_e32 v24, 0xffff0000, v80
	v_rcp_f32_e32 v16, v16
	v_add_f32_e32 v17, 1.0, v17
	v_mul_f32_e32 v21, v21, v24
	v_lshlrev_b32_e32 v24, 16, v81
	v_rcp_f32_e32 v17, v17
	v_mul_f32_e32 v22, v22, v24
	v_and_b32_e32 v24, 0xffff0000, v81
	v_mul_f32_e32 v23, v23, v24
	v_lshlrev_b32_e32 v24, 16, v82
	v_mul_f32_e32 v24, v16, v24
	v_and_b32_e32 v16, 0xffff0000, v82
	v_mul_f32_e32 v25, v17, v16
	v_add_f32_e32 v17, v18, v66
	v_mul_f32_e32 v17, 0xbfb8aa3b, v17
	v_exp_f32_e32 v17, v17
	v_lshlrev_b32_e32 v16, 16, v83
	v_add_f32_e32 v12, v12, v72
	v_mul_f32_e32 v12, 0xbfb8aa3b, v12
	v_add_f32_e32 v17, 1.0, v17
	v_rcp_f32_e32 v17, v17
	v_add_f32_e32 v13, v13, v73
	v_exp_f32_e32 v12, v12
	v_mul_f32_e32 v13, 0xbfb8aa3b, v13
	v_mul_f32_e32 v26, v17, v16
	v_add_f32_e32 v17, v19, v67
	v_mul_f32_e32 v17, 0xbfb8aa3b, v17
	v_exp_f32_e32 v17, v17
	v_add_f32_e32 v14, v14, v74
	v_exp_f32_e32 v13, v13
	v_mul_f32_e32 v14, 0xbfb8aa3b, v14
	v_add_f32_e32 v15, v15, v75
	v_add_f32_e32 v17, 1.0, v17
	v_exp_f32_e32 v14, v14
	v_mul_f32_e32 v15, 0xbfb8aa3b, v15
	v_add_f32_e32 v8, v8, v64
	v_rcp_f32_e32 v17, v17
	v_exp_f32_e32 v15, v15
	v_mul_f32_e32 v8, 0xbfb8aa3b, v8
	v_add_f32_e32 v9, v9, v65
	v_add_f32_e32 v12, 1.0, v12
	v_exp_f32_e32 v8, v8
	v_mul_f32_e32 v9, 0xbfb8aa3b, v9
	v_rcp_f32_e32 v12, v12
	v_add_f32_e32 v13, 1.0, v13
	v_exp_f32_e32 v9, v9
	v_and_b32_e32 v16, 0xffff0000, v83
	v_rcp_f32_e32 v13, v13
	v_add_f32_e32 v14, 1.0, v14
	v_mul_f32_e32 v19, v17, v16
	v_cvt_pk_bf16_f32 v16, v20, v21
	v_rcp_f32_e32 v14, v14
	v_add_f32_e32 v15, 1.0, v15
	v_cvt_pk_bf16_f32 v17, v22, v23
	v_cvt_pk_bf16_f32 v18, v24, v25
	v_cvt_pk_bf16_f32 v19, v26, v19
	global_store_dwordx4 v[116:117], v[16:19], off offset:2304
	v_rcp_f32_e32 v15, v15
	v_add_f32_e32 v8, 1.0, v8
	v_lshlrev_b32_e32 v16, 16, v76
	v_mul_f32_e32 v12, v12, v16
	v_and_b32_e32 v16, 0xffff0000, v76
	v_rcp_f32_e32 v8, v8
	v_add_f32_e32 v9, 1.0, v9
	v_mul_f32_e32 v13, v13, v16
	v_lshlrev_b32_e32 v16, 16, v77
	v_rcp_f32_e32 v9, v9
	v_mul_f32_e32 v14, v14, v16
	v_and_b32_e32 v16, 0xffff0000, v77
	v_mul_f32_e32 v15, v15, v16
	v_lshlrev_b32_e32 v16, 16, v78
	v_mul_f32_e32 v16, v8, v16
	v_and_b32_e32 v8, 0xffff0000, v78
	v_mul_f32_e32 v17, v9, v8
	v_add_f32_e32 v9, v10, v66
	v_mul_f32_e32 v9, 0xbfb8aa3b, v9
	v_exp_f32_e32 v9, v9
	v_lshlrev_b32_e32 v8, 16, v79
	v_add_f32_e32 v4, v4, v72
	v_mul_f32_e32 v4, 0xbfb8aa3b, v4
	v_add_f32_e32 v9, 1.0, v9
	v_rcp_f32_e32 v9, v9
	v_add_f32_e32 v5, v5, v73
	v_exp_f32_e32 v4, v4
	v_mul_f32_e32 v5, 0xbfb8aa3b, v5
	v_mul_f32_e32 v18, v9, v8
	v_add_f32_e32 v9, v11, v67
	v_mul_f32_e32 v9, 0xbfb8aa3b, v9
	v_exp_f32_e32 v9, v9
	v_add_f32_e32 v6, v6, v74
	v_exp_f32_e32 v5, v5
	v_mul_f32_e32 v6, 0xbfb8aa3b, v6
	v_add_f32_e32 v7, v7, v75
	v_add_f32_e32 v9, 1.0, v9
	v_exp_f32_e32 v6, v6
	v_mul_f32_e32 v7, 0xbfb8aa3b, v7
	v_add_f32_e32 v0, v0, v64
	v_rcp_f32_e32 v9, v9
	v_exp_f32_e32 v7, v7
	v_mul_f32_e32 v0, 0xbfb8aa3b, v0
	v_add_f32_e32 v1, v1, v65
	v_add_f32_e32 v4, 1.0, v4
	v_exp_f32_e32 v0, v0
	v_mul_f32_e32 v1, 0xbfb8aa3b, v1
	v_rcp_f32_e32 v4, v4
	v_add_f32_e32 v5, 1.0, v5
	v_exp_f32_e32 v1, v1
	v_and_b32_e32 v8, 0xffff0000, v79
	v_rcp_f32_e32 v5, v5
	v_add_f32_e32 v6, 1.0, v6
	v_mul_f32_e32 v11, v9, v8
	v_cvt_pk_bf16_f32 v8, v12, v13
	v_rcp_f32_e32 v6, v6
	v_add_f32_e32 v7, 1.0, v7
	v_cvt_pk_bf16_f32 v9, v14, v15
	v_cvt_pk_bf16_f32 v10, v16, v17
	v_cvt_pk_bf16_f32 v11, v18, v11
	global_store_dwordx4 v[112:113], v[8:11], off offset:2304
	v_rcp_f32_e32 v7, v7
	v_add_f32_e32 v0, 1.0, v0
	v_lshlrev_b32_e32 v8, 16, v68
	v_mul_f32_e32 v4, v4, v8
	v_and_b32_e32 v8, 0xffff0000, v68
	v_rcp_f32_e32 v0, v0
	v_add_f32_e32 v1, 1.0, v1
	v_mul_f32_e32 v5, v5, v8
	v_lshlrev_b32_e32 v8, 16, v69
	v_rcp_f32_e32 v1, v1
	v_mul_f32_e32 v6, v6, v8
	v_and_b32_e32 v8, 0xffff0000, v69
	v_mul_f32_e32 v7, v7, v8
	v_lshlrev_b32_e32 v8, 16, v70
	v_mul_f32_e32 v8, v0, v8
	v_and_b32_e32 v0, 0xffff0000, v70
	v_mul_f32_e32 v9, v1, v0
	v_add_f32_e32 v1, v2, v66
	v_mul_f32_e32 v1, 0xbfb8aa3b, v1
	v_exp_f32_e32 v1, v1
	v_lshlrev_b32_e32 v0, 16, v71
	v_cvt_pk_bf16_f32 v2, v8, v9
	v_add_f32_e32 v1, 1.0, v1
	v_rcp_f32_e32 v1, v1
	s_nop 0
	v_mul_f32_e32 v10, v1, v0
	v_add_f32_e32 v1, v3, v67
	v_mul_f32_e32 v1, 0xbfb8aa3b, v1
	v_exp_f32_e32 v1, v1
	v_and_b32_e32 v0, 0xffff0000, v71
	v_add_f32_e32 v1, 1.0, v1
	v_rcp_f32_e32 v1, v1
	s_nop 0
	v_mul_f32_e32 v3, v1, v0
	v_cvt_pk_bf16_f32 v0, v4, v5
	v_cvt_pk_bf16_f32 v1, v6, v7
	v_cvt_pk_bf16_f32 v3, v10, v3
	global_store_dwordx4 v[100:101], v[0:3], off offset:2304
	s_cbranch_vccz .LBB0_913
	s_waitcnt vmcnt(0)
	v_readlane_b32 s30, v237, 2
	s_cmpk_gt_u32 s16, 0xff
	v_readlane_b32 s31, v237, 3
	v_readlane_b32 s12, v237, 22
	s_movk_i32 s56, 0xc00
	v_readlane_b32 s13, v237, 23
	v_readlane_b32 s14, v237, 24
	v_readlane_b32 s15, v237, 25
	v_readlane_b32 s16, v237, 26
	v_readlane_b32 s17, v237, 27
	v_readlane_b32 s18, v237, 28
	v_readlane_b32 s19, v237, 29
	v_readlane_b32 s20, v237, 30
	v_readlane_b32 s21, v237, 31
	v_readlane_b32 s22, v237, 32
	v_readlane_b32 s23, v237, 33
	v_readlane_b32 s24, v237, 34
	v_readlane_b32 s25, v237, 35
	v_readlane_b32 s26, v237, 36
	v_readlane_b32 s27, v237, 37
	s_cbranch_scc1 .LBB0_924
	s_barrier

	.amdhsa_kernel _Z14fwd_megakernel1P
		.amdhsa_group_segment_fixed_size 0
		.amdhsa_private_segment_fixed_size 0
		.amdhsa_kernarg_size 480
		.amdhsa_user_sgpr_count 2
		.amdhsa_user_sgpr_dispatch_ptr 0
		.amdhsa_user_sgpr_queue_ptr 0
		.amdhsa_user_sgpr_kernarg_segment_ptr 1
		.amdhsa_user_sgpr_dispatch_id 0
		.amdhsa_user_sgpr_kernarg_preload_length 0
		.amdhsa_user_sgpr_kernarg_preload_offset 0
		.amdhsa_user_sgpr_private_segment_size 0
		.amdhsa_uses_dynamic_stack 0
		.amdhsa_enable_private_segment 0
		.amdhsa_system_sgpr_workgroup_id_x 1
		.amdhsa_system_sgpr_workgroup_id_y 0
		.amdhsa_system_sgpr_workgroup_id_z 0
		.amdhsa_system_sgpr_workgroup_info 0
		.amdhsa_system_vgpr_workitem_id 2
		.amdhsa_next_free_vgpr 256
		.amdhsa_next_free_sgpr 100
		.amdhsa_accum_offset 256
		.amdhsa_reserve_vcc 1
		.amdhsa_float_round_mode_32 0
		.amdhsa_float_round_mode_16_64 0
		.amdhsa_float_denorm_mode_32 3
		.amdhsa_float_denorm_mode_16_64 3
		.amdhsa_dx10_clamp 1
		.amdhsa_ieee_mode 1
		.amdhsa_fp16_overflow 0
		.amdhsa_tg_split 0
		.amdhsa_exception_fp_ieee_invalid_op 0
		.amdhsa_exception_fp_denorm_src 0
		.amdhsa_exception_fp_ieee_div_zero 0
		.amdhsa_exception_fp_ieee_overflow 0
		.amdhsa_exception_fp_ieee_underflow 0
		.amdhsa_exception_fp_ieee_inexact 0
		.amdhsa_exception_int_div_zero 0
	.end_amdhsa_kernel

amdhsa.kernels:
  - .agpr_count:     0
    .args:
      - .offset:         0
        .size:           224
        .value_kind:     by_value
      - .offset:         224
        .size:           4
        .value_kind:     hidden_block_count_x
      - .offset:         228
        .size:           4
        .value_kind:     hidden_block_count_y
      - .offset:         232
        .size:           4
        .value_kind:     hidden_block_count_z
      - .offset:         236
        .size:           2
        .value_kind:     hidden_group_size_x
      - .offset:         238
        .size:           2
        .value_kind:     hidden_group_size_y
      - .offset:         240
        .size:           2
        .value_kind:     hidden_group_size_z
      - .offset:         242
        .size:           2
        .value_kind:     hidden_remainder_x
      - .offset:         244
        .size:           2
        .value_kind:     hidden_remainder_y
      - .offset:         246
        .size:           2
        .value_kind:     hidden_remainder_z
      - .offset:         264
        .size:           8
        .value_kind:     hidden_global_offset_x
      - .offset:         272
        .size:           8
        .value_kind:     hidden_global_offset_y
      - .offset:         280
        .size:           8
        .value_kind:     hidden_global_offset_z
      - .offset:         288
        .size:           2
        .value_kind:     hidden_grid_dims
      - .offset:         312
        .size:           8
        .value_kind:     hidden_multigrid_sync_arg
      - .offset:         344
        .size:           4
        .value_kind:     hidden_dynamic_lds_size
    .group_segment_fixed_size: 0
    .kernarg_segment_align: 8
    .kernarg_segment_size: 480
    .language:       OpenCL C
    .language_version:
      - 2
      - 0
    .max_flat_workgroup_size: 512
    .name:           _Z14fwd_megakernel1P
    .private_segment_fixed_size: 0
    .sgpr_count:     106
    .sgpr_spill_count: 259
    .symbol:         _Z14fwd_megakernel1P.kd
    .uniform_work_group_size: 1
    .uses_dynamic_stack: false
    .vgpr_count:     256
    .vgpr_spill_count: 0
    .wavefront_size: 64
